# GEMM main loops: second-K-step LDS-DMA loads use a scalar temp base (first-step base + 0x80), all 64-bit VALU address builds gone in the four regular loops
# speedup vs baseline: 1.0067x; 1.0067x over previous
.LBB0_139:
	v_add_u32_e32 v253, 0x10000, v146
	ds_read_b128 v[140:143], v253
	ds_read_b128 v[150:153], v253 offset:1024
	ds_read_b128 v[154:157], v253 offset:2048
	ds_read_b128 v[158:161], v253 offset:3072
	s_add_u32 s10, s6, 0xfff80080
	s_addc_u32 s11, s7, -1
	s_cmp_eq_u32 s41, 28
	s_cselect_b32 s11, s63, s11
	s_cselect_b32 s10, s62, s10
	s_cselect_b32 s53, s61, s29
	s_cselect_b32 s52, s60, s28
	s_mov_b32 m0, s12
	ds_read_b128 v[162:165], v145
	ds_read_b128 v[166:169], v145 offset:1024
	ds_read_b128 v[170:173], v145 offset:2048
	ds_read_b128 v[174:177], v145 offset:3072
	ds_read_b128 v[178:181], v145 offset:4096
	ds_read_b128 v[182:185], v145 offset:5120
	ds_read_b128 v[186:189], v145 offset:6144
	ds_read_b128 v[190:193], v145 offset:7168
	global_load_lds_dwordx4 v136, s[6:7]
	s_mov_b32 m0, s78
	s_nop 0
	global_load_lds_dwordx4 v138, s[6:7]
	s_waitcnt lgkmcnt(8)
	s_setprio 1
	s_barrier
	s_waitcnt lgkmcnt(0)
	v_mfma_f32_16x16x32_bf16 v[126:129], v[140:143], v[162:165], v[126:129]
	v_mfma_f32_16x16x32_bf16 v[122:125], v[154:157], v[162:165], v[122:125]
	v_mfma_f32_16x16x32_bf16 v[118:121], v[140:143], v[170:173], v[118:121]
	v_mfma_f32_16x16x32_bf16 v[110:113], v[154:157], v[170:173], v[110:113]
	v_mfma_f32_16x16x32_bf16 v[102:105], v[140:143], v[178:181], v[102:105]
	v_mfma_f32_16x16x32_bf16 v[94:97], v[154:157], v[178:181], v[94:97]
	v_mfma_f32_16x16x32_bf16 v[86:89], v[140:143], v[186:189], v[86:89]
	v_mfma_f32_16x16x32_bf16 v[78:81], v[154:157], v[186:189], v[78:81]
	v_mfma_f32_16x16x32_bf16 v[126:129], v[150:153], v[166:169], v[126:129]
	v_mfma_f32_16x16x32_bf16 v[122:125], v[158:161], v[166:169], v[122:125]
	v_mfma_f32_16x16x32_bf16 v[118:121], v[150:153], v[174:177], v[118:121]
	v_mfma_f32_16x16x32_bf16 v[110:113], v[158:161], v[174:177], v[110:113]
	v_mfma_f32_16x16x32_bf16 v[102:105], v[150:153], v[182:185], v[102:105]
	v_mfma_f32_16x16x32_bf16 v[94:97], v[158:161], v[182:185], v[94:97]
	v_mfma_f32_16x16x32_bf16 v[86:89], v[150:153], v[190:193], v[86:89]
	v_mfma_f32_16x16x32_bf16 v[78:81], v[158:161], v[190:193], v[78:81]
	s_barrier
	s_setprio 0
	s_mov_b32 m0, s83
	ds_read_b128 v[206:209], v253 offset:16384
	ds_read_b128 v[210:213], v253 offset:17408
	ds_read_b128 v[214:217], v253 offset:18432
	ds_read_b128 v[218:221], v253 offset:19456
	global_load_lds_dwordx4 v194, s[52:53]
	s_mov_b32 m0, s54
	s_nop 0
	global_load_lds_dwordx4 v134, s[52:53]
	s_setprio 1
	s_barrier
	s_waitcnt lgkmcnt(0)
	v_mfma_f32_16x16x32_bf16 v[114:117], v[206:209], v[162:165], v[114:117]
	v_mfma_f32_16x16x32_bf16 v[106:109], v[214:217], v[162:165], v[106:109]
	v_mfma_f32_16x16x32_bf16 v[98:101], v[206:209], v[170:173], v[98:101]
	v_mfma_f32_16x16x32_bf16 v[90:93], v[214:217], v[170:173], v[90:93]
	v_mfma_f32_16x16x32_bf16 v[82:85], v[206:209], v[178:181], v[82:85]
	v_mfma_f32_16x16x32_bf16 v[74:77], v[214:217], v[178:181], v[74:77]
	v_mfma_f32_16x16x32_bf16 v[70:73], v[206:209], v[186:189], v[70:73]
	v_mfma_f32_16x16x32_bf16 v[66:69], v[214:217], v[186:189], v[66:69]
	v_mfma_f32_16x16x32_bf16 v[114:117], v[210:213], v[166:169], v[114:117]
	v_mfma_f32_16x16x32_bf16 v[106:109], v[218:221], v[166:169], v[106:109]
	v_mfma_f32_16x16x32_bf16 v[98:101], v[210:213], v[174:177], v[98:101]
	v_mfma_f32_16x16x32_bf16 v[90:93], v[218:221], v[174:177], v[90:93]
	v_mfma_f32_16x16x32_bf16 v[82:85], v[210:213], v[182:185], v[82:85]
	v_mfma_f32_16x16x32_bf16 v[74:77], v[218:221], v[182:185], v[74:77]
	v_mfma_f32_16x16x32_bf16 v[70:73], v[210:213], v[190:193], v[70:73]
	s_mov_b32 m0, s55
	v_mfma_f32_16x16x32_bf16 v[66:69], v[218:221], v[190:193], v[66:69]
	s_barrier
	s_setprio 0
	ds_read_b128 v[162:165], v145 offset:16384
	ds_read_b128 v[166:169], v145 offset:17408
	ds_read_b128 v[170:173], v145 offset:18432
	ds_read_b128 v[174:177], v145 offset:19456
	ds_read_b128 v[178:181], v145 offset:20480
	ds_read_b128 v[182:185], v145 offset:21504
	ds_read_b128 v[186:189], v145 offset:22528
	ds_read_b128 v[190:193], v145 offset:23552
	global_load_lds_dwordx4 v130, s[10:11]
	s_mov_b32 m0, s34
	s_nop 0
	global_load_lds_dwordx4 v132, s[10:11]
	s_setprio 1
	s_barrier
	s_waitcnt lgkmcnt(0)
	v_mfma_f32_16x16x32_bf16 v[62:65], v[140:143], v[162:165], v[62:65]
	v_mfma_f32_16x16x32_bf16 v[58:61], v[154:157], v[162:165], v[58:61]
	v_mfma_f32_16x16x32_bf16 v[54:57], v[140:143], v[170:173], v[54:57]
	v_mfma_f32_16x16x32_bf16 v[46:49], v[154:157], v[170:173], v[46:49]
	v_mfma_f32_16x16x32_bf16 v[38:41], v[140:143], v[178:181], v[38:41]
	v_mfma_f32_16x16x32_bf16 v[30:33], v[154:157], v[178:181], v[30:33]
	v_mfma_f32_16x16x32_bf16 v[22:25], v[140:143], v[186:189], v[22:25]
	v_mfma_f32_16x16x32_bf16 v[14:17], v[154:157], v[186:189], v[14:17]
	v_mfma_f32_16x16x32_bf16 v[62:65], v[150:153], v[166:169], v[62:65]
	v_mfma_f32_16x16x32_bf16 v[58:61], v[158:161], v[166:169], v[58:61]
	v_mfma_f32_16x16x32_bf16 v[54:57], v[150:153], v[174:177], v[54:57]
	v_mfma_f32_16x16x32_bf16 v[46:49], v[158:161], v[174:177], v[46:49]
	v_mfma_f32_16x16x32_bf16 v[38:41], v[150:153], v[182:185], v[38:41]
	v_mfma_f32_16x16x32_bf16 v[30:33], v[158:161], v[182:185], v[30:33]
	v_mfma_f32_16x16x32_bf16 v[22:25], v[150:153], v[190:193], v[22:25]
	v_mfma_f32_16x16x32_bf16 v[14:17], v[158:161], v[190:193], v[14:17]
	s_barrier
	s_setprio 0
	s_add_u32 s58, s52, 0x80000
	s_addc_u32 s59, s53, 0
	s_mov_b32 m0, s4
	s_nop 0
	global_load_lds_dwordx4 v194, s[58:59]
	s_mov_b32 m0, s5
	s_nop 0
	global_load_lds_dwordx4 v134, s[58:59]
	s_waitcnt vmcnt(6)
	s_setprio 1
	s_barrier
	v_mfma_f32_16x16x32_bf16 v[50:53], v[206:209], v[162:165], v[50:53]
	v_mfma_f32_16x16x32_bf16 v[42:45], v[214:217], v[162:165], v[42:45]
	v_mfma_f32_16x16x32_bf16 v[34:37], v[206:209], v[170:173], v[34:37]
	v_mfma_f32_16x16x32_bf16 v[26:29], v[214:217], v[170:173], v[26:29]
	v_mfma_f32_16x16x32_bf16 v[18:21], v[206:209], v[178:181], v[18:21]
	v_mfma_f32_16x16x32_bf16 v[10:13], v[214:217], v[178:181], v[10:13]
	v_mfma_f32_16x16x32_bf16 v[6:9], v[206:209], v[186:189], v[6:9]
	v_mfma_f32_16x16x32_bf16 v[2:5], v[214:217], v[186:189], v[2:5]
	v_mfma_f32_16x16x32_bf16 v[50:53], v[210:213], v[166:169], v[50:53]
	v_mfma_f32_16x16x32_bf16 v[42:45], v[218:221], v[166:169], v[42:45]
	v_mfma_f32_16x16x32_bf16 v[34:37], v[210:213], v[174:177], v[34:37]
	v_mfma_f32_16x16x32_bf16 v[26:29], v[218:221], v[174:177], v[26:29]
	v_mfma_f32_16x16x32_bf16 v[18:21], v[210:213], v[182:185], v[18:21]
	v_mfma_f32_16x16x32_bf16 v[10:13], v[218:221], v[182:185], v[10:13]
	v_mfma_f32_16x16x32_bf16 v[6:9], v[210:213], v[190:193], v[6:9]
	v_mfma_f32_16x16x32_bf16 v[2:5], v[218:221], v[190:193], v[2:5]
	s_barrier
	s_setprio 0
	ds_read_b128 v[140:143], v253 offset:32768
	ds_read_b128 v[150:153], v253 offset:33792
	ds_read_b128 v[154:157], v253 offset:34816
	ds_read_b128 v[158:161], v253 offset:35840
	s_add_u32 s10, s10, 0x80000
	s_addc_u32 s11, s11, 0
	s_mov_b32 m0, s56
	ds_read_b128 v[162:165], v145 offset:32768
	ds_read_b128 v[166:169], v145 offset:33792
	ds_read_b128 v[170:173], v145 offset:34816
	ds_read_b128 v[174:177], v145 offset:35840
	ds_read_b128 v[178:181], v145 offset:36864
	ds_read_b128 v[182:185], v145 offset:37888
	ds_read_b128 v[186:189], v145 offset:38912
	ds_read_b128 v[190:193], v145 offset:39936
	global_load_lds_dwordx4 v130, s[10:11]
	s_mov_b32 m0, s57
	s_nop 0
	global_load_lds_dwordx4 v132, s[10:11]
	s_waitcnt lgkmcnt(8)
	s_setprio 1
	s_barrier
	s_waitcnt lgkmcnt(0)
	v_mfma_f32_16x16x32_bf16 v[126:129], v[140:143], v[162:165], v[126:129]
	v_mfma_f32_16x16x32_bf16 v[122:125], v[154:157], v[162:165], v[122:125]
	v_mfma_f32_16x16x32_bf16 v[118:121], v[140:143], v[170:173], v[118:121]
	v_mfma_f32_16x16x32_bf16 v[110:113], v[154:157], v[170:173], v[110:113]
	v_mfma_f32_16x16x32_bf16 v[102:105], v[140:143], v[178:181], v[102:105]
	v_mfma_f32_16x16x32_bf16 v[94:97], v[154:157], v[178:181], v[94:97]
	v_mfma_f32_16x16x32_bf16 v[86:89], v[140:143], v[186:189], v[86:89]
	v_mfma_f32_16x16x32_bf16 v[78:81], v[154:157], v[186:189], v[78:81]
	v_mfma_f32_16x16x32_bf16 v[126:129], v[150:153], v[166:169], v[126:129]
	v_mfma_f32_16x16x32_bf16 v[122:125], v[158:161], v[166:169], v[122:125]
	v_mfma_f32_16x16x32_bf16 v[118:121], v[150:153], v[174:177], v[118:121]
	v_mfma_f32_16x16x32_bf16 v[110:113], v[158:161], v[174:177], v[110:113]
	v_mfma_f32_16x16x32_bf16 v[102:105], v[150:153], v[182:185], v[102:105]
	v_mfma_f32_16x16x32_bf16 v[94:97], v[158:161], v[182:185], v[94:97]
	v_mfma_f32_16x16x32_bf16 v[86:89], v[150:153], v[190:193], v[86:89]
	v_mfma_f32_16x16x32_bf16 v[78:81], v[158:161], v[190:193], v[78:81]
	s_barrier
	s_setprio 0
	s_mov_b32 m0, s70
	ds_read_b128 v[206:209], v253 offset:49152
	ds_read_b128 v[210:213], v253 offset:50176
	ds_read_b128 v[214:217], v253 offset:51200
	ds_read_b128 v[218:221], v253 offset:52224
	s_add_u32 s98, s52, 0x80
	s_addc_u32 s99, s53, 0
	global_load_lds_dwordx4 v194, s[98:99]
	s_mov_b32 m0, s71
	s_nop 0
	global_load_lds_dwordx4 v134, s[98:99]
	s_setprio 1
	s_barrier
	s_waitcnt lgkmcnt(0)
	v_mfma_f32_16x16x32_bf16 v[114:117], v[206:209], v[162:165], v[114:117]
	v_mfma_f32_16x16x32_bf16 v[106:109], v[214:217], v[162:165], v[106:109]
	v_mfma_f32_16x16x32_bf16 v[98:101], v[206:209], v[170:173], v[98:101]
	v_mfma_f32_16x16x32_bf16 v[90:93], v[214:217], v[170:173], v[90:93]
	v_mfma_f32_16x16x32_bf16 v[82:85], v[206:209], v[178:181], v[82:85]
	v_mfma_f32_16x16x32_bf16 v[74:77], v[214:217], v[178:181], v[74:77]
	v_mfma_f32_16x16x32_bf16 v[70:73], v[206:209], v[186:189], v[70:73]
	v_mfma_f32_16x16x32_bf16 v[66:69], v[214:217], v[186:189], v[66:69]
	v_mfma_f32_16x16x32_bf16 v[114:117], v[210:213], v[166:169], v[114:117]
	v_mfma_f32_16x16x32_bf16 v[106:109], v[218:221], v[166:169], v[106:109]
	v_mfma_f32_16x16x32_bf16 v[98:101], v[210:213], v[174:177], v[98:101]
	v_mfma_f32_16x16x32_bf16 v[90:93], v[218:221], v[174:177], v[90:93]
	v_mfma_f32_16x16x32_bf16 v[82:85], v[210:213], v[182:185], v[82:85]
	v_mfma_f32_16x16x32_bf16 v[74:77], v[218:221], v[182:185], v[74:77]
	v_mfma_f32_16x16x32_bf16 v[70:73], v[210:213], v[190:193], v[70:73]
	s_mov_b32 m0, s33
	v_mfma_f32_16x16x32_bf16 v[66:69], v[218:221], v[190:193], v[66:69]
	s_barrier
	s_setprio 0
	ds_read_b128 v[162:165], v145 offset:49152
	ds_read_b128 v[166:169], v145 offset:50176
	ds_read_b128 v[170:173], v145 offset:51200
	ds_read_b128 v[174:177], v145 offset:52224
	ds_read_b128 v[178:181], v145 offset:53248
	ds_read_b128 v[182:185], v145 offset:54272
	ds_read_b128 v[186:189], v145 offset:55296
	ds_read_b128 v[190:193], v145 offset:56320
	s_add_u32 s100, s10, 0xfff80080
	s_addc_u32 s101, s11, -1
	global_load_lds_dwordx4 v130, s[100:101]
	s_mov_b32 m0, s35
	s_nop 0
	global_load_lds_dwordx4 v132, s[100:101]
	s_setprio 1
	s_barrier
	s_waitcnt lgkmcnt(0)
	v_mfma_f32_16x16x32_bf16 v[62:65], v[140:143], v[162:165], v[62:65]
	v_mfma_f32_16x16x32_bf16 v[58:61], v[154:157], v[162:165], v[58:61]
	v_mfma_f32_16x16x32_bf16 v[54:57], v[140:143], v[170:173], v[54:57]
	v_mfma_f32_16x16x32_bf16 v[46:49], v[154:157], v[170:173], v[46:49]
	v_mfma_f32_16x16x32_bf16 v[38:41], v[140:143], v[178:181], v[38:41]
	v_mfma_f32_16x16x32_bf16 v[30:33], v[154:157], v[178:181], v[30:33]
	v_mfma_f32_16x16x32_bf16 v[22:25], v[140:143], v[186:189], v[22:25]
	v_mfma_f32_16x16x32_bf16 v[14:17], v[154:157], v[186:189], v[14:17]
	v_mfma_f32_16x16x32_bf16 v[62:65], v[150:153], v[166:169], v[62:65]
	v_mfma_f32_16x16x32_bf16 v[58:61], v[158:161], v[166:169], v[58:61]
	v_mfma_f32_16x16x32_bf16 v[54:57], v[150:153], v[174:177], v[54:57]
	v_mfma_f32_16x16x32_bf16 v[46:49], v[158:161], v[174:177], v[46:49]
	v_mfma_f32_16x16x32_bf16 v[38:41], v[150:153], v[182:185], v[38:41]
	v_mfma_f32_16x16x32_bf16 v[30:33], v[158:161], v[182:185], v[30:33]
	v_mfma_f32_16x16x32_bf16 v[22:25], v[150:153], v[190:193], v[22:25]
	v_mfma_f32_16x16x32_bf16 v[14:17], v[158:161], v[190:193], v[14:17]
	s_barrier
	s_setprio 0
	s_add_u32 s10, s52, 0x80080
	s_addc_u32 s11, s53, 0
	s_mov_b32 m0, s67
	s_nop 0
	global_load_lds_dwordx4 v194, s[10:11]
	s_mov_b32 m0, s17
	s_nop 0
	global_load_lds_dwordx4 v134, s[10:11]
	s_waitcnt vmcnt(6)
	s_setprio 1
	s_barrier
	v_mfma_f32_16x16x32_bf16 v[50:53], v[206:209], v[162:165], v[50:53]
	v_mfma_f32_16x16x32_bf16 v[42:45], v[214:217], v[162:165], v[42:45]
	v_mfma_f32_16x16x32_bf16 v[34:37], v[206:209], v[170:173], v[34:37]
	v_mfma_f32_16x16x32_bf16 v[26:29], v[214:217], v[170:173], v[26:29]
	v_mfma_f32_16x16x32_bf16 v[18:21], v[206:209], v[178:181], v[18:21]
	v_mfma_f32_16x16x32_bf16 v[10:13], v[214:217], v[178:181], v[10:13]
	v_mfma_f32_16x16x32_bf16 v[6:9], v[206:209], v[186:189], v[6:9]
	v_mfma_f32_16x16x32_bf16 v[2:5], v[214:217], v[186:189], v[2:5]
	v_mfma_f32_16x16x32_bf16 v[50:53], v[210:213], v[166:169], v[50:53]
	v_mfma_f32_16x16x32_bf16 v[42:45], v[218:221], v[166:169], v[42:45]
	v_mfma_f32_16x16x32_bf16 v[34:37], v[210:213], v[174:177], v[34:37]
	v_mfma_f32_16x16x32_bf16 v[26:29], v[218:221], v[174:177], v[26:29]
	v_mfma_f32_16x16x32_bf16 v[18:21], v[210:213], v[182:185], v[18:21]
	v_mfma_f32_16x16x32_bf16 v[10:13], v[218:221], v[182:185], v[10:13]
	v_mfma_f32_16x16x32_bf16 v[6:9], v[210:213], v[190:193], v[6:9]
	v_mfma_f32_16x16x32_bf16 v[2:5], v[218:221], v[190:193], v[2:5]
	s_setprio 0
	s_add_i32 s41, s41, 2
	s_add_u32 s6, s6, 0x100
	s_addc_u32 s7, s7, 0
	s_add_u32 s28, s28, 0x100
	s_addc_u32 s29, s29, 0
	s_cmp_gt_u32 s41, 29
	s_barrier
	s_cbranch_scc0 .LBB0_139
	s_cmp_gt_i32 s79, 3
	s_mov_b64 s[6:7], -1
	s_cbranch_scc0 .LBB0_146
	s_lshl_b32 s10, s82, 8
	v_lshl_or_b32 v140, s80, 8, v149
	s_cmp_lg_u32 s79, 4
	v_ashrrev_i32_e32 v141, 31, v140
	s_cbranch_scc0 .LBB0_143
	v_readlane_b32 s6, v252, 55
	v_readlane_b32 s7, v252, 56
	v_add_u32_e32 v150, s10, v147
	s_nop 0
	v_mov_b64_e32 v[142:143], s[6:7]
	s_mov_b32 s6, 0x9000
	v_mad_i64_i32 v[142:143], s[6:7], v150, s6, v[142:143]
	v_lshl_add_u64 v[142:143], v[140:141], 1, v[142:143]
	v_cvt_pk_bf16_f32 v150, v126, v127
	v_cvt_pk_bf16_f32 v151, v128, v129
	v_cvt_pk_bf16_f32 v152, v122, v123
	v_cvt_pk_bf16_f32 v153, v124, v125
	global_store_dwordx4 v[142:143], v[150:153], off
	v_add_co_u32_e32 v154, vcc, s44, v142
	s_nop 0
	v_cvt_pk_bf16_f32 v150, v114, v115
	v_cvt_pk_bf16_f32 v151, v116, v117
	v_cvt_pk_bf16_f32 v152, v106, v107
	v_cvt_pk_bf16_f32 v153, v108, v109
	global_store_dwordx4 v[142:143], v[150:153], off offset:256
	v_addc_co_u32_e32 v155, vcc, 0, v143, vcc
	s_nop 0
	v_cvt_pk_bf16_f32 v150, v118, v119
	v_cvt_pk_bf16_f32 v151, v120, v121
	v_cvt_pk_bf16_f32 v152, v110, v111
	v_cvt_pk_bf16_f32 v153, v112, v113
	global_store_dwordx4 v[154:155], v[150:153], off
	s_mov_b64 s[6:7], 0
	s_nop 0
	v_cvt_pk_bf16_f32 v150, v98, v99
	v_cvt_pk_bf16_f32 v151, v100, v101
	v_cvt_pk_bf16_f32 v152, v90, v91
	v_cvt_pk_bf16_f32 v153, v92, v93
	global_store_dwordx4 v[154:155], v[150:153], off offset:256
	v_add_co_u32_e32 v154, vcc, s45, v142
	s_nop 0
	v_cvt_pk_bf16_f32 v150, v102, v103
	v_cvt_pk_bf16_f32 v151, v104, v105
	v_cvt_pk_bf16_f32 v152, v94, v95
	v_cvt_pk_bf16_f32 v153, v96, v97
	s_nop 0
	v_addc_co_u32_e32 v155, vcc, 0, v143, vcc
	global_store_dwordx4 v[154:155], v[150:153], off
	s_nop 1
	v_cvt_pk_bf16_f32 v150, v82, v83
	v_cvt_pk_bf16_f32 v151, v84, v85
	v_cvt_pk_bf16_f32 v152, v74, v75
	v_cvt_pk_bf16_f32 v153, v76, v77
	global_store_dwordx4 v[154:155], v[150:153], off offset:256
	v_add_co_u32_e32 v154, vcc, s90, v142
	s_nop 0
	v_cvt_pk_bf16_f32 v150, v86, v87
	v_cvt_pk_bf16_f32 v151, v88, v89
	v_cvt_pk_bf16_f32 v152, v78, v79
	v_cvt_pk_bf16_f32 v153, v80, v81
	s_nop 0
	v_addc_co_u32_e32 v155, vcc, 0, v143, vcc
	global_store_dwordx4 v[154:155], v[150:153], off
	s_nop 1
	v_cvt_pk_bf16_f32 v150, v70, v71
	v_cvt_pk_bf16_f32 v151, v72, v73
	v_cvt_pk_bf16_f32 v152, v66, v67
	v_cvt_pk_bf16_f32 v153, v68, v69
	global_store_dwordx4 v[154:155], v[150:153], off offset:256
	v_add_co_u32_e32 v154, vcc, s20, v142
	s_nop 0
	v_cvt_pk_bf16_f32 v150, v62, v63
	v_cvt_pk_bf16_f32 v151, v64, v65
	v_cvt_pk_bf16_f32 v152, v58, v59
	v_cvt_pk_bf16_f32 v153, v60, v61
	s_nop 0
	v_addc_co_u32_e32 v155, vcc, 0, v143, vcc
	global_store_dwordx4 v[154:155], v[150:153], off
	s_nop 1
	v_cvt_pk_bf16_f32 v150, v50, v51
	v_cvt_pk_bf16_f32 v151, v52, v53
	v_cvt_pk_bf16_f32 v152, v42, v43
	v_cvt_pk_bf16_f32 v153, v44, v45
	global_store_dwordx4 v[154:155], v[150:153], off offset:256
	v_add_co_u32_e32 v154, vcc, s21, v142
	s_nop 0
	v_cvt_pk_bf16_f32 v150, v54, v55
	v_cvt_pk_bf16_f32 v151, v56, v57
	v_cvt_pk_bf16_f32 v152, v46, v47
	v_cvt_pk_bf16_f32 v153, v48, v49
	s_nop 0
	v_addc_co_u32_e32 v155, vcc, 0, v143, vcc
	global_store_dwordx4 v[154:155], v[150:153], off
	s_nop 1
	v_cvt_pk_bf16_f32 v150, v34, v35
	v_cvt_pk_bf16_f32 v151, v36, v37
	v_cvt_pk_bf16_f32 v152, v26, v27
	v_cvt_pk_bf16_f32 v153, v28, v29
	global_store_dwordx4 v[154:155], v[150:153], off offset:256
	v_add_co_u32_e32 v154, vcc, s22, v142
	s_nop 0
	v_cvt_pk_bf16_f32 v150, v38, v39
	v_cvt_pk_bf16_f32 v151, v40, v41
	v_cvt_pk_bf16_f32 v152, v30, v31
	v_cvt_pk_bf16_f32 v153, v32, v33
	s_nop 0
	v_addc_co_u32_e32 v155, vcc, 0, v143, vcc
	global_store_dwordx4 v[154:155], v[150:153], off
	v_add_co_u32_e32 v142, vcc, s23, v142
	s_nop 0
	v_cvt_pk_bf16_f32 v150, v18, v19
	v_cvt_pk_bf16_f32 v151, v20, v21
	v_cvt_pk_bf16_f32 v152, v10, v11
	v_cvt_pk_bf16_f32 v153, v12, v13
	global_store_dwordx4 v[154:155], v[150:153], off offset:256
	v_addc_co_u32_e32 v143, vcc, 0, v143, vcc
	s_nop 0
	v_cvt_pk_bf16_f32 v150, v22, v23
	v_cvt_pk_bf16_f32 v151, v24, v25
	v_cvt_pk_bf16_f32 v152, v14, v15
	v_cvt_pk_bf16_f32 v153, v16, v17
	global_store_dwordx4 v[142:143], v[150:153], off
	s_nop 1
	v_cvt_pk_bf16_f32 v150, v6, v7
	v_cvt_pk_bf16_f32 v151, v8, v9
	v_cvt_pk_bf16_f32 v152, v2, v3
	v_cvt_pk_bf16_f32 v153, v4, v5
	global_store_dwordx4 v[142:143], v[150:153], off offset:256

.LBB0_255:
	v_add_u32_e32 v253, 0x10000, v182
	ds_read_b128 v[130:133], v253
	ds_read_b128 v[134:137], v253 offset:1024
	ds_read_b128 v[138:141], v253 offset:2048
	ds_read_b128 v[142:145], v253 offset:3072
	s_add_u32 s8, s6, 0xfff00080
	s_addc_u32 s9, s7, -1
	s_cmp_eq_u32 s79, 60
	s_cselect_b32 s11, s53, s9
	s_cselect_b32 s10, s52, s8
	s_cselect_b32 s9, s61, s78
	s_cselect_b32 s8, s60, s1
	s_add_i32 m0, s5, 0xc000
	ds_read_b128 v[146:149], v181
	ds_read_b128 v[150:153], v181 offset:1024
	ds_read_b128 v[154:157], v181 offset:2048
	ds_read_b128 v[170:173], v181 offset:3072
	ds_read_b128 v[174:177], v181 offset:4096
	ds_read_b128 v[184:187], v181 offset:5120
	ds_read_b128 v[188:191], v181 offset:6144
	ds_read_b128 v[206:209], v181 offset:7168
	global_load_lds_dwordx4 v166, s[6:7]
	s_add_i32 m0, s5, 0xe000
	s_nop 0
	global_load_lds_dwordx4 v168, s[6:7]
	s_waitcnt lgkmcnt(8)
	s_setprio 1
	s_barrier
	s_waitcnt lgkmcnt(0)
	v_mfma_f32_16x16x32_bf16 v[126:129], v[130:133], v[146:149], v[126:129]
	v_mfma_f32_16x16x32_bf16 v[122:125], v[138:141], v[146:149], v[122:125]
	v_mfma_f32_16x16x32_bf16 v[110:113], v[130:133], v[154:157], v[110:113]
	v_mfma_f32_16x16x32_bf16 v[106:109], v[138:141], v[154:157], v[106:109]
	v_mfma_f32_16x16x32_bf16 v[94:97], v[130:133], v[174:177], v[94:97]
	v_mfma_f32_16x16x32_bf16 v[90:93], v[138:141], v[174:177], v[90:93]
	v_mfma_f32_16x16x32_bf16 v[78:81], v[130:133], v[188:191], v[78:81]
	v_mfma_f32_16x16x32_bf16 v[74:77], v[138:141], v[188:191], v[74:77]
	v_mfma_f32_16x16x32_bf16 v[126:129], v[134:137], v[150:153], v[126:129]
	v_mfma_f32_16x16x32_bf16 v[122:125], v[142:145], v[150:153], v[122:125]
	v_mfma_f32_16x16x32_bf16 v[110:113], v[134:137], v[170:173], v[110:113]
	v_mfma_f32_16x16x32_bf16 v[106:109], v[142:145], v[170:173], v[106:109]
	v_mfma_f32_16x16x32_bf16 v[94:97], v[134:137], v[184:187], v[94:97]
	v_mfma_f32_16x16x32_bf16 v[90:93], v[142:145], v[184:187], v[90:93]
	v_mfma_f32_16x16x32_bf16 v[78:81], v[134:137], v[206:209], v[78:81]
	v_mfma_f32_16x16x32_bf16 v[74:77], v[142:145], v[206:209], v[74:77]
	s_barrier
	s_setprio 0
	ds_read_b128 v[210:213], v253 offset:16384
	ds_read_b128 v[214:217], v253 offset:17408
	s_mov_b32 m0, s12
	ds_read_b128 v[218:221], v253 offset:18432
	ds_read_b128 v[222:225], v253 offset:19456
	global_load_lds_dwordx4 v162, s[8:9]
	s_mov_b32 m0, s17
	s_nop 0
	global_load_lds_dwordx4 v158, s[8:9]
	s_setprio 1
	s_barrier
	s_waitcnt lgkmcnt(0)
	v_mfma_f32_16x16x32_bf16 v[118:121], v[210:213], v[146:149], v[118:121]
	v_mfma_f32_16x16x32_bf16 v[114:117], v[218:221], v[146:149], v[114:117]
	v_mfma_f32_16x16x32_bf16 v[102:105], v[210:213], v[154:157], v[102:105]
	v_mfma_f32_16x16x32_bf16 v[98:101], v[218:221], v[154:157], v[98:101]
	v_mfma_f32_16x16x32_bf16 v[86:89], v[210:213], v[174:177], v[86:89]
	v_mfma_f32_16x16x32_bf16 v[82:85], v[218:221], v[174:177], v[82:85]
	v_mfma_f32_16x16x32_bf16 v[70:73], v[210:213], v[188:191], v[70:73]
	v_mfma_f32_16x16x32_bf16 v[66:69], v[218:221], v[188:191], v[66:69]
	v_mfma_f32_16x16x32_bf16 v[118:121], v[214:217], v[150:153], v[118:121]
	v_mfma_f32_16x16x32_bf16 v[114:117], v[222:225], v[150:153], v[114:117]
	v_mfma_f32_16x16x32_bf16 v[102:105], v[214:217], v[170:173], v[102:105]
	v_mfma_f32_16x16x32_bf16 v[98:101], v[222:225], v[170:173], v[98:101]
	v_mfma_f32_16x16x32_bf16 v[86:89], v[214:217], v[184:187], v[86:89]
	v_mfma_f32_16x16x32_bf16 v[82:85], v[222:225], v[184:187], v[82:85]
	v_mfma_f32_16x16x32_bf16 v[70:73], v[214:217], v[206:209], v[70:73]
	s_mov_b32 m0, s5
	v_mfma_f32_16x16x32_bf16 v[66:69], v[222:225], v[206:209], v[66:69]
	s_barrier
	s_setprio 0
	ds_read_b128 v[146:149], v181 offset:16384
	ds_read_b128 v[150:153], v181 offset:17408
	ds_read_b128 v[154:157], v181 offset:18432
	ds_read_b128 v[170:173], v181 offset:19456
	ds_read_b128 v[174:177], v181 offset:20480
	ds_read_b128 v[184:187], v181 offset:21504
	ds_read_b128 v[188:191], v181 offset:22528
	ds_read_b128 v[206:209], v181 offset:23552
	global_load_lds_dwordx4 v164, s[10:11]
	s_mov_b32 m0, s26
	s_nop 0
	global_load_lds_dwordx4 v160, s[10:11]
	s_setprio 1
	s_barrier
	s_waitcnt lgkmcnt(0)
	v_mfma_f32_16x16x32_bf16 v[62:65], v[130:133], v[146:149], v[62:65]
	v_mfma_f32_16x16x32_bf16 v[58:61], v[138:141], v[146:149], v[58:61]
	v_mfma_f32_16x16x32_bf16 v[46:49], v[130:133], v[154:157], v[46:49]
	v_mfma_f32_16x16x32_bf16 v[42:45], v[138:141], v[154:157], v[42:45]
	v_mfma_f32_16x16x32_bf16 v[30:33], v[130:133], v[174:177], v[30:33]
	v_mfma_f32_16x16x32_bf16 v[26:29], v[138:141], v[174:177], v[26:29]
	v_mfma_f32_16x16x32_bf16 v[14:17], v[130:133], v[188:191], v[14:17]
	v_mfma_f32_16x16x32_bf16 v[10:13], v[138:141], v[188:191], v[10:13]
	v_mfma_f32_16x16x32_bf16 v[62:65], v[134:137], v[150:153], v[62:65]
	v_mfma_f32_16x16x32_bf16 v[58:61], v[142:145], v[150:153], v[58:61]
	v_mfma_f32_16x16x32_bf16 v[46:49], v[134:137], v[170:173], v[46:49]
	v_mfma_f32_16x16x32_bf16 v[42:45], v[142:145], v[170:173], v[42:45]
	v_mfma_f32_16x16x32_bf16 v[30:33], v[134:137], v[184:187], v[30:33]
	v_mfma_f32_16x16x32_bf16 v[26:29], v[142:145], v[184:187], v[26:29]
	v_mfma_f32_16x16x32_bf16 v[14:17], v[134:137], v[206:209], v[14:17]
	v_mfma_f32_16x16x32_bf16 v[10:13], v[142:145], v[206:209], v[10:13]
	s_barrier
	s_setprio 0
	s_add_u32 s80, s8, 0x100000
	s_addc_u32 s81, s9, 0
	s_mov_b32 m0, s34
	s_nop 0
	global_load_lds_dwordx4 v162, s[80:81]
	s_mov_b32 m0, s35
	s_nop 0
	global_load_lds_dwordx4 v158, s[80:81]
	s_waitcnt vmcnt(6)
	s_setprio 1
	s_barrier
	v_mfma_f32_16x16x32_bf16 v[54:57], v[210:213], v[146:149], v[54:57]
	v_mfma_f32_16x16x32_bf16 v[50:53], v[218:221], v[146:149], v[50:53]
	v_mfma_f32_16x16x32_bf16 v[38:41], v[210:213], v[154:157], v[38:41]
	v_mfma_f32_16x16x32_bf16 v[34:37], v[218:221], v[154:157], v[34:37]
	v_mfma_f32_16x16x32_bf16 v[22:25], v[210:213], v[174:177], v[22:25]
	v_mfma_f32_16x16x32_bf16 v[18:21], v[218:221], v[174:177], v[18:21]
	v_mfma_f32_16x16x32_bf16 v[6:9], v[210:213], v[188:191], v[6:9]
	v_mfma_f32_16x16x32_bf16 v[2:5], v[218:221], v[188:191], v[2:5]
	v_mfma_f32_16x16x32_bf16 v[54:57], v[214:217], v[150:153], v[54:57]
	v_mfma_f32_16x16x32_bf16 v[50:53], v[222:225], v[150:153], v[50:53]
	v_mfma_f32_16x16x32_bf16 v[38:41], v[214:217], v[170:173], v[38:41]
	v_mfma_f32_16x16x32_bf16 v[34:37], v[222:225], v[170:173], v[34:37]
	v_mfma_f32_16x16x32_bf16 v[22:25], v[214:217], v[184:187], v[22:25]
	v_mfma_f32_16x16x32_bf16 v[18:21], v[222:225], v[184:187], v[18:21]
	v_mfma_f32_16x16x32_bf16 v[6:9], v[214:217], v[206:209], v[6:9]
	v_mfma_f32_16x16x32_bf16 v[2:5], v[222:225], v[206:209], v[2:5]
	s_barrier
	s_setprio 0
	ds_read_b128 v[130:133], v253 offset:32768
	ds_read_b128 v[134:137], v253 offset:33792
	ds_read_b128 v[138:141], v253 offset:34816
	ds_read_b128 v[142:145], v253 offset:35840
	s_add_u32 s10, s10, 0x100000
	s_addc_u32 s11, s11, 0
	s_mov_b32 m0, s42
	ds_read_b128 v[146:149], v181 offset:32768
	ds_read_b128 v[150:153], v181 offset:33792
	ds_read_b128 v[154:157], v181 offset:34816
	ds_read_b128 v[170:173], v181 offset:35840
	ds_read_b128 v[174:177], v181 offset:36864
	ds_read_b128 v[184:187], v181 offset:37888
	ds_read_b128 v[188:191], v181 offset:38912
	ds_read_b128 v[206:209], v181 offset:39936
	global_load_lds_dwordx4 v164, s[10:11]
	s_mov_b32 m0, s54
	s_nop 0
	global_load_lds_dwordx4 v160, s[10:11]
	s_waitcnt lgkmcnt(8)
	s_setprio 1
	s_barrier
	s_waitcnt lgkmcnt(0)
	v_mfma_f32_16x16x32_bf16 v[126:129], v[130:133], v[146:149], v[126:129]
	v_mfma_f32_16x16x32_bf16 v[122:125], v[138:141], v[146:149], v[122:125]
	v_mfma_f32_16x16x32_bf16 v[110:113], v[130:133], v[154:157], v[110:113]
	v_mfma_f32_16x16x32_bf16 v[106:109], v[138:141], v[154:157], v[106:109]
	v_mfma_f32_16x16x32_bf16 v[94:97], v[130:133], v[174:177], v[94:97]
	v_mfma_f32_16x16x32_bf16 v[90:93], v[138:141], v[174:177], v[90:93]
	v_mfma_f32_16x16x32_bf16 v[78:81], v[130:133], v[188:191], v[78:81]
	v_mfma_f32_16x16x32_bf16 v[74:77], v[138:141], v[188:191], v[74:77]
	v_mfma_f32_16x16x32_bf16 v[126:129], v[134:137], v[150:153], v[126:129]
	v_mfma_f32_16x16x32_bf16 v[122:125], v[142:145], v[150:153], v[122:125]
	v_mfma_f32_16x16x32_bf16 v[110:113], v[134:137], v[170:173], v[110:113]
	v_mfma_f32_16x16x32_bf16 v[106:109], v[142:145], v[170:173], v[106:109]
	v_mfma_f32_16x16x32_bf16 v[94:97], v[134:137], v[184:187], v[94:97]
	v_mfma_f32_16x16x32_bf16 v[90:93], v[142:145], v[184:187], v[90:93]
	v_mfma_f32_16x16x32_bf16 v[78:81], v[134:137], v[206:209], v[78:81]
	v_mfma_f32_16x16x32_bf16 v[74:77], v[142:145], v[206:209], v[74:77]
	s_barrier
	s_setprio 0
	s_mov_b32 m0, s55
	ds_read_b128 v[210:213], v253 offset:49152
	ds_read_b128 v[214:217], v253 offset:50176
	ds_read_b128 v[218:221], v253 offset:51200
	ds_read_b128 v[222:225], v253 offset:52224
	s_add_u32 s98, s8, 0x80
	s_addc_u32 s99, s9, 0
	global_load_lds_dwordx4 v162, s[98:99]
	s_mov_b32 m0, s56
	s_nop 0
	global_load_lds_dwordx4 v158, s[98:99]
	s_setprio 1
	s_barrier
	s_waitcnt lgkmcnt(0)
	v_mfma_f32_16x16x32_bf16 v[118:121], v[210:213], v[146:149], v[118:121]
	v_mfma_f32_16x16x32_bf16 v[114:117], v[218:221], v[146:149], v[114:117]
	v_mfma_f32_16x16x32_bf16 v[102:105], v[210:213], v[154:157], v[102:105]
	v_mfma_f32_16x16x32_bf16 v[98:101], v[218:221], v[154:157], v[98:101]
	v_mfma_f32_16x16x32_bf16 v[86:89], v[210:213], v[174:177], v[86:89]
	v_mfma_f32_16x16x32_bf16 v[82:85], v[218:221], v[174:177], v[82:85]
	v_mfma_f32_16x16x32_bf16 v[70:73], v[210:213], v[188:191], v[70:73]
	v_mfma_f32_16x16x32_bf16 v[66:69], v[218:221], v[188:191], v[66:69]
	v_mfma_f32_16x16x32_bf16 v[118:121], v[214:217], v[150:153], v[118:121]
	v_mfma_f32_16x16x32_bf16 v[114:117], v[222:225], v[150:153], v[114:117]
	v_mfma_f32_16x16x32_bf16 v[102:105], v[214:217], v[170:173], v[102:105]
	v_mfma_f32_16x16x32_bf16 v[98:101], v[222:225], v[170:173], v[98:101]
	v_mfma_f32_16x16x32_bf16 v[86:89], v[214:217], v[184:187], v[86:89]
	v_mfma_f32_16x16x32_bf16 v[82:85], v[222:225], v[184:187], v[82:85]
	v_mfma_f32_16x16x32_bf16 v[70:73], v[214:217], v[206:209], v[70:73]
	s_mov_b32 m0, s57
	v_mfma_f32_16x16x32_bf16 v[66:69], v[222:225], v[206:209], v[66:69]
	s_barrier
	s_setprio 0
	ds_read_b128 v[146:149], v181 offset:49152
	ds_read_b128 v[150:153], v181 offset:50176
	ds_read_b128 v[154:157], v181 offset:51200
	ds_read_b128 v[170:173], v181 offset:52224
	ds_read_b128 v[174:177], v181 offset:53248
	ds_read_b128 v[184:187], v181 offset:54272
	ds_read_b128 v[188:191], v181 offset:55296
	ds_read_b128 v[206:209], v181 offset:56320
	s_add_u32 s100, s10, 0xfff00080
	s_addc_u32 s101, s11, -1
	global_load_lds_dwordx4 v164, s[100:101]
	s_mov_b32 m0, s58
	s_nop 0
	global_load_lds_dwordx4 v160, s[100:101]
	s_setprio 1
	s_barrier
	s_waitcnt lgkmcnt(0)
	v_mfma_f32_16x16x32_bf16 v[62:65], v[130:133], v[146:149], v[62:65]
	v_mfma_f32_16x16x32_bf16 v[58:61], v[138:141], v[146:149], v[58:61]
	v_mfma_f32_16x16x32_bf16 v[46:49], v[130:133], v[154:157], v[46:49]
	v_mfma_f32_16x16x32_bf16 v[42:45], v[138:141], v[154:157], v[42:45]
	v_mfma_f32_16x16x32_bf16 v[30:33], v[130:133], v[174:177], v[30:33]
	v_mfma_f32_16x16x32_bf16 v[26:29], v[138:141], v[174:177], v[26:29]
	v_mfma_f32_16x16x32_bf16 v[14:17], v[130:133], v[188:191], v[14:17]
	v_mfma_f32_16x16x32_bf16 v[10:13], v[138:141], v[188:191], v[10:13]
	v_mfma_f32_16x16x32_bf16 v[62:65], v[134:137], v[150:153], v[62:65]
	v_mfma_f32_16x16x32_bf16 v[58:61], v[142:145], v[150:153], v[58:61]
	v_mfma_f32_16x16x32_bf16 v[46:49], v[134:137], v[170:173], v[46:49]
	v_mfma_f32_16x16x32_bf16 v[42:45], v[142:145], v[170:173], v[42:45]
	v_mfma_f32_16x16x32_bf16 v[30:33], v[134:137], v[184:187], v[30:33]
	v_mfma_f32_16x16x32_bf16 v[26:29], v[142:145], v[184:187], v[26:29]
	v_mfma_f32_16x16x32_bf16 v[14:17], v[134:137], v[206:209], v[14:17]
	v_mfma_f32_16x16x32_bf16 v[10:13], v[142:145], v[206:209], v[10:13]
	s_barrier
	s_setprio 0
	s_add_u32 s8, s8, 0x100080
	s_addc_u32 s9, s9, 0
	s_mov_b32 m0, s59
	s_nop 0
	global_load_lds_dwordx4 v162, s[8:9]
	s_mov_b32 m0, s67
	s_nop 0
	global_load_lds_dwordx4 v158, s[8:9]
	s_waitcnt vmcnt(6)
	s_setprio 1
	s_barrier
	v_mfma_f32_16x16x32_bf16 v[54:57], v[210:213], v[146:149], v[54:57]
	v_mfma_f32_16x16x32_bf16 v[50:53], v[218:221], v[146:149], v[50:53]
	v_mfma_f32_16x16x32_bf16 v[38:41], v[210:213], v[154:157], v[38:41]
	v_mfma_f32_16x16x32_bf16 v[34:37], v[218:221], v[154:157], v[34:37]
	v_mfma_f32_16x16x32_bf16 v[22:25], v[210:213], v[174:177], v[22:25]
	v_mfma_f32_16x16x32_bf16 v[18:21], v[218:221], v[174:177], v[18:21]
	v_mfma_f32_16x16x32_bf16 v[6:9], v[210:213], v[188:191], v[6:9]
	v_mfma_f32_16x16x32_bf16 v[2:5], v[218:221], v[188:191], v[2:5]
	v_mfma_f32_16x16x32_bf16 v[54:57], v[214:217], v[150:153], v[54:57]
	v_mfma_f32_16x16x32_bf16 v[50:53], v[222:225], v[150:153], v[50:53]
	v_mfma_f32_16x16x32_bf16 v[38:41], v[214:217], v[170:173], v[38:41]
	v_mfma_f32_16x16x32_bf16 v[34:37], v[222:225], v[170:173], v[34:37]
	v_mfma_f32_16x16x32_bf16 v[22:25], v[214:217], v[184:187], v[22:25]
	v_mfma_f32_16x16x32_bf16 v[18:21], v[222:225], v[184:187], v[18:21]
	v_mfma_f32_16x16x32_bf16 v[6:9], v[214:217], v[206:209], v[6:9]
	v_mfma_f32_16x16x32_bf16 v[2:5], v[222:225], v[206:209], v[2:5]
	s_setprio 0
	s_add_i32 s79, s79, 2
	s_add_u32 s6, s6, 0x100
	s_addc_u32 s7, s7, 0
	s_add_u32 s1, s1, 0x100
	s_addc_u32 s78, s78, 0
	s_cmp_gt_u32 s79, 61
	s_barrier
	s_cbranch_scc0 .LBB0_255
	s_lshl_b32 s1, s28, 9
	s_and_b32 s1, s1, 0xfffff800
	s_lshl_b32 s6, s29, 8
	s_add_i32 s1, s1, s6
	v_add_u32_e32 v172, s1, v180
	s_lshl_b32 s1, s28, 8
	s_and_b32 s1, s1, 0x300
	v_or_b32_e32 v132, s1, v183
	v_mov_b64_e32 v[170:171], s[50:51]
	v_mad_i64_i32 v[130:131], s[6:7], v172, s37, v[170:171]
	v_lshlrev_b32_e32 v194, 1, v132
	v_lshl_add_u64 v[130:131], v[130:131], 0, v[194:195]
	v_lshl_add_u64 v[132:133], v[130:131], 0, s[84:85]
	v_add_co_u32_e32 v130, vcc, s16, v130
	v_or_b32_e32 v178, 16, v172
	s_nop 0
	v_addc_co_u32_e32 v131, vcc, 0, v131, vcc
	global_load_dwordx4 v[184:187], v[130:131], off offset:2048
	global_load_dwordx4 v[154:157], v[132:133], off offset:256
	v_mad_i64_i32 v[130:131], s[6:7], v178, s37, v[170:171]
	v_lshl_add_u64 v[130:131], v[130:131], 0, v[194:195]
	v_lshl_add_u64 v[132:133], v[130:131], 0, s[84:85]
	v_add_co_u32_e32 v130, vcc, s16, v130
	v_or_b32_e32 v176, 32, v172
	s_nop 0
	v_addc_co_u32_e32 v131, vcc, 0, v131, vcc
	global_load_dwordx4 v[150:153], v[130:131], off offset:2048
	global_load_dwordx4 v[146:149], v[132:133], off offset:256
	v_mad_i64_i32 v[130:131], s[6:7], v176, s37, v[170:171]
	v_lshl_add_u64 v[130:131], v[130:131], 0, v[194:195]
	v_lshl_add_u64 v[132:133], v[130:131], 0, s[84:85]
	v_add_co_u32_e32 v130, vcc, s16, v130
	v_or_b32_e32 v174, 48, v172
	s_nop 0
	v_addc_co_u32_e32 v131, vcc, 0, v131, vcc
	global_load_dwordx4 v[142:145], v[130:131], off offset:2048
	global_load_dwordx4 v[138:141], v[132:133], off offset:256
	v_mad_i64_i32 v[130:131], s[6:7], v174, s37, v[170:171]
	v_lshl_add_u64 v[130:131], v[130:131], 0, v[194:195]
	v_lshl_add_u64 v[132:133], v[130:131], 0, s[84:85]
	v_add_co_u32_e32 v130, vcc, s16, v130
	v_pk_mul_f32 v[126:127], v[126:127], s[72:73] op_sel_hi:[1,0]
	s_nop 0
	v_addc_co_u32_e32 v131, vcc, 0, v131, vcc
	global_load_dwordx4 v[134:137], v[130:131], off offset:2048
	s_nop 0
	global_load_dwordx4 v[130:133], v[132:133], off offset:256
	v_pk_mul_f32 v[190:191], v[124:125], s[72:73] op_sel_hi:[1,0]
	v_pk_mul_f32 v[128:129], v[128:129], s[72:73] op_sel_hi:[1,0]
	v_pk_mul_f32 v[122:123], v[122:123], s[72:73] op_sel_hi:[1,0]
	v_ashrrev_i32_e32 v173, 31, v172
	v_lshlrev_b64 v[188:189], 11, v[172:173]
	v_pk_mul_f32 v[118:119], v[118:119], s[72:73] op_sel_hi:[1,0]
	v_pk_mul_f32 v[120:121], v[120:121], s[72:73] op_sel_hi:[1,0]
	v_pk_mul_f32 v[110:111], v[110:111], s[72:73] op_sel_hi:[1,0]
	v_pk_mul_f32 v[112:113], v[112:113], s[72:73] op_sel_hi:[1,0]
	v_ashrrev_i32_e32 v179, 31, v178
	v_pk_mul_f32 v[102:103], v[102:103], s[72:73] op_sel_hi:[1,0]
	v_pk_mul_f32 v[104:105], v[104:105], s[72:73] op_sel_hi:[1,0]
	v_pk_mul_f32 v[94:95], v[94:95], s[72:73] op_sel_hi:[1,0]
	v_pk_mul_f32 v[96:97], v[96:97], s[72:73] op_sel_hi:[1,0]
	v_ashrrev_i32_e32 v177, 31, v176
	v_pk_mul_f32 v[86:87], v[86:87], s[72:73] op_sel_hi:[1,0]
	v_pk_mul_f32 v[88:89], v[88:89], s[72:73] op_sel_hi:[1,0]
	v_pk_mul_f32 v[78:79], v[78:79], s[72:73] op_sel_hi:[1,0]
	v_pk_mul_f32 v[80:81], v[80:81], s[72:73] op_sel_hi:[1,0]
	v_ashrrev_i32_e32 v175, 31, v174
	v_pk_mul_f32 v[70:71], v[70:71], s[72:73] op_sel_hi:[1,0]
	v_pk_mul_f32 v[72:73], v[72:73], s[72:73] op_sel_hi:[1,0]
	s_waitcnt vmcnt(0)
	v_lshlrev_b32_e32 v124, 16, v184
	v_and_b32_e32 v125, 0xffff0000, v184
	v_mul_f32_e32 v124, v126, v124
	v_mul_f32_e32 v125, v127, v125
	v_cvt_pk_bf16_f32 v124, v124, v125
	v_lshlrev_b32_e32 v125, 16, v185
	v_and_b32_e32 v126, 0xffff0000, v185
	v_mul_f32_e32 v125, v128, v125
	v_mul_f32_e32 v126, v129, v126
	v_cvt_pk_bf16_f32 v125, v125, v126
	v_lshlrev_b32_e32 v126, 16, v186
	v_mul_f32_e32 v122, v122, v126
	v_and_b32_e32 v126, 0xffff0000, v186
	v_mul_f32_e32 v123, v123, v126
	v_cvt_pk_bf16_f32 v126, v122, v123
	v_lshlrev_b32_e32 v122, 16, v187
	v_and_b32_e32 v123, 0xffff0000, v187
	v_mul_f32_e32 v122, v190, v122
	v_mul_f32_e32 v123, v191, v123
	v_cvt_pk_bf16_f32 v127, v122, v123
	v_lshl_add_u64 v[122:123], s[74:75], 0, v[188:189]
	v_lshl_add_u64 v[122:123], v[122:123], 0, v[194:195]
	global_store_dwordx4 v[122:123], v[124:127], off
	s_nop 1
	v_pk_mul_f32 v[124:125], v[116:117], s[72:73] op_sel_hi:[1,0]
	v_pk_mul_f32 v[116:117], v[114:115], s[72:73] op_sel_hi:[1,0]
	v_lshlrev_b32_e32 v114, 16, v154
	v_and_b32_e32 v115, 0xffff0000, v154
	v_mul_f32_e32 v114, v118, v114
	v_mul_f32_e32 v115, v119, v115
	v_cvt_pk_bf16_f32 v114, v114, v115
	v_lshlrev_b32_e32 v115, 16, v155
	v_and_b32_e32 v118, 0xffff0000, v155
	v_mul_f32_e32 v115, v120, v115
	v_mul_f32_e32 v118, v121, v118
	v_cvt_pk_bf16_f32 v115, v115, v118
	v_lshlrev_b32_e32 v118, 16, v156
	v_mul_f32_e32 v116, v116, v118
	v_and_b32_e32 v118, 0xffff0000, v156
	v_mul_f32_e32 v117, v117, v118
	v_cvt_pk_bf16_f32 v116, v116, v117
	v_lshlrev_b32_e32 v117, 16, v157
	v_mul_f32_e32 v117, v124, v117
	v_and_b32_e32 v118, 0xffff0000, v157
	v_mul_f32_e32 v118, v125, v118
	v_cvt_pk_bf16_f32 v117, v117, v118
	global_store_dwordx4 v[122:123], v[114:117], off offset:256
	s_nop 1
	v_pk_mul_f32 v[116:117], v[108:109], s[72:73] op_sel_hi:[1,0]
	v_pk_mul_f32 v[108:109], v[106:107], s[72:73] op_sel_hi:[1,0]
	v_lshlrev_b32_e32 v106, 16, v150
	v_and_b32_e32 v107, 0xffff0000, v150
	v_mul_f32_e32 v106, v110, v106
	v_mul_f32_e32 v107, v111, v107
	v_cvt_pk_bf16_f32 v106, v106, v107
	v_lshlrev_b32_e32 v107, 16, v151
	v_and_b32_e32 v110, 0xffff0000, v151
	v_mul_f32_e32 v107, v112, v107
	v_mul_f32_e32 v110, v113, v110
	v_cvt_pk_bf16_f32 v107, v107, v110
	v_lshlrev_b32_e32 v110, 16, v152
	v_mul_f32_e32 v108, v108, v110
	v_and_b32_e32 v110, 0xffff0000, v152
	v_mul_f32_e32 v109, v109, v110
	v_cvt_pk_bf16_f32 v108, v108, v109
	v_lshlrev_b32_e32 v109, 16, v153
	v_and_b32_e32 v110, 0xffff0000, v153
	v_lshlrev_b64 v[114:115], 11, v[178:179]
	v_mul_f32_e32 v109, v116, v109
	v_mul_f32_e32 v110, v117, v110
	v_cvt_pk_bf16_f32 v109, v109, v110
	v_lshl_add_u64 v[110:111], s[74:75], 0, v[114:115]
	v_lshl_add_u64 v[110:111], v[110:111], 0, v[194:195]
	global_store_dwordx4 v[110:111], v[106:109], off
	s_nop 1
	v_pk_mul_f32 v[106:107], v[100:101], s[72:73] op_sel_hi:[1,0]
	v_pk_mul_f32 v[100:101], v[98:99], s[72:73] op_sel_hi:[1,0]
	v_lshlrev_b32_e32 v98, 16, v146
	v_and_b32_e32 v99, 0xffff0000, v146
	v_mul_f32_e32 v98, v102, v98
	v_mul_f32_e32 v99, v103, v99
	v_cvt_pk_bf16_f32 v98, v98, v99
	v_lshlrev_b32_e32 v99, 16, v147
	v_and_b32_e32 v102, 0xffff0000, v147
	v_mul_f32_e32 v99, v104, v99
	v_mul_f32_e32 v102, v105, v102
	v_cvt_pk_bf16_f32 v99, v99, v102
	v_lshlrev_b32_e32 v102, 16, v148
	v_mul_f32_e32 v100, v100, v102
	v_and_b32_e32 v102, 0xffff0000, v148
	v_mul_f32_e32 v101, v101, v102
	v_cvt_pk_bf16_f32 v100, v100, v101
	v_lshlrev_b32_e32 v101, 16, v149
	v_mul_f32_e32 v101, v106, v101
	v_and_b32_e32 v102, 0xffff0000, v149
	v_mul_f32_e32 v102, v107, v102
	v_cvt_pk_bf16_f32 v101, v101, v102
	global_store_dwordx4 v[110:111], v[98:101], off offset:256
	s_nop 1
	v_pk_mul_f32 v[100:101], v[92:93], s[72:73] op_sel_hi:[1,0]
	v_pk_mul_f32 v[92:93], v[90:91], s[72:73] op_sel_hi:[1,0]
	v_lshlrev_b32_e32 v90, 16, v142
	v_and_b32_e32 v91, 0xffff0000, v142
	v_mul_f32_e32 v90, v94, v90
	v_mul_f32_e32 v91, v95, v91
	v_cvt_pk_bf16_f32 v90, v90, v91
	v_lshlrev_b32_e32 v91, 16, v143
	v_and_b32_e32 v94, 0xffff0000, v143
	v_mul_f32_e32 v91, v96, v91
	v_mul_f32_e32 v94, v97, v94
	v_cvt_pk_bf16_f32 v91, v91, v94
	v_lshlrev_b32_e32 v94, 16, v144
	v_mul_f32_e32 v92, v92, v94
	v_and_b32_e32 v94, 0xffff0000, v144
	v_mul_f32_e32 v93, v93, v94
	v_cvt_pk_bf16_f32 v92, v92, v93
	v_lshlrev_b32_e32 v93, 16, v145
	v_and_b32_e32 v94, 0xffff0000, v145
	v_lshlrev_b64 v[98:99], 11, v[176:177]
	v_mul_f32_e32 v93, v100, v93
	v_mul_f32_e32 v94, v101, v94
	v_cvt_pk_bf16_f32 v93, v93, v94
	v_lshl_add_u64 v[94:95], s[74:75], 0, v[98:99]
	v_lshl_add_u64 v[94:95], v[94:95], 0, v[194:195]
	global_store_dwordx4 v[94:95], v[90:93], off
	s_nop 1
	v_pk_mul_f32 v[90:91], v[84:85], s[72:73] op_sel_hi:[1,0]
	v_pk_mul_f32 v[84:85], v[82:83], s[72:73] op_sel_hi:[1,0]
	v_lshlrev_b32_e32 v82, 16, v138
	v_and_b32_e32 v83, 0xffff0000, v138
	v_mul_f32_e32 v82, v86, v82
	v_mul_f32_e32 v83, v87, v83
	v_cvt_pk_bf16_f32 v82, v82, v83
	v_lshlrev_b32_e32 v83, 16, v139
	v_and_b32_e32 v86, 0xffff0000, v139
	v_mul_f32_e32 v83, v88, v83
	v_mul_f32_e32 v86, v89, v86
	v_cvt_pk_bf16_f32 v83, v83, v86
	v_lshlrev_b32_e32 v86, 16, v140
	v_mul_f32_e32 v84, v84, v86
	v_and_b32_e32 v86, 0xffff0000, v140
	v_mul_f32_e32 v85, v85, v86
	v_cvt_pk_bf16_f32 v84, v84, v85
	v_lshlrev_b32_e32 v85, 16, v141
	v_mul_f32_e32 v85, v90, v85
	v_and_b32_e32 v86, 0xffff0000, v141
	v_mul_f32_e32 v86, v91, v86
	v_cvt_pk_bf16_f32 v85, v85, v86
	global_store_dwordx4 v[94:95], v[82:85], off offset:256
	s_nop 1
	v_pk_mul_f32 v[84:85], v[76:77], s[72:73] op_sel_hi:[1,0]
	v_pk_mul_f32 v[76:77], v[74:75], s[72:73] op_sel_hi:[1,0]
	v_lshlrev_b32_e32 v74, 16, v134
	v_and_b32_e32 v75, 0xffff0000, v134
	v_mul_f32_e32 v74, v78, v74
	v_mul_f32_e32 v75, v79, v75
	v_cvt_pk_bf16_f32 v74, v74, v75
	v_lshlrev_b32_e32 v75, 16, v135
	v_and_b32_e32 v78, 0xffff0000, v135
	v_mul_f32_e32 v75, v80, v75
	v_mul_f32_e32 v78, v81, v78
	v_cvt_pk_bf16_f32 v75, v75, v78
	v_lshlrev_b32_e32 v78, 16, v136
	v_mul_f32_e32 v76, v76, v78
	v_and_b32_e32 v78, 0xffff0000, v136
	v_mul_f32_e32 v77, v77, v78
	v_cvt_pk_bf16_f32 v76, v76, v77
	v_lshlrev_b32_e32 v77, 16, v137
	v_and_b32_e32 v78, 0xffff0000, v137
	v_lshlrev_b64 v[82:83], 11, v[174:175]
	v_mul_f32_e32 v77, v84, v77
	v_mul_f32_e32 v78, v85, v78
	v_cvt_pk_bf16_f32 v77, v77, v78
	v_lshl_add_u64 v[78:79], s[74:75], 0, v[82:83]
	v_lshl_add_u64 v[78:79], v[78:79], 0, v[194:195]
	global_store_dwordx4 v[78:79], v[74:77], off
	s_nop 1
	v_pk_mul_f32 v[74:75], v[68:69], s[72:73] op_sel_hi:[1,0]
	v_pk_mul_f32 v[68:69], v[66:67], s[72:73] op_sel_hi:[1,0]
	v_lshlrev_b32_e32 v66, 16, v130
	v_and_b32_e32 v67, 0xffff0000, v130
	v_mul_f32_e32 v66, v70, v66
	v_mul_f32_e32 v67, v71, v67
	v_cvt_pk_bf16_f32 v66, v66, v67
	v_lshlrev_b32_e32 v67, 16, v131
	v_and_b32_e32 v70, 0xffff0000, v131
	v_mul_f32_e32 v67, v72, v67
	v_mul_f32_e32 v70, v73, v70
	v_cvt_pk_bf16_f32 v67, v67, v70
	v_lshlrev_b32_e32 v70, 16, v132
	v_mul_f32_e32 v68, v68, v70
	v_and_b32_e32 v70, 0xffff0000, v132
	v_mul_f32_e32 v69, v69, v70
	v_cvt_pk_bf16_f32 v68, v68, v69
	v_lshlrev_b32_e32 v69, 16, v133
	v_mul_f32_e32 v69, v74, v69
	v_and_b32_e32 v70, 0xffff0000, v133
	v_mul_f32_e32 v70, v75, v70
	v_cvt_pk_bf16_f32 v69, v69, v70
	global_store_dwordx4 v[78:79], v[66:69], off offset:256
	v_add_u32_e32 v78, 0x80, v172
	s_nop 0
	v_mad_i64_i32 v[66:67], s[6:7], v78, s37, v[170:171]
	v_lshl_add_u64 v[66:67], v[66:67], 0, v[194:195]
	v_add_co_u32_e32 v68, vcc, s16, v66
	v_add_u32_e32 v86, 0x90, v172
	s_nop 0
	v_addc_co_u32_e32 v69, vcc, 0, v67, vcc
	global_load_dwordx4 v[70:73], v[68:69], off offset:2048
	v_lshl_add_u64 v[66:67], v[66:67], 0, s[84:85]
	global_load_dwordx4 v[74:77], v[66:67], off offset:256
	v_pk_mul_f32 v[96:97], v[56:57], s[72:73] op_sel_hi:[1,0]
	v_mad_i64_i32 v[56:57], s[6:7], v86, s37, v[170:171]
	v_lshl_add_u64 v[56:57], v[56:57], 0, v[194:195]
	v_pk_mul_f32 v[94:95], v[58:59], s[72:73] op_sel_hi:[1,0]
	v_add_co_u32_e32 v58, vcc, s16, v56
	v_pk_mul_f32 v[92:93], v[60:61], s[72:73] op_sel_hi:[1,0]
	s_nop 0
	v_addc_co_u32_e32 v59, vcc, 0, v57, vcc
	global_load_dwordx4 v[58:61], v[58:59], off offset:2048
	v_add_u32_e32 v68, 0xa0, v172
	v_pk_mul_f32 v[102:103], v[50:51], s[72:73] op_sel_hi:[1,0]
	v_mad_i64_i32 v[50:51], s[6:7], v68, s37, v[170:171]
	v_add_u32_e32 v66, 0xb0, v172
	v_lshl_add_u64 v[50:51], v[50:51], 0, v[194:195]
	v_pk_mul_f32 v[100:101], v[52:53], s[72:73] op_sel_hi:[1,0]
	v_mad_i64_i32 v[52:53], s[6:7], v66, s37, v[170:171]
	v_lshl_add_u64 v[82:83], v[50:51], 0, s[84:85]
	v_add_co_u32_e32 v50, vcc, s16, v50
	v_lshl_add_u64 v[52:53], v[52:53], 0, v[194:195]
	s_nop 0
	v_addc_co_u32_e32 v51, vcc, 0, v51, vcc
	v_ashrrev_i32_e32 v79, 31, v78
	v_lshl_add_u64 v[104:105], v[52:53], 0, s[84:85]
	v_add_co_u32_e32 v52, vcc, s16, v52
	v_pk_mul_f32 v[98:99], v[54:55], s[72:73] op_sel_hi:[1,0]
	v_lshlrev_b64 v[54:55], 11, v[78:79]
	v_lshl_add_u64 v[56:57], v[56:57], 0, s[84:85]
	v_addc_co_u32_e32 v53, vcc, 0, v53, vcc
	v_pk_mul_f32 v[88:89], v[64:65], s[72:73] op_sel_hi:[1,0]
	v_pk_mul_f32 v[90:91], v[62:63], s[72:73] op_sel_hi:[1,0]
	v_lshl_add_u64 v[106:107], s[74:75], 0, v[54:55]
	global_load_dwordx4 v[62:65], v[56:57], off offset:256
	global_load_dwordx4 v[78:81], v[50:51], off offset:2048
	s_nop 0
	global_load_dwordx4 v[82:85], v[82:83], off offset:256
	s_nop 0
	global_load_dwordx4 v[54:57], v[52:53], off offset:2048
	s_nop 0
	global_load_dwordx4 v[50:53], v[104:105], off offset:256
	v_lshl_add_u64 v[104:105], v[106:107], 0, v[194:195]
	v_pk_mul_f32 v[46:47], v[46:47], s[72:73] op_sel_hi:[1,0]
	v_pk_mul_f32 v[48:49], v[48:49], s[72:73] op_sel_hi:[1,0]
	v_ashrrev_i32_e32 v87, 31, v86
	v_pk_mul_f32 v[38:39], v[38:39], s[72:73] op_sel_hi:[1,0]
	v_pk_mul_f32 v[40:41], v[40:41], s[72:73] op_sel_hi:[1,0]
	v_pk_mul_f32 v[30:31], v[30:31], s[72:73] op_sel_hi:[1,0]
	v_pk_mul_f32 v[32:33], v[32:33], s[72:73] op_sel_hi:[1,0]
	v_ashrrev_i32_e32 v69, 31, v68
	v_pk_mul_f32 v[22:23], v[22:23], s[72:73] op_sel_hi:[1,0]
	v_pk_mul_f32 v[24:25], v[24:25], s[72:73] op_sel_hi:[1,0]
	v_pk_mul_f32 v[14:15], v[14:15], s[72:73] op_sel_hi:[1,0]
	v_pk_mul_f32 v[16:17], v[16:17], s[72:73] op_sel_hi:[1,0]
	v_ashrrev_i32_e32 v67, 31, v66
	v_pk_mul_f32 v[6:7], v[6:7], s[72:73] op_sel_hi:[1,0]
	v_pk_mul_f32 v[8:9], v[8:9], s[72:73] op_sel_hi:[1,0]
	s_waitcnt vmcnt(0)
	v_lshlrev_b32_e32 v106, 16, v70
	v_and_b32_e32 v70, 0xffff0000, v70
	v_lshlrev_b32_e32 v107, 16, v71
	v_and_b32_e32 v71, 0xffff0000, v71
	v_lshlrev_b32_e32 v108, 16, v72
	v_and_b32_e32 v72, 0xffff0000, v72
	v_lshlrev_b32_e32 v109, 16, v73
	v_and_b32_e32 v73, 0xffff0000, v73
	v_mul_f32_e32 v70, v91, v70
	v_mul_f32_e32 v71, v89, v71
	v_mul_f32_e32 v72, v95, v72
	v_mul_f32_e32 v73, v93, v73
	v_mul_f32_e32 v90, v90, v106
	v_mul_f32_e32 v88, v88, v107
	v_mul_f32_e32 v89, v94, v108
	v_mul_f32_e32 v91, v92, v109
	v_cvt_pk_bf16_f32 v70, v90, v70
	v_cvt_pk_bf16_f32 v71, v88, v71
	v_cvt_pk_bf16_f32 v72, v89, v72
	v_cvt_pk_bf16_f32 v73, v91, v73
	v_lshlrev_b32_e32 v111, 16, v75
	v_and_b32_e32 v75, 0xffff0000, v75
	global_store_dwordx4 v[104:105], v[70:73], off
	v_lshlrev_b32_e32 v110, 16, v74
	v_and_b32_e32 v74, 0xffff0000, v74
	v_lshlrev_b32_e32 v72, 16, v76
	v_and_b32_e32 v73, 0xffff0000, v76
	v_mul_f32_e32 v71, v97, v75
	v_mul_f32_e32 v72, v102, v72
	v_mul_f32_e32 v73, v103, v73
	v_mul_f32_e32 v92, v98, v110
	v_mul_f32_e32 v74, v99, v74
	v_mul_f32_e32 v93, v96, v111
	v_cvt_pk_bf16_f32 v70, v92, v74
	v_cvt_pk_bf16_f32 v71, v93, v71
	v_cvt_pk_bf16_f32 v72, v72, v73
	v_lshlrev_b32_e32 v73, 16, v77
	v_mul_f32_e32 v73, v100, v73
	v_and_b32_e32 v74, 0xffff0000, v77
	v_mul_f32_e32 v74, v101, v74
	v_cvt_pk_bf16_f32 v73, v73, v74
	global_store_dwordx4 v[104:105], v[70:73], off offset:256
	s_nop 1
	v_pk_mul_f32 v[72:73], v[44:45], s[72:73] op_sel_hi:[1,0]
	v_pk_mul_f32 v[44:45], v[42:43], s[72:73] op_sel_hi:[1,0]
	v_lshlrev_b32_e32 v42, 16, v58
	v_and_b32_e32 v43, 0xffff0000, v58
	v_mul_f32_e32 v42, v46, v42
	v_mul_f32_e32 v43, v47, v43
	v_cvt_pk_bf16_f32 v42, v42, v43
	v_lshlrev_b32_e32 v43, 16, v59
	v_and_b32_e32 v46, 0xffff0000, v59
	v_mul_f32_e32 v43, v48, v43
	v_mul_f32_e32 v46, v49, v46
	v_cvt_pk_bf16_f32 v43, v43, v46
	v_lshlrev_b32_e32 v46, 16, v60
	v_mul_f32_e32 v44, v44, v46
	v_and_b32_e32 v46, 0xffff0000, v60
	v_mul_f32_e32 v45, v45, v46
	v_cvt_pk_bf16_f32 v44, v44, v45
	v_lshlrev_b32_e32 v45, 16, v61
	v_and_b32_e32 v46, 0xffff0000, v61
	v_lshlrev_b64 v[70:71], 11, v[86:87]
	v_mul_f32_e32 v45, v72, v45
	v_mul_f32_e32 v46, v73, v46
	v_cvt_pk_bf16_f32 v45, v45, v46
	v_lshl_add_u64 v[46:47], s[74:75], 0, v[70:71]
	v_lshl_add_u64 v[46:47], v[46:47], 0, v[194:195]
	global_store_dwordx4 v[46:47], v[42:45], off
	s_nop 1
	v_pk_mul_f32 v[42:43], v[36:37], s[72:73] op_sel_hi:[1,0]
	v_pk_mul_f32 v[36:37], v[34:35], s[72:73] op_sel_hi:[1,0]
	v_lshlrev_b32_e32 v34, 16, v62
	v_and_b32_e32 v35, 0xffff0000, v62
	v_mul_f32_e32 v34, v38, v34
	v_mul_f32_e32 v35, v39, v35
	v_cvt_pk_bf16_f32 v34, v34, v35
	v_lshlrev_b32_e32 v35, 16, v63
	v_and_b32_e32 v38, 0xffff0000, v63
	v_mul_f32_e32 v35, v40, v35
	v_mul_f32_e32 v38, v41, v38
	v_cvt_pk_bf16_f32 v35, v35, v38
	v_lshlrev_b32_e32 v38, 16, v64
	v_mul_f32_e32 v36, v36, v38
	v_and_b32_e32 v38, 0xffff0000, v64
	v_mul_f32_e32 v37, v37, v38
	v_cvt_pk_bf16_f32 v36, v36, v37
	v_lshlrev_b32_e32 v37, 16, v65
	v_mul_f32_e32 v37, v42, v37
	v_and_b32_e32 v38, 0xffff0000, v65
	v_mul_f32_e32 v38, v43, v38
	v_cvt_pk_bf16_f32 v37, v37, v38
	global_store_dwordx4 v[46:47], v[34:37], off offset:256
	s_nop 1
	v_pk_mul_f32 v[36:37], v[28:29], s[72:73] op_sel_hi:[1,0]
	v_pk_mul_f32 v[28:29], v[26:27], s[72:73] op_sel_hi:[1,0]
	v_lshlrev_b32_e32 v26, 16, v78
	v_and_b32_e32 v27, 0xffff0000, v78
	v_mul_f32_e32 v26, v30, v26
	v_mul_f32_e32 v27, v31, v27
	v_cvt_pk_bf16_f32 v26, v26, v27
	v_lshlrev_b32_e32 v27, 16, v79
	v_and_b32_e32 v30, 0xffff0000, v79
	v_mul_f32_e32 v27, v32, v27
	v_mul_f32_e32 v30, v33, v30
	v_cvt_pk_bf16_f32 v27, v27, v30
	v_lshlrev_b32_e32 v30, 16, v80
	v_mul_f32_e32 v28, v28, v30
	v_and_b32_e32 v30, 0xffff0000, v80
	v_mul_f32_e32 v29, v29, v30
	v_cvt_pk_bf16_f32 v28, v28, v29
	v_lshlrev_b32_e32 v29, 16, v81
	v_and_b32_e32 v30, 0xffff0000, v81
	v_lshlrev_b64 v[34:35], 11, v[68:69]
	v_mul_f32_e32 v29, v36, v29
	v_mul_f32_e32 v30, v37, v30
	v_cvt_pk_bf16_f32 v29, v29, v30
	v_lshl_add_u64 v[30:31], s[74:75], 0, v[34:35]
	v_lshl_add_u64 v[30:31], v[30:31], 0, v[194:195]
	global_store_dwordx4 v[30:31], v[26:29], off
	s_nop 1
	v_pk_mul_f32 v[26:27], v[20:21], s[72:73] op_sel_hi:[1,0]
	v_pk_mul_f32 v[20:21], v[18:19], s[72:73] op_sel_hi:[1,0]
	v_lshlrev_b32_e32 v18, 16, v82
	v_and_b32_e32 v19, 0xffff0000, v82
	v_mul_f32_e32 v18, v22, v18
	v_mul_f32_e32 v19, v23, v19
	v_cvt_pk_bf16_f32 v18, v18, v19
	v_lshlrev_b32_e32 v19, 16, v83
	v_and_b32_e32 v22, 0xffff0000, v83
	v_mul_f32_e32 v19, v24, v19
	v_mul_f32_e32 v22, v25, v22
	v_cvt_pk_bf16_f32 v19, v19, v22
	v_lshlrev_b32_e32 v22, 16, v84
	v_mul_f32_e32 v20, v20, v22
	v_and_b32_e32 v22, 0xffff0000, v84
	v_mul_f32_e32 v21, v21, v22
	v_cvt_pk_bf16_f32 v20, v20, v21
	v_lshlrev_b32_e32 v21, 16, v85
	v_mul_f32_e32 v21, v26, v21
	v_and_b32_e32 v22, 0xffff0000, v85
	v_mul_f32_e32 v22, v27, v22
	v_cvt_pk_bf16_f32 v21, v21, v22
	global_store_dwordx4 v[30:31], v[18:21], off offset:256
	s_nop 1
	v_pk_mul_f32 v[20:21], v[12:13], s[72:73] op_sel_hi:[1,0]
	v_pk_mul_f32 v[12:13], v[10:11], s[72:73] op_sel_hi:[1,0]
	v_lshlrev_b32_e32 v10, 16, v54
	v_and_b32_e32 v11, 0xffff0000, v54
	v_mul_f32_e32 v10, v14, v10
	v_mul_f32_e32 v11, v15, v11
	v_cvt_pk_bf16_f32 v10, v10, v11
	v_lshlrev_b32_e32 v11, 16, v55
	v_and_b32_e32 v14, 0xffff0000, v55
	v_mul_f32_e32 v11, v16, v11
	v_mul_f32_e32 v14, v17, v14
	v_cvt_pk_bf16_f32 v11, v11, v14
	v_lshlrev_b32_e32 v14, 16, v56
	v_mul_f32_e32 v12, v12, v14
	v_and_b32_e32 v14, 0xffff0000, v56
	v_mul_f32_e32 v13, v13, v14
	v_cvt_pk_bf16_f32 v12, v12, v13
	v_lshlrev_b32_e32 v13, 16, v57
	v_and_b32_e32 v14, 0xffff0000, v57
	v_lshlrev_b64 v[18:19], 11, v[66:67]
	v_mul_f32_e32 v13, v20, v13
	v_mul_f32_e32 v14, v21, v14
	v_cvt_pk_bf16_f32 v13, v13, v14
	v_lshl_add_u64 v[14:15], s[74:75], 0, v[18:19]
	v_lshl_add_u64 v[14:15], v[14:15], 0, v[194:195]
	global_store_dwordx4 v[14:15], v[10:13], off
	s_nop 1
	v_pk_mul_f32 v[10:11], v[4:5], s[72:73] op_sel_hi:[1,0]
	v_pk_mul_f32 v[4:5], v[2:3], s[72:73] op_sel_hi:[1,0]
	v_lshlrev_b32_e32 v2, 16, v50
	v_and_b32_e32 v3, 0xffff0000, v50
	v_mul_f32_e32 v2, v6, v2
	v_mul_f32_e32 v3, v7, v3
	v_cvt_pk_bf16_f32 v2, v2, v3
	v_lshlrev_b32_e32 v3, 16, v51
	v_and_b32_e32 v6, 0xffff0000, v51
	v_mul_f32_e32 v3, v8, v3
	v_mul_f32_e32 v6, v9, v6
	v_cvt_pk_bf16_f32 v3, v3, v6
	v_lshlrev_b32_e32 v6, 16, v52
	v_mul_f32_e32 v4, v4, v6
	v_and_b32_e32 v6, 0xffff0000, v52
	v_mul_f32_e32 v5, v5, v6
	v_cvt_pk_bf16_f32 v4, v4, v5
	v_lshlrev_b32_e32 v5, 16, v53
	v_mul_f32_e32 v5, v10, v5
	v_and_b32_e32 v6, 0xffff0000, v53
	v_mul_f32_e32 v6, v11, v6
	v_cvt_pk_bf16_f32 v5, v5, v6
	global_store_dwordx4 v[14:15], v[2:5], off offset:256
	s_and_b64 vcc, exec, s[62:63]
	s_mov_b32 s29, s71
	s_mov_b32 s28, s0
	s_mov_b64 s[8:9], s[60:61]
	s_mov_b64 s[6:7], s[52:53]
	s_cbranch_vccz .LBB0_252
	s_waitcnt vmcnt(0)
	v_readlane_b32 s28, v250, 12
	s_cmpk_gt_u32 s4, 0xff
	v_readlane_b32 s29, v250, 13
	s_mov_b32 s70, 0x800000
	s_cbranch_scc1 .LBB0_259
	s_barrier

.LBB0_368:
	v_add_u32_e32 v253, 0x10000, v201
	ds_read_b128 v[130:133], v253
	ds_read_b128 v[134:137], v253 offset:1024
	ds_read_b128 v[138:141], v253 offset:2048
	ds_read_b128 v[142:145], v253 offset:3072
	s_add_u32 s10, s8, 0xfffc0080
	s_addc_u32 s11, s9, -1
	s_cmp_eq_u32 s29, 12
	s_cselect_b32 s11, s81, s11
	s_cselect_b32 s10, s80, s10
	s_cselect_b32 s53, s83, s28
	s_cselect_b32 s52, s82, s7
	s_add_i32 m0, s34, 0xc000
	ds_read_b128 v[146:149], v199
	ds_read_b128 v[150:153], v199 offset:1024
	ds_read_b128 v[154:157], v199 offset:2048
	ds_read_b128 v[158:161], v199 offset:3072
	ds_read_b128 v[162:165], v199 offset:4096
	ds_read_b128 v[166:169], v199 offset:5120
	ds_read_b128 v[170:173], v199 offset:6144
	ds_read_b128 v[174:177], v199 offset:7168
	global_load_lds_dwordx4 v212, s[8:9]
	s_add_i32 m0, s34, 0xe000
	s_nop 0
	global_load_lds_dwordx4 v214, s[8:9]
	s_waitcnt lgkmcnt(8)
	s_setprio 1
	s_barrier
	s_waitcnt lgkmcnt(0)
	v_mfma_f32_16x16x32_bf16 v[126:129], v[130:133], v[146:149], v[126:129]
	v_mfma_f32_16x16x32_bf16 v[122:125], v[138:141], v[146:149], v[122:125]
	v_mfma_f32_16x16x32_bf16 v[118:121], v[130:133], v[154:157], v[118:121]
	v_mfma_f32_16x16x32_bf16 v[114:117], v[138:141], v[154:157], v[114:117]
	v_mfma_f32_16x16x32_bf16 v[110:113], v[130:133], v[162:165], v[110:113]
	v_mfma_f32_16x16x32_bf16 v[106:109], v[138:141], v[162:165], v[106:109]
	v_mfma_f32_16x16x32_bf16 v[102:105], v[130:133], v[170:173], v[102:105]
	v_mfma_f32_16x16x32_bf16 v[98:101], v[138:141], v[170:173], v[98:101]
	v_mfma_f32_16x16x32_bf16 v[126:129], v[134:137], v[150:153], v[126:129]
	v_mfma_f32_16x16x32_bf16 v[122:125], v[142:145], v[150:153], v[122:125]
	v_mfma_f32_16x16x32_bf16 v[118:121], v[134:137], v[158:161], v[118:121]
	v_mfma_f32_16x16x32_bf16 v[114:117], v[142:145], v[158:161], v[114:117]
	v_mfma_f32_16x16x32_bf16 v[110:113], v[134:137], v[166:169], v[110:113]
	v_mfma_f32_16x16x32_bf16 v[106:109], v[142:145], v[166:169], v[106:109]
	v_mfma_f32_16x16x32_bf16 v[102:105], v[134:137], v[174:177], v[102:105]
	v_mfma_f32_16x16x32_bf16 v[98:101], v[142:145], v[174:177], v[98:101]
	s_barrier
	s_setprio 0
	s_mov_b32 m0, s35
	ds_read_b128 v[178:181], v253 offset:16384
	ds_read_b128 v[182:185], v253 offset:17408
	ds_read_b128 v[186:189], v253 offset:18432
	ds_read_b128 v[190:193], v253 offset:19456
	global_load_lds_dwordx4 v194, s[52:53]
	s_mov_b32 m0, s42
	s_nop 0
	global_load_lds_dwordx4 v210, s[52:53]
	s_setprio 1
	s_barrier
	s_waitcnt lgkmcnt(0)
	v_mfma_f32_16x16x32_bf16 v[94:97], v[178:181], v[146:149], v[94:97]
	v_mfma_f32_16x16x32_bf16 v[90:93], v[186:189], v[146:149], v[90:93]
	v_mfma_f32_16x16x32_bf16 v[86:89], v[178:181], v[154:157], v[86:89]
	v_mfma_f32_16x16x32_bf16 v[82:85], v[186:189], v[154:157], v[82:85]
	v_mfma_f32_16x16x32_bf16 v[78:81], v[178:181], v[162:165], v[78:81]
	v_mfma_f32_16x16x32_bf16 v[74:77], v[186:189], v[162:165], v[74:77]
	v_mfma_f32_16x16x32_bf16 v[70:73], v[178:181], v[170:173], v[70:73]
	v_mfma_f32_16x16x32_bf16 v[66:69], v[186:189], v[170:173], v[66:69]
	v_mfma_f32_16x16x32_bf16 v[94:97], v[182:185], v[150:153], v[94:97]
	v_mfma_f32_16x16x32_bf16 v[90:93], v[190:193], v[150:153], v[90:93]
	v_mfma_f32_16x16x32_bf16 v[86:89], v[182:185], v[158:161], v[86:89]
	v_mfma_f32_16x16x32_bf16 v[82:85], v[190:193], v[158:161], v[82:85]
	v_mfma_f32_16x16x32_bf16 v[78:81], v[182:185], v[166:169], v[78:81]
	v_mfma_f32_16x16x32_bf16 v[74:77], v[190:193], v[166:169], v[74:77]
	v_mfma_f32_16x16x32_bf16 v[70:73], v[182:185], v[174:177], v[70:73]
	s_mov_b32 m0, s34
	v_mfma_f32_16x16x32_bf16 v[66:69], v[190:193], v[174:177], v[66:69]
	s_barrier
	s_setprio 0
	ds_read_b128 v[146:149], v199 offset:16384
	ds_read_b128 v[150:153], v199 offset:17408
	ds_read_b128 v[154:157], v199 offset:18432
	ds_read_b128 v[158:161], v199 offset:19456
	ds_read_b128 v[162:165], v199 offset:20480
	ds_read_b128 v[166:169], v199 offset:21504
	ds_read_b128 v[170:173], v199 offset:22528
	ds_read_b128 v[174:177], v199 offset:23552
	global_load_lds_dwordx4 v206, s[10:11]
	s_mov_b32 m0, s56
	s_nop 0
	global_load_lds_dwordx4 v208, s[10:11]
	s_setprio 1
	s_barrier
	s_waitcnt lgkmcnt(0)
	v_mfma_f32_16x16x32_bf16 v[62:65], v[130:133], v[146:149], v[62:65]
	v_mfma_f32_16x16x32_bf16 v[58:61], v[138:141], v[146:149], v[58:61]
	v_mfma_f32_16x16x32_bf16 v[54:57], v[130:133], v[154:157], v[54:57]
	v_mfma_f32_16x16x32_bf16 v[50:53], v[138:141], v[154:157], v[50:53]
	v_mfma_f32_16x16x32_bf16 v[46:49], v[130:133], v[162:165], v[46:49]
	v_mfma_f32_16x16x32_bf16 v[42:45], v[138:141], v[162:165], v[42:45]
	v_mfma_f32_16x16x32_bf16 v[38:41], v[130:133], v[170:173], v[38:41]
	v_mfma_f32_16x16x32_bf16 v[34:37], v[138:141], v[170:173], v[34:37]
	v_mfma_f32_16x16x32_bf16 v[62:65], v[134:137], v[150:153], v[62:65]
	v_mfma_f32_16x16x32_bf16 v[58:61], v[142:145], v[150:153], v[58:61]
	v_mfma_f32_16x16x32_bf16 v[54:57], v[134:137], v[158:161], v[54:57]
	v_mfma_f32_16x16x32_bf16 v[50:53], v[142:145], v[158:161], v[50:53]
	v_mfma_f32_16x16x32_bf16 v[46:49], v[134:137], v[166:169], v[46:49]
	v_mfma_f32_16x16x32_bf16 v[42:45], v[142:145], v[166:169], v[42:45]
	v_mfma_f32_16x16x32_bf16 v[38:41], v[134:137], v[174:177], v[38:41]
	v_mfma_f32_16x16x32_bf16 v[34:37], v[142:145], v[174:177], v[34:37]
	s_barrier
	s_setprio 0
	s_add_u32 s86, s52, 0x40000
	s_addc_u32 s87, s53, 0
	s_mov_b32 m0, s57
	s_nop 0
	global_load_lds_dwordx4 v194, s[86:87]
	s_mov_b32 m0, s67
	s_nop 0
	global_load_lds_dwordx4 v210, s[86:87]
	s_waitcnt vmcnt(6)
	s_setprio 1
	s_barrier
	v_mfma_f32_16x16x32_bf16 v[30:33], v[178:181], v[146:149], v[30:33]
	v_mfma_f32_16x16x32_bf16 v[26:29], v[186:189], v[146:149], v[26:29]
	v_mfma_f32_16x16x32_bf16 v[22:25], v[178:181], v[154:157], v[22:25]
	v_mfma_f32_16x16x32_bf16 v[18:21], v[186:189], v[154:157], v[18:21]
	v_mfma_f32_16x16x32_bf16 v[14:17], v[178:181], v[162:165], v[14:17]
	v_mfma_f32_16x16x32_bf16 v[10:13], v[186:189], v[162:165], v[10:13]
	v_mfma_f32_16x16x32_bf16 v[6:9], v[178:181], v[170:173], v[6:9]
	v_mfma_f32_16x16x32_bf16 v[2:5], v[186:189], v[170:173], v[2:5]
	v_mfma_f32_16x16x32_bf16 v[30:33], v[182:185], v[150:153], v[30:33]
	v_mfma_f32_16x16x32_bf16 v[26:29], v[190:193], v[150:153], v[26:29]
	v_mfma_f32_16x16x32_bf16 v[22:25], v[182:185], v[158:161], v[22:25]
	v_mfma_f32_16x16x32_bf16 v[18:21], v[190:193], v[158:161], v[18:21]
	v_mfma_f32_16x16x32_bf16 v[14:17], v[182:185], v[166:169], v[14:17]
	v_mfma_f32_16x16x32_bf16 v[10:13], v[190:193], v[166:169], v[10:13]
	v_mfma_f32_16x16x32_bf16 v[6:9], v[182:185], v[174:177], v[6:9]
	v_mfma_f32_16x16x32_bf16 v[2:5], v[190:193], v[174:177], v[2:5]
	s_barrier
	s_setprio 0
	ds_read_b128 v[130:133], v253 offset:32768
	ds_read_b128 v[134:137], v253 offset:33792
	ds_read_b128 v[138:141], v253 offset:34816
	ds_read_b128 v[142:145], v253 offset:35840
	s_add_u32 s10, s10, 0x40000
	s_addc_u32 s11, s11, 0
	s_mov_b32 m0, s70
	ds_read_b128 v[146:149], v199 offset:32768
	ds_read_b128 v[150:153], v199 offset:33792
	ds_read_b128 v[154:157], v199 offset:34816
	ds_read_b128 v[158:161], v199 offset:35840
	ds_read_b128 v[162:165], v199 offset:36864
	ds_read_b128 v[166:169], v199 offset:37888
	ds_read_b128 v[170:173], v199 offset:38912
	ds_read_b128 v[174:177], v199 offset:39936
	global_load_lds_dwordx4 v206, s[10:11]
	s_mov_b32 m0, s71
	s_nop 0
	global_load_lds_dwordx4 v208, s[10:11]
	s_waitcnt lgkmcnt(8)
	s_setprio 1
	s_barrier
	s_waitcnt lgkmcnt(0)
	v_mfma_f32_16x16x32_bf16 v[126:129], v[130:133], v[146:149], v[126:129]
	v_mfma_f32_16x16x32_bf16 v[122:125], v[138:141], v[146:149], v[122:125]
	v_mfma_f32_16x16x32_bf16 v[118:121], v[130:133], v[154:157], v[118:121]
	v_mfma_f32_16x16x32_bf16 v[114:117], v[138:141], v[154:157], v[114:117]
	v_mfma_f32_16x16x32_bf16 v[110:113], v[130:133], v[162:165], v[110:113]
	v_mfma_f32_16x16x32_bf16 v[106:109], v[138:141], v[162:165], v[106:109]
	v_mfma_f32_16x16x32_bf16 v[102:105], v[130:133], v[170:173], v[102:105]
	v_mfma_f32_16x16x32_bf16 v[98:101], v[138:141], v[170:173], v[98:101]
	v_mfma_f32_16x16x32_bf16 v[126:129], v[134:137], v[150:153], v[126:129]
	v_mfma_f32_16x16x32_bf16 v[122:125], v[142:145], v[150:153], v[122:125]
	v_mfma_f32_16x16x32_bf16 v[118:121], v[134:137], v[158:161], v[118:121]
	v_mfma_f32_16x16x32_bf16 v[114:117], v[142:145], v[158:161], v[114:117]
	v_mfma_f32_16x16x32_bf16 v[110:113], v[134:137], v[166:169], v[110:113]
	v_mfma_f32_16x16x32_bf16 v[106:109], v[142:145], v[166:169], v[106:109]
	v_mfma_f32_16x16x32_bf16 v[102:105], v[134:137], v[174:177], v[102:105]
	v_mfma_f32_16x16x32_bf16 v[98:101], v[142:145], v[174:177], v[98:101]
	s_barrier
	s_setprio 0
	s_mov_b32 m0, s78
	ds_read_b128 v[178:181], v253 offset:49152
	ds_read_b128 v[182:185], v253 offset:50176
	ds_read_b128 v[186:189], v253 offset:51200
	ds_read_b128 v[190:193], v253 offset:52224
	s_add_u32 s98, s52, 0x80
	s_addc_u32 s99, s53, 0
	global_load_lds_dwordx4 v194, s[98:99]
	s_mov_b32 m0, s79
	s_nop 0
	global_load_lds_dwordx4 v210, s[98:99]
	s_setprio 1
	s_barrier
	s_waitcnt lgkmcnt(0)
	v_mfma_f32_16x16x32_bf16 v[94:97], v[178:181], v[146:149], v[94:97]
	v_mfma_f32_16x16x32_bf16 v[90:93], v[186:189], v[146:149], v[90:93]
	v_mfma_f32_16x16x32_bf16 v[86:89], v[178:181], v[154:157], v[86:89]
	v_mfma_f32_16x16x32_bf16 v[82:85], v[186:189], v[154:157], v[82:85]
	v_mfma_f32_16x16x32_bf16 v[78:81], v[178:181], v[162:165], v[78:81]
	v_mfma_f32_16x16x32_bf16 v[74:77], v[186:189], v[162:165], v[74:77]
	v_mfma_f32_16x16x32_bf16 v[70:73], v[178:181], v[170:173], v[70:73]
	v_mfma_f32_16x16x32_bf16 v[66:69], v[186:189], v[170:173], v[66:69]
	v_mfma_f32_16x16x32_bf16 v[94:97], v[182:185], v[150:153], v[94:97]
	v_mfma_f32_16x16x32_bf16 v[90:93], v[190:193], v[150:153], v[90:93]
	v_mfma_f32_16x16x32_bf16 v[86:89], v[182:185], v[158:161], v[86:89]
	v_mfma_f32_16x16x32_bf16 v[82:85], v[190:193], v[158:161], v[82:85]
	v_mfma_f32_16x16x32_bf16 v[78:81], v[182:185], v[166:169], v[78:81]
	v_mfma_f32_16x16x32_bf16 v[74:77], v[190:193], v[166:169], v[74:77]
	v_mfma_f32_16x16x32_bf16 v[70:73], v[182:185], v[174:177], v[70:73]
	s_mov_b32 m0, s26
	v_mfma_f32_16x16x32_bf16 v[66:69], v[190:193], v[174:177], v[66:69]
	s_barrier
	s_setprio 0
	ds_read_b128 v[146:149], v199 offset:49152
	ds_read_b128 v[150:153], v199 offset:50176
	ds_read_b128 v[154:157], v199 offset:51200
	ds_read_b128 v[158:161], v199 offset:52224
	ds_read_b128 v[162:165], v199 offset:53248
	ds_read_b128 v[166:169], v199 offset:54272
	ds_read_b128 v[170:173], v199 offset:55296
	ds_read_b128 v[174:177], v199 offset:56320
	s_add_u32 s100, s10, 0xfffc0080
	s_addc_u32 s101, s11, -1
	global_load_lds_dwordx4 v206, s[100:101]
	s_mov_b32 m0, s4
	s_nop 0
	global_load_lds_dwordx4 v208, s[100:101]
	s_setprio 1
	s_barrier
	s_waitcnt lgkmcnt(0)
	v_mfma_f32_16x16x32_bf16 v[62:65], v[130:133], v[146:149], v[62:65]
	v_mfma_f32_16x16x32_bf16 v[58:61], v[138:141], v[146:149], v[58:61]
	v_mfma_f32_16x16x32_bf16 v[54:57], v[130:133], v[154:157], v[54:57]
	v_mfma_f32_16x16x32_bf16 v[50:53], v[138:141], v[154:157], v[50:53]
	v_mfma_f32_16x16x32_bf16 v[46:49], v[130:133], v[162:165], v[46:49]
	v_mfma_f32_16x16x32_bf16 v[42:45], v[138:141], v[162:165], v[42:45]
	v_mfma_f32_16x16x32_bf16 v[38:41], v[130:133], v[170:173], v[38:41]
	v_mfma_f32_16x16x32_bf16 v[34:37], v[138:141], v[170:173], v[34:37]
	v_mfma_f32_16x16x32_bf16 v[62:65], v[134:137], v[150:153], v[62:65]
	v_mfma_f32_16x16x32_bf16 v[58:61], v[142:145], v[150:153], v[58:61]
	v_mfma_f32_16x16x32_bf16 v[54:57], v[134:137], v[158:161], v[54:57]
	v_mfma_f32_16x16x32_bf16 v[50:53], v[142:145], v[158:161], v[50:53]
	v_mfma_f32_16x16x32_bf16 v[46:49], v[134:137], v[166:169], v[46:49]
	v_mfma_f32_16x16x32_bf16 v[42:45], v[142:145], v[166:169], v[42:45]
	v_mfma_f32_16x16x32_bf16 v[38:41], v[134:137], v[174:177], v[38:41]
	v_mfma_f32_16x16x32_bf16 v[34:37], v[142:145], v[174:177], v[34:37]
	s_barrier
	s_setprio 0
	s_add_u32 s10, s52, 0x40080
	s_addc_u32 s11, s53, 0
	s_mov_b32 m0, s5
	s_nop 0
	global_load_lds_dwordx4 v194, s[10:11]
	s_mov_b32 m0, s58
	s_nop 0
	global_load_lds_dwordx4 v210, s[10:11]
	s_waitcnt vmcnt(6)
	s_setprio 1
	s_barrier
	v_mfma_f32_16x16x32_bf16 v[30:33], v[178:181], v[146:149], v[30:33]
	v_mfma_f32_16x16x32_bf16 v[26:29], v[186:189], v[146:149], v[26:29]
	v_mfma_f32_16x16x32_bf16 v[22:25], v[178:181], v[154:157], v[22:25]
	v_mfma_f32_16x16x32_bf16 v[18:21], v[186:189], v[154:157], v[18:21]
	v_mfma_f32_16x16x32_bf16 v[14:17], v[178:181], v[162:165], v[14:17]
	v_mfma_f32_16x16x32_bf16 v[10:13], v[186:189], v[162:165], v[10:13]
	v_mfma_f32_16x16x32_bf16 v[6:9], v[178:181], v[170:173], v[6:9]
	v_mfma_f32_16x16x32_bf16 v[2:5], v[186:189], v[170:173], v[2:5]
	v_mfma_f32_16x16x32_bf16 v[30:33], v[182:185], v[150:153], v[30:33]
	v_mfma_f32_16x16x32_bf16 v[26:29], v[190:193], v[150:153], v[26:29]
	v_mfma_f32_16x16x32_bf16 v[22:25], v[182:185], v[158:161], v[22:25]
	v_mfma_f32_16x16x32_bf16 v[18:21], v[190:193], v[158:161], v[18:21]
	v_mfma_f32_16x16x32_bf16 v[14:17], v[182:185], v[166:169], v[14:17]
	v_mfma_f32_16x16x32_bf16 v[10:13], v[190:193], v[166:169], v[10:13]
	v_mfma_f32_16x16x32_bf16 v[6:9], v[182:185], v[174:177], v[6:9]
	v_mfma_f32_16x16x32_bf16 v[2:5], v[190:193], v[174:177], v[2:5]
	s_setprio 0
	s_add_i32 s29, s29, 2
	s_add_u32 s8, s8, 0x100
	s_addc_u32 s9, s9, 0
	s_add_u32 s7, s7, 0x100
	s_addc_u32 s28, s28, 0
	s_cmp_gt_u32 s29, 13
	s_barrier
	s_cbranch_scc0 .LBB0_368
	s_cmp_gt_i32 s95, 1
	s_cselect_b64 s[52:53], -1, 0
	s_mul_i32 s7, s6, 0x680000
	s_lshl_b32 s8, s95, 12
	s_lshl_b32 s9, s54, 9
	s_add_i32 s7, s7, s8
	s_add_i32 s7, s7, s9
	s_add_i32 s7, s7, 0x3800
	s_add_u32 s20, s50, s7
	s_addc_u32 s21, s51, 0
	s_lshl_b32 s7, s6, 20
	s_add_i32 s7, s7, s9
	s_add_u32 s10, s96, s7
	s_addc_u32 s11, s97, 0
	s_mov_b32 s86, 0xbfb8aa3b
	s_mov_b32 s87, 0xbfb8aa3b
	v_mul_u32_u24_e32 v253, 0x6800, v197
	v_lshlrev_b32_e32 v255, 12, v197
	v_lshl_add_u32 v253, v203, 1, v253
	v_lshl_add_u32 v255, v203, 1, v255
	v_add_u32_e32 v254, 0x1000, v253
	s_cmp_eq_u32 s95, 2
	s_cbranch_scc1 .Lem_br2
	global_load_dwordx4 v[130:133], v253, s[20:21]
	global_load_dwordx4 v[134:137], v254, s[20:21]
	global_load_dwordx4 v[138:141], v253, s[20:21] offset:256
	global_load_dwordx4 v[142:145], v254, s[20:21] offset:256
	s_add_u32 s28, s20, 0x68000
	s_addc_u32 s29, s21, 0
	global_load_dwordx4 v[146:149], v253, s[28:29]
	global_load_dwordx4 v[150:153], v254, s[28:29]
	global_load_dwordx4 v[154:157], v253, s[28:29] offset:256
	global_load_dwordx4 v[158:161], v254, s[28:29] offset:256
	s_add_u32 s28, s20, 0xd0000
	s_addc_u32 s29, s21, 0
	global_load_dwordx4 v[162:165], v253, s[28:29]
	global_load_dwordx4 v[166:169], v254, s[28:29]
	global_load_dwordx4 v[170:173], v253, s[28:29] offset:256
	global_load_dwordx4 v[174:177], v254, s[28:29] offset:256
	s_add_u32 s28, s20, 0x138000
	s_addc_u32 s29, s21, 0
	global_load_dwordx4 v[178:181], v253, s[28:29]
	global_load_dwordx4 v[182:185], v254, s[28:29]
	global_load_dwordx4 v[186:189], v253, s[28:29] offset:256
	global_load_dwordx4 v[190:193], v254, s[28:29] offset:256
	s_waitcnt vmcnt(12)
	v_lshlrev_b32_e32 v216, 16, v130
	v_and_b32_e32 v217, 0xffff0000, v130
	v_lshlrev_b32_e32 v218, 16, v131
	v_and_b32_e32 v219, 0xffff0000, v131
	v_lshlrev_b32_e32 v220, 16, v132
	v_and_b32_e32 v221, 0xffff0000, v132
	v_lshlrev_b32_e32 v222, 16, v133
	v_and_b32_e32 v223, 0xffff0000, v133
	v_pk_mul_f32 v[216:217], v[216:217], s[86:87] op_sel_hi:[1,0]
	v_pk_mul_f32 v[218:219], v[218:219], s[86:87] op_sel_hi:[1,0]
	v_pk_mul_f32 v[220:221], v[220:221], s[86:87] op_sel_hi:[1,0]
	v_pk_mul_f32 v[222:223], v[222:223], s[86:87] op_sel_hi:[1,0]
	v_exp_f32_e32 v216, v216
	v_exp_f32_e32 v217, v217
	v_exp_f32_e32 v218, v218
	v_exp_f32_e32 v219, v219
	v_exp_f32_e32 v220, v220
	v_exp_f32_e32 v221, v221
	v_exp_f32_e32 v222, v222
	v_exp_f32_e32 v223, v223
	v_pk_add_f32 v[216:217], v[216:217], 1.0 op_sel_hi:[1,0]
	v_pk_add_f32 v[218:219], v[218:219], 1.0 op_sel_hi:[1,0]
	v_pk_add_f32 v[220:221], v[220:221], 1.0 op_sel_hi:[1,0]
	v_pk_add_f32 v[222:223], v[222:223], 1.0 op_sel_hi:[1,0]
	v_rcp_f32_e32 v216, v216
	v_rcp_f32_e32 v217, v217
	v_rcp_f32_e32 v218, v218
	v_rcp_f32_e32 v219, v219
	v_rcp_f32_e32 v220, v220
	v_rcp_f32_e32 v221, v221
	v_rcp_f32_e32 v222, v222
	v_rcp_f32_e32 v223, v223
	v_lshlrev_b32_e32 v242, 16, v134
	v_and_b32_e32 v243, 0xffff0000, v134
	v_lshlrev_b32_e32 v244, 16, v135
	v_and_b32_e32 v245, 0xffff0000, v135
	v_lshlrev_b32_e32 v246, 16, v136
	v_and_b32_e32 v247, 0xffff0000, v136
	v_lshlrev_b32_e32 v248, 16, v137
	v_and_b32_e32 v249, 0xffff0000, v137
	v_pk_mul_f32 v[242:243], v[242:243], s[86:87] op_sel_hi:[1,0]
	v_pk_mul_f32 v[244:245], v[244:245], s[86:87] op_sel_hi:[1,0]
	v_pk_mul_f32 v[246:247], v[246:247], s[86:87] op_sel_hi:[1,0]
	v_pk_mul_f32 v[248:249], v[248:249], s[86:87] op_sel_hi:[1,0]
	v_exp_f32_e32 v242, v242
	v_exp_f32_e32 v243, v243
	v_exp_f32_e32 v244, v244
	v_exp_f32_e32 v245, v245
	v_exp_f32_e32 v246, v246
	v_exp_f32_e32 v247, v247
	v_exp_f32_e32 v248, v248
	v_exp_f32_e32 v249, v249
	v_pk_add_f32 v[242:243], v[242:243], 1.0 op_sel_hi:[1,0]
	v_pk_add_f32 v[244:245], v[244:245], 1.0 op_sel_hi:[1,0]
	v_pk_add_f32 v[246:247], v[246:247], 1.0 op_sel_hi:[1,0]
	v_pk_add_f32 v[248:249], v[248:249], 1.0 op_sel_hi:[1,0]
	v_pk_mul_f32 v[216:217], v[216:217], v[242:243]
	v_pk_mul_f32 v[218:219], v[218:219], v[244:245]
	v_pk_mul_f32 v[220:221], v[220:221], v[246:247]
	v_pk_mul_f32 v[222:223], v[222:223], v[248:249]
	v_pk_mul_f32 v[126:127], v[126:127], v[216:217]
	v_pk_mul_f32 v[128:129], v[128:129], v[218:219]
	v_pk_mul_f32 v[122:123], v[122:123], v[220:221]
	v_pk_mul_f32 v[124:125], v[124:125], v[222:223]
	v_lshlrev_b32_e32 v216, 16, v138
	v_and_b32_e32 v217, 0xffff0000, v138
	v_lshlrev_b32_e32 v218, 16, v139
	v_and_b32_e32 v219, 0xffff0000, v139
	v_lshlrev_b32_e32 v220, 16, v140
	v_and_b32_e32 v221, 0xffff0000, v140
	v_lshlrev_b32_e32 v222, 16, v141
	v_and_b32_e32 v223, 0xffff0000, v141
	v_pk_mul_f32 v[216:217], v[216:217], s[86:87] op_sel_hi:[1,0]
	v_pk_mul_f32 v[218:219], v[218:219], s[86:87] op_sel_hi:[1,0]
	v_pk_mul_f32 v[220:221], v[220:221], s[86:87] op_sel_hi:[1,0]
	v_pk_mul_f32 v[222:223], v[222:223], s[86:87] op_sel_hi:[1,0]
	v_exp_f32_e32 v216, v216
	v_exp_f32_e32 v217, v217
	v_exp_f32_e32 v218, v218
	v_exp_f32_e32 v219, v219
	v_exp_f32_e32 v220, v220
	v_exp_f32_e32 v221, v221
	v_exp_f32_e32 v222, v222
	v_exp_f32_e32 v223, v223
	v_pk_add_f32 v[216:217], v[216:217], 1.0 op_sel_hi:[1,0]
	v_pk_add_f32 v[218:219], v[218:219], 1.0 op_sel_hi:[1,0]
	v_pk_add_f32 v[220:221], v[220:221], 1.0 op_sel_hi:[1,0]
	v_pk_add_f32 v[222:223], v[222:223], 1.0 op_sel_hi:[1,0]
	v_rcp_f32_e32 v216, v216
	v_rcp_f32_e32 v217, v217
	v_rcp_f32_e32 v218, v218
	v_rcp_f32_e32 v219, v219
	v_rcp_f32_e32 v220, v220
	v_rcp_f32_e32 v221, v221
	v_rcp_f32_e32 v222, v222
	v_rcp_f32_e32 v223, v223
	v_lshlrev_b32_e32 v242, 16, v142
	v_and_b32_e32 v243, 0xffff0000, v142
	v_lshlrev_b32_e32 v244, 16, v143
	v_and_b32_e32 v245, 0xffff0000, v143
	v_lshlrev_b32_e32 v246, 16, v144
	v_and_b32_e32 v247, 0xffff0000, v144
	v_lshlrev_b32_e32 v248, 16, v145
	v_and_b32_e32 v249, 0xffff0000, v145
	v_pk_mul_f32 v[242:243], v[242:243], s[86:87] op_sel_hi:[1,0]
	v_pk_mul_f32 v[244:245], v[244:245], s[86:87] op_sel_hi:[1,0]
	v_pk_mul_f32 v[246:247], v[246:247], s[86:87] op_sel_hi:[1,0]
	v_pk_mul_f32 v[248:249], v[248:249], s[86:87] op_sel_hi:[1,0]
	v_exp_f32_e32 v242, v242
	v_exp_f32_e32 v243, v243
	v_exp_f32_e32 v244, v244
	v_exp_f32_e32 v245, v245
	v_exp_f32_e32 v246, v246
	v_exp_f32_e32 v247, v247
	v_exp_f32_e32 v248, v248
	v_exp_f32_e32 v249, v249
	v_pk_add_f32 v[242:243], v[242:243], 1.0 op_sel_hi:[1,0]
	v_pk_add_f32 v[244:245], v[244:245], 1.0 op_sel_hi:[1,0]
	v_pk_add_f32 v[246:247], v[246:247], 1.0 op_sel_hi:[1,0]
	v_pk_add_f32 v[248:249], v[248:249], 1.0 op_sel_hi:[1,0]
	v_pk_mul_f32 v[216:217], v[216:217], v[242:243]
	v_pk_mul_f32 v[218:219], v[218:219], v[244:245]
	v_pk_mul_f32 v[220:221], v[220:221], v[246:247]
	v_pk_mul_f32 v[222:223], v[222:223], v[248:249]
	v_pk_mul_f32 v[94:95], v[94:95], v[216:217]
	v_pk_mul_f32 v[96:97], v[96:97], v[218:219]
	v_pk_mul_f32 v[90:91], v[90:91], v[220:221]
	v_pk_mul_f32 v[92:93], v[92:93], v[222:223]
	s_add_u32 s28, s20, 0x340000
	s_addc_u32 s29, s21, 0
	global_load_dwordx4 v[130:133], v253, s[28:29]
	global_load_dwordx4 v[134:137], v254, s[28:29]
	global_load_dwordx4 v[138:141], v253, s[28:29] offset:256
	global_load_dwordx4 v[142:145], v254, s[28:29] offset:256
	s_waitcnt vmcnt(12)
	v_lshlrev_b32_e32 v216, 16, v146
	v_and_b32_e32 v217, 0xffff0000, v146
	v_lshlrev_b32_e32 v218, 16, v147
	v_and_b32_e32 v219, 0xffff0000, v147
	v_lshlrev_b32_e32 v220, 16, v148
	v_and_b32_e32 v221, 0xffff0000, v148
	v_lshlrev_b32_e32 v222, 16, v149
	v_and_b32_e32 v223, 0xffff0000, v149
	v_pk_mul_f32 v[216:217], v[216:217], s[86:87] op_sel_hi:[1,0]
	v_pk_mul_f32 v[218:219], v[218:219], s[86:87] op_sel_hi:[1,0]
	v_pk_mul_f32 v[220:221], v[220:221], s[86:87] op_sel_hi:[1,0]
	v_pk_mul_f32 v[222:223], v[222:223], s[86:87] op_sel_hi:[1,0]
	v_exp_f32_e32 v216, v216
	v_exp_f32_e32 v217, v217
	v_exp_f32_e32 v218, v218
	v_exp_f32_e32 v219, v219
	v_exp_f32_e32 v220, v220
	v_exp_f32_e32 v221, v221
	v_exp_f32_e32 v222, v222
	v_exp_f32_e32 v223, v223
	v_pk_add_f32 v[216:217], v[216:217], 1.0 op_sel_hi:[1,0]
	v_pk_add_f32 v[218:219], v[218:219], 1.0 op_sel_hi:[1,0]
	v_pk_add_f32 v[220:221], v[220:221], 1.0 op_sel_hi:[1,0]
	v_pk_add_f32 v[222:223], v[222:223], 1.0 op_sel_hi:[1,0]
	v_rcp_f32_e32 v216, v216
	v_rcp_f32_e32 v217, v217
	v_rcp_f32_e32 v218, v218
	v_rcp_f32_e32 v219, v219
	v_rcp_f32_e32 v220, v220
	v_rcp_f32_e32 v221, v221
	v_rcp_f32_e32 v222, v222
	v_rcp_f32_e32 v223, v223
	v_lshlrev_b32_e32 v242, 16, v150
	v_and_b32_e32 v243, 0xffff0000, v150
	v_lshlrev_b32_e32 v244, 16, v151
	v_and_b32_e32 v245, 0xffff0000, v151
	v_lshlrev_b32_e32 v246, 16, v152
	v_and_b32_e32 v247, 0xffff0000, v152
	v_lshlrev_b32_e32 v248, 16, v153
	v_and_b32_e32 v249, 0xffff0000, v153
	v_pk_mul_f32 v[242:243], v[242:243], s[86:87] op_sel_hi:[1,0]
	v_pk_mul_f32 v[244:245], v[244:245], s[86:87] op_sel_hi:[1,0]
	v_pk_mul_f32 v[246:247], v[246:247], s[86:87] op_sel_hi:[1,0]
	v_pk_mul_f32 v[248:249], v[248:249], s[86:87] op_sel_hi:[1,0]
	v_exp_f32_e32 v242, v242
	v_exp_f32_e32 v243, v243
	v_exp_f32_e32 v244, v244
	v_exp_f32_e32 v245, v245
	v_exp_f32_e32 v246, v246
	v_exp_f32_e32 v247, v247
	v_exp_f32_e32 v248, v248
	v_exp_f32_e32 v249, v249
	v_pk_add_f32 v[242:243], v[242:243], 1.0 op_sel_hi:[1,0]
	v_pk_add_f32 v[244:245], v[244:245], 1.0 op_sel_hi:[1,0]
	v_pk_add_f32 v[246:247], v[246:247], 1.0 op_sel_hi:[1,0]
	v_pk_add_f32 v[248:249], v[248:249], 1.0 op_sel_hi:[1,0]
	v_pk_mul_f32 v[216:217], v[216:217], v[242:243]
	v_pk_mul_f32 v[218:219], v[218:219], v[244:245]
	v_pk_mul_f32 v[220:221], v[220:221], v[246:247]
	v_pk_mul_f32 v[222:223], v[222:223], v[248:249]
	v_pk_mul_f32 v[118:119], v[118:119], v[216:217]
	v_pk_mul_f32 v[120:121], v[120:121], v[218:219]
	v_pk_mul_f32 v[114:115], v[114:115], v[220:221]
	v_pk_mul_f32 v[116:117], v[116:117], v[222:223]
	v_lshlrev_b32_e32 v216, 16, v154
	v_and_b32_e32 v217, 0xffff0000, v154
	v_lshlrev_b32_e32 v218, 16, v155
	v_and_b32_e32 v219, 0xffff0000, v155
	v_lshlrev_b32_e32 v220, 16, v156
	v_and_b32_e32 v221, 0xffff0000, v156
	v_lshlrev_b32_e32 v222, 16, v157
	v_and_b32_e32 v223, 0xffff0000, v157
	v_pk_mul_f32 v[216:217], v[216:217], s[86:87] op_sel_hi:[1,0]
	v_pk_mul_f32 v[218:219], v[218:219], s[86:87] op_sel_hi:[1,0]
	v_pk_mul_f32 v[220:221], v[220:221], s[86:87] op_sel_hi:[1,0]
	v_pk_mul_f32 v[222:223], v[222:223], s[86:87] op_sel_hi:[1,0]
	v_exp_f32_e32 v216, v216
	v_exp_f32_e32 v217, v217
	v_exp_f32_e32 v218, v218
	v_exp_f32_e32 v219, v219
	v_exp_f32_e32 v220, v220
	v_exp_f32_e32 v221, v221
	v_exp_f32_e32 v222, v222
	v_exp_f32_e32 v223, v223
	v_pk_add_f32 v[216:217], v[216:217], 1.0 op_sel_hi:[1,0]
	v_pk_add_f32 v[218:219], v[218:219], 1.0 op_sel_hi:[1,0]
	v_pk_add_f32 v[220:221], v[220:221], 1.0 op_sel_hi:[1,0]
	v_pk_add_f32 v[222:223], v[222:223], 1.0 op_sel_hi:[1,0]
	v_rcp_f32_e32 v216, v216
	v_rcp_f32_e32 v217, v217
	v_rcp_f32_e32 v218, v218
	v_rcp_f32_e32 v219, v219
	v_rcp_f32_e32 v220, v220
	v_rcp_f32_e32 v221, v221
	v_rcp_f32_e32 v222, v222
	v_rcp_f32_e32 v223, v223
	v_lshlrev_b32_e32 v242, 16, v158
	v_and_b32_e32 v243, 0xffff0000, v158
	v_lshlrev_b32_e32 v244, 16, v159
	v_and_b32_e32 v245, 0xffff0000, v159
	v_lshlrev_b32_e32 v246, 16, v160
	v_and_b32_e32 v247, 0xffff0000, v160
	v_lshlrev_b32_e32 v248, 16, v161
	v_and_b32_e32 v249, 0xffff0000, v161
	v_pk_mul_f32 v[242:243], v[242:243], s[86:87] op_sel_hi:[1,0]
	v_pk_mul_f32 v[244:245], v[244:245], s[86:87] op_sel_hi:[1,0]
	v_pk_mul_f32 v[246:247], v[246:247], s[86:87] op_sel_hi:[1,0]
	v_pk_mul_f32 v[248:249], v[248:249], s[86:87] op_sel_hi:[1,0]
	v_exp_f32_e32 v242, v242
	v_exp_f32_e32 v243, v243
	v_exp_f32_e32 v244, v244
	v_exp_f32_e32 v245, v245
	v_exp_f32_e32 v246, v246
	v_exp_f32_e32 v247, v247
	v_exp_f32_e32 v248, v248
	v_exp_f32_e32 v249, v249
	v_pk_add_f32 v[242:243], v[242:243], 1.0 op_sel_hi:[1,0]
	v_pk_add_f32 v[244:245], v[244:245], 1.0 op_sel_hi:[1,0]
	v_pk_add_f32 v[246:247], v[246:247], 1.0 op_sel_hi:[1,0]
	v_pk_add_f32 v[248:249], v[248:249], 1.0 op_sel_hi:[1,0]
	v_pk_mul_f32 v[216:217], v[216:217], v[242:243]
	v_pk_mul_f32 v[218:219], v[218:219], v[244:245]
	v_pk_mul_f32 v[220:221], v[220:221], v[246:247]
	v_pk_mul_f32 v[222:223], v[222:223], v[248:249]
	v_pk_mul_f32 v[86:87], v[86:87], v[216:217]
	v_pk_mul_f32 v[88:89], v[88:89], v[218:219]
	v_pk_mul_f32 v[82:83], v[82:83], v[220:221]
	v_pk_mul_f32 v[84:85], v[84:85], v[222:223]
	s_add_u32 s28, s20, 0x3a8000
	s_addc_u32 s29, s21, 0
	global_load_dwordx4 v[146:149], v253, s[28:29]
	global_load_dwordx4 v[150:153], v254, s[28:29]
	global_load_dwordx4 v[154:157], v253, s[28:29] offset:256
	global_load_dwordx4 v[158:161], v254, s[28:29] offset:256
	s_waitcnt vmcnt(12)
	v_lshlrev_b32_e32 v216, 16, v162
	v_and_b32_e32 v217, 0xffff0000, v162
	v_lshlrev_b32_e32 v218, 16, v163
	v_and_b32_e32 v219, 0xffff0000, v163
	v_lshlrev_b32_e32 v220, 16, v164
	v_and_b32_e32 v221, 0xffff0000, v164
	v_lshlrev_b32_e32 v222, 16, v165
	v_and_b32_e32 v223, 0xffff0000, v165
	v_pk_mul_f32 v[216:217], v[216:217], s[86:87] op_sel_hi:[1,0]
	v_pk_mul_f32 v[218:219], v[218:219], s[86:87] op_sel_hi:[1,0]
	v_pk_mul_f32 v[220:221], v[220:221], s[86:87] op_sel_hi:[1,0]
	v_pk_mul_f32 v[222:223], v[222:223], s[86:87] op_sel_hi:[1,0]
	v_exp_f32_e32 v216, v216
	v_exp_f32_e32 v217, v217
	v_exp_f32_e32 v218, v218
	v_exp_f32_e32 v219, v219
	v_exp_f32_e32 v220, v220
	v_exp_f32_e32 v221, v221
	v_exp_f32_e32 v222, v222
	v_exp_f32_e32 v223, v223
	v_pk_add_f32 v[216:217], v[216:217], 1.0 op_sel_hi:[1,0]
	v_pk_add_f32 v[218:219], v[218:219], 1.0 op_sel_hi:[1,0]
	v_pk_add_f32 v[220:221], v[220:221], 1.0 op_sel_hi:[1,0]
	v_pk_add_f32 v[222:223], v[222:223], 1.0 op_sel_hi:[1,0]
	v_rcp_f32_e32 v216, v216
	v_rcp_f32_e32 v217, v217
	v_rcp_f32_e32 v218, v218
	v_rcp_f32_e32 v219, v219
	v_rcp_f32_e32 v220, v220
	v_rcp_f32_e32 v221, v221
	v_rcp_f32_e32 v222, v222
	v_rcp_f32_e32 v223, v223
	v_lshlrev_b32_e32 v242, 16, v166
	v_and_b32_e32 v243, 0xffff0000, v166
	v_lshlrev_b32_e32 v244, 16, v167
	v_and_b32_e32 v245, 0xffff0000, v167
	v_lshlrev_b32_e32 v246, 16, v168
	v_and_b32_e32 v247, 0xffff0000, v168
	v_lshlrev_b32_e32 v248, 16, v169
	v_and_b32_e32 v249, 0xffff0000, v169
	v_pk_mul_f32 v[242:243], v[242:243], s[86:87] op_sel_hi:[1,0]
	v_pk_mul_f32 v[244:245], v[244:245], s[86:87] op_sel_hi:[1,0]
	v_pk_mul_f32 v[246:247], v[246:247], s[86:87] op_sel_hi:[1,0]
	v_pk_mul_f32 v[248:249], v[248:249], s[86:87] op_sel_hi:[1,0]
	v_exp_f32_e32 v242, v242
	v_exp_f32_e32 v243, v243
	v_exp_f32_e32 v244, v244
	v_exp_f32_e32 v245, v245
	v_exp_f32_e32 v246, v246
	v_exp_f32_e32 v247, v247
	v_exp_f32_e32 v248, v248
	v_exp_f32_e32 v249, v249
	v_pk_add_f32 v[242:243], v[242:243], 1.0 op_sel_hi:[1,0]
	v_pk_add_f32 v[244:245], v[244:245], 1.0 op_sel_hi:[1,0]
	v_pk_add_f32 v[246:247], v[246:247], 1.0 op_sel_hi:[1,0]
	v_pk_add_f32 v[248:249], v[248:249], 1.0 op_sel_hi:[1,0]
	v_pk_mul_f32 v[216:217], v[216:217], v[242:243]
	v_pk_mul_f32 v[218:219], v[218:219], v[244:245]
	v_pk_mul_f32 v[220:221], v[220:221], v[246:247]
	v_pk_mul_f32 v[222:223], v[222:223], v[248:249]
	v_pk_mul_f32 v[110:111], v[110:111], v[216:217]
	v_pk_mul_f32 v[112:113], v[112:113], v[218:219]
	v_pk_mul_f32 v[106:107], v[106:107], v[220:221]
	v_pk_mul_f32 v[108:109], v[108:109], v[222:223]
	v_lshlrev_b32_e32 v216, 16, v170
	v_and_b32_e32 v217, 0xffff0000, v170
	v_lshlrev_b32_e32 v218, 16, v171
	v_and_b32_e32 v219, 0xffff0000, v171
	v_lshlrev_b32_e32 v220, 16, v172
	v_and_b32_e32 v221, 0xffff0000, v172
	v_lshlrev_b32_e32 v222, 16, v173
	v_and_b32_e32 v223, 0xffff0000, v173
	v_pk_mul_f32 v[216:217], v[216:217], s[86:87] op_sel_hi:[1,0]
	v_pk_mul_f32 v[218:219], v[218:219], s[86:87] op_sel_hi:[1,0]
	v_pk_mul_f32 v[220:221], v[220:221], s[86:87] op_sel_hi:[1,0]
	v_pk_mul_f32 v[222:223], v[222:223], s[86:87] op_sel_hi:[1,0]
	v_exp_f32_e32 v216, v216
	v_exp_f32_e32 v217, v217
	v_exp_f32_e32 v218, v218
	v_exp_f32_e32 v219, v219
	v_exp_f32_e32 v220, v220
	v_exp_f32_e32 v221, v221
	v_exp_f32_e32 v222, v222
	v_exp_f32_e32 v223, v223
	v_pk_add_f32 v[216:217], v[216:217], 1.0 op_sel_hi:[1,0]
	v_pk_add_f32 v[218:219], v[218:219], 1.0 op_sel_hi:[1,0]
	v_pk_add_f32 v[220:221], v[220:221], 1.0 op_sel_hi:[1,0]
	v_pk_add_f32 v[222:223], v[222:223], 1.0 op_sel_hi:[1,0]
	v_rcp_f32_e32 v216, v216
	v_rcp_f32_e32 v217, v217
	v_rcp_f32_e32 v218, v218
	v_rcp_f32_e32 v219, v219
	v_rcp_f32_e32 v220, v220
	v_rcp_f32_e32 v221, v221
	v_rcp_f32_e32 v222, v222
	v_rcp_f32_e32 v223, v223
	v_lshlrev_b32_e32 v242, 16, v174
	v_and_b32_e32 v243, 0xffff0000, v174
	v_lshlrev_b32_e32 v244, 16, v175
	v_and_b32_e32 v245, 0xffff0000, v175
	v_lshlrev_b32_e32 v246, 16, v176
	v_and_b32_e32 v247, 0xffff0000, v176
	v_lshlrev_b32_e32 v248, 16, v177
	v_and_b32_e32 v249, 0xffff0000, v177
	v_pk_mul_f32 v[242:243], v[242:243], s[86:87] op_sel_hi:[1,0]
	v_pk_mul_f32 v[244:245], v[244:245], s[86:87] op_sel_hi:[1,0]
	v_pk_mul_f32 v[246:247], v[246:247], s[86:87] op_sel_hi:[1,0]
	v_pk_mul_f32 v[248:249], v[248:249], s[86:87] op_sel_hi:[1,0]
	v_exp_f32_e32 v242, v242
	v_exp_f32_e32 v243, v243
	v_exp_f32_e32 v244, v244
	v_exp_f32_e32 v245, v245
	v_exp_f32_e32 v246, v246
	v_exp_f32_e32 v247, v247
	v_exp_f32_e32 v248, v248
	v_exp_f32_e32 v249, v249
	v_pk_add_f32 v[242:243], v[242:243], 1.0 op_sel_hi:[1,0]
	v_pk_add_f32 v[244:245], v[244:245], 1.0 op_sel_hi:[1,0]
	v_pk_add_f32 v[246:247], v[246:247], 1.0 op_sel_hi:[1,0]
	v_pk_add_f32 v[248:249], v[248:249], 1.0 op_sel_hi:[1,0]
	v_pk_mul_f32 v[216:217], v[216:217], v[242:243]
	v_pk_mul_f32 v[218:219], v[218:219], v[244:245]
	v_pk_mul_f32 v[220:221], v[220:221], v[246:247]
	v_pk_mul_f32 v[222:223], v[222:223], v[248:249]
	v_pk_mul_f32 v[78:79], v[78:79], v[216:217]
	v_pk_mul_f32 v[80:81], v[80:81], v[218:219]
	v_pk_mul_f32 v[74:75], v[74:75], v[220:221]
	v_pk_mul_f32 v[76:77], v[76:77], v[222:223]
	s_add_u32 s28, s20, 0x410000
	s_addc_u32 s29, s21, 0
	global_load_dwordx4 v[162:165], v253, s[28:29]
	global_load_dwordx4 v[166:169], v254, s[28:29]
	global_load_dwordx4 v[170:173], v253, s[28:29] offset:256
	global_load_dwordx4 v[174:177], v254, s[28:29] offset:256
	s_waitcnt vmcnt(12)
	v_lshlrev_b32_e32 v216, 16, v178
	v_and_b32_e32 v217, 0xffff0000, v178
	v_lshlrev_b32_e32 v218, 16, v179
	v_and_b32_e32 v219, 0xffff0000, v179
	v_lshlrev_b32_e32 v220, 16, v180
	v_and_b32_e32 v221, 0xffff0000, v180
	v_lshlrev_b32_e32 v222, 16, v181
	v_and_b32_e32 v223, 0xffff0000, v181
	v_pk_mul_f32 v[216:217], v[216:217], s[86:87] op_sel_hi:[1,0]
	v_pk_mul_f32 v[218:219], v[218:219], s[86:87] op_sel_hi:[1,0]
	v_pk_mul_f32 v[220:221], v[220:221], s[86:87] op_sel_hi:[1,0]
	v_pk_mul_f32 v[222:223], v[222:223], s[86:87] op_sel_hi:[1,0]
	v_exp_f32_e32 v216, v216
	v_exp_f32_e32 v217, v217
	v_exp_f32_e32 v218, v218
	v_exp_f32_e32 v219, v219
	v_exp_f32_e32 v220, v220
	v_exp_f32_e32 v221, v221
	v_exp_f32_e32 v222, v222
	v_exp_f32_e32 v223, v223
	v_pk_add_f32 v[216:217], v[216:217], 1.0 op_sel_hi:[1,0]
	v_pk_add_f32 v[218:219], v[218:219], 1.0 op_sel_hi:[1,0]
	v_pk_add_f32 v[220:221], v[220:221], 1.0 op_sel_hi:[1,0]
	v_pk_add_f32 v[222:223], v[222:223], 1.0 op_sel_hi:[1,0]
	v_rcp_f32_e32 v216, v216
	v_rcp_f32_e32 v217, v217
	v_rcp_f32_e32 v218, v218
	v_rcp_f32_e32 v219, v219
	v_rcp_f32_e32 v220, v220
	v_rcp_f32_e32 v221, v221
	v_rcp_f32_e32 v222, v222
	v_rcp_f32_e32 v223, v223
	v_lshlrev_b32_e32 v242, 16, v182
	v_and_b32_e32 v243, 0xffff0000, v182
	v_lshlrev_b32_e32 v244, 16, v183
	v_and_b32_e32 v245, 0xffff0000, v183
	v_lshlrev_b32_e32 v246, 16, v184
	v_and_b32_e32 v247, 0xffff0000, v184
	v_lshlrev_b32_e32 v248, 16, v185
	v_and_b32_e32 v249, 0xffff0000, v185
	v_pk_mul_f32 v[242:243], v[242:243], s[86:87] op_sel_hi:[1,0]
	v_pk_mul_f32 v[244:245], v[244:245], s[86:87] op_sel_hi:[1,0]
	v_pk_mul_f32 v[246:247], v[246:247], s[86:87] op_sel_hi:[1,0]
	v_pk_mul_f32 v[248:249], v[248:249], s[86:87] op_sel_hi:[1,0]
	v_exp_f32_e32 v242, v242
	v_exp_f32_e32 v243, v243
	v_exp_f32_e32 v244, v244
	v_exp_f32_e32 v245, v245
	v_exp_f32_e32 v246, v246
	v_exp_f32_e32 v247, v247
	v_exp_f32_e32 v248, v248
	v_exp_f32_e32 v249, v249
	v_pk_add_f32 v[242:243], v[242:243], 1.0 op_sel_hi:[1,0]
	v_pk_add_f32 v[244:245], v[244:245], 1.0 op_sel_hi:[1,0]
	v_pk_add_f32 v[246:247], v[246:247], 1.0 op_sel_hi:[1,0]
	v_pk_add_f32 v[248:249], v[248:249], 1.0 op_sel_hi:[1,0]
	v_pk_mul_f32 v[216:217], v[216:217], v[242:243]
	v_pk_mul_f32 v[218:219], v[218:219], v[244:245]
	v_pk_mul_f32 v[220:221], v[220:221], v[246:247]
	v_pk_mul_f32 v[222:223], v[222:223], v[248:249]
	v_pk_mul_f32 v[102:103], v[102:103], v[216:217]
	v_pk_mul_f32 v[104:105], v[104:105], v[218:219]
	v_pk_mul_f32 v[98:99], v[98:99], v[220:221]
	v_pk_mul_f32 v[100:101], v[100:101], v[222:223]
	v_lshlrev_b32_e32 v216, 16, v186
	v_and_b32_e32 v217, 0xffff0000, v186
	v_lshlrev_b32_e32 v218, 16, v187
	v_and_b32_e32 v219, 0xffff0000, v187
	v_lshlrev_b32_e32 v220, 16, v188
	v_and_b32_e32 v221, 0xffff0000, v188
	v_lshlrev_b32_e32 v222, 16, v189
	v_and_b32_e32 v223, 0xffff0000, v189
	v_pk_mul_f32 v[216:217], v[216:217], s[86:87] op_sel_hi:[1,0]
	v_pk_mul_f32 v[218:219], v[218:219], s[86:87] op_sel_hi:[1,0]
	v_pk_mul_f32 v[220:221], v[220:221], s[86:87] op_sel_hi:[1,0]
	v_pk_mul_f32 v[222:223], v[222:223], s[86:87] op_sel_hi:[1,0]
	v_exp_f32_e32 v216, v216
	v_exp_f32_e32 v217, v217
	v_exp_f32_e32 v218, v218
	v_exp_f32_e32 v219, v219
	v_exp_f32_e32 v220, v220
	v_exp_f32_e32 v221, v221
	v_exp_f32_e32 v222, v222
	v_exp_f32_e32 v223, v223
	v_pk_add_f32 v[216:217], v[216:217], 1.0 op_sel_hi:[1,0]
	v_pk_add_f32 v[218:219], v[218:219], 1.0 op_sel_hi:[1,0]
	v_pk_add_f32 v[220:221], v[220:221], 1.0 op_sel_hi:[1,0]
	v_pk_add_f32 v[222:223], v[222:223], 1.0 op_sel_hi:[1,0]
	v_rcp_f32_e32 v216, v216
	v_rcp_f32_e32 v217, v217
	v_rcp_f32_e32 v218, v218
	v_rcp_f32_e32 v219, v219
	v_rcp_f32_e32 v220, v220
	v_rcp_f32_e32 v221, v221
	v_rcp_f32_e32 v222, v222
	v_rcp_f32_e32 v223, v223
	v_lshlrev_b32_e32 v242, 16, v190
	v_and_b32_e32 v243, 0xffff0000, v190
	v_lshlrev_b32_e32 v244, 16, v191
	v_and_b32_e32 v245, 0xffff0000, v191
	v_lshlrev_b32_e32 v246, 16, v192
	v_and_b32_e32 v247, 0xffff0000, v192
	v_lshlrev_b32_e32 v248, 16, v193
	v_and_b32_e32 v249, 0xffff0000, v193
	v_pk_mul_f32 v[242:243], v[242:243], s[86:87] op_sel_hi:[1,0]
	v_pk_mul_f32 v[244:245], v[244:245], s[86:87] op_sel_hi:[1,0]
	v_pk_mul_f32 v[246:247], v[246:247], s[86:87] op_sel_hi:[1,0]
	v_pk_mul_f32 v[248:249], v[248:249], s[86:87] op_sel_hi:[1,0]
	v_exp_f32_e32 v242, v242
	v_exp_f32_e32 v243, v243
	v_exp_f32_e32 v244, v244
	v_exp_f32_e32 v245, v245
	v_exp_f32_e32 v246, v246
	v_exp_f32_e32 v247, v247
	v_exp_f32_e32 v248, v248
	v_exp_f32_e32 v249, v249
	v_pk_add_f32 v[242:243], v[242:243], 1.0 op_sel_hi:[1,0]
	v_pk_add_f32 v[244:245], v[244:245], 1.0 op_sel_hi:[1,0]
	v_pk_add_f32 v[246:247], v[246:247], 1.0 op_sel_hi:[1,0]
	v_pk_add_f32 v[248:249], v[248:249], 1.0 op_sel_hi:[1,0]
	v_pk_mul_f32 v[216:217], v[216:217], v[242:243]
	v_pk_mul_f32 v[218:219], v[218:219], v[244:245]
	v_pk_mul_f32 v[220:221], v[220:221], v[246:247]
	v_pk_mul_f32 v[222:223], v[222:223], v[248:249]
	v_pk_mul_f32 v[70:71], v[70:71], v[216:217]
	v_pk_mul_f32 v[72:73], v[72:73], v[218:219]
	v_pk_mul_f32 v[66:67], v[66:67], v[220:221]
	v_pk_mul_f32 v[68:69], v[68:69], v[222:223]
	s_add_u32 s28, s20, 0x478000
	s_addc_u32 s29, s21, 0
	global_load_dwordx4 v[178:181], v253, s[28:29]
	global_load_dwordx4 v[182:185], v254, s[28:29]
	global_load_dwordx4 v[186:189], v253, s[28:29] offset:256
	global_load_dwordx4 v[190:193], v254, s[28:29] offset:256
	s_waitcnt vmcnt(12)
	v_lshlrev_b32_e32 v216, 16, v130
	v_and_b32_e32 v217, 0xffff0000, v130
	v_lshlrev_b32_e32 v218, 16, v131
	v_and_b32_e32 v219, 0xffff0000, v131
	v_lshlrev_b32_e32 v220, 16, v132
	v_and_b32_e32 v221, 0xffff0000, v132
	v_lshlrev_b32_e32 v222, 16, v133
	v_and_b32_e32 v223, 0xffff0000, v133
	v_pk_mul_f32 v[216:217], v[216:217], s[86:87] op_sel_hi:[1,0]
	v_pk_mul_f32 v[218:219], v[218:219], s[86:87] op_sel_hi:[1,0]
	v_pk_mul_f32 v[220:221], v[220:221], s[86:87] op_sel_hi:[1,0]
	v_pk_mul_f32 v[222:223], v[222:223], s[86:87] op_sel_hi:[1,0]
	v_exp_f32_e32 v216, v216
	v_exp_f32_e32 v217, v217
	v_exp_f32_e32 v218, v218
	v_exp_f32_e32 v219, v219
	v_exp_f32_e32 v220, v220
	v_exp_f32_e32 v221, v221
	v_exp_f32_e32 v222, v222
	v_exp_f32_e32 v223, v223
	v_pk_add_f32 v[216:217], v[216:217], 1.0 op_sel_hi:[1,0]
	v_pk_add_f32 v[218:219], v[218:219], 1.0 op_sel_hi:[1,0]
	v_pk_add_f32 v[220:221], v[220:221], 1.0 op_sel_hi:[1,0]
	v_pk_add_f32 v[222:223], v[222:223], 1.0 op_sel_hi:[1,0]
	v_rcp_f32_e32 v216, v216
	v_rcp_f32_e32 v217, v217
	v_rcp_f32_e32 v218, v218
	v_rcp_f32_e32 v219, v219
	v_rcp_f32_e32 v220, v220
	v_rcp_f32_e32 v221, v221
	v_rcp_f32_e32 v222, v222
	v_rcp_f32_e32 v223, v223
	v_lshlrev_b32_e32 v242, 16, v134
	v_and_b32_e32 v243, 0xffff0000, v134
	v_lshlrev_b32_e32 v244, 16, v135
	v_and_b32_e32 v245, 0xffff0000, v135
	v_lshlrev_b32_e32 v246, 16, v136
	v_and_b32_e32 v247, 0xffff0000, v136
	v_lshlrev_b32_e32 v248, 16, v137
	v_and_b32_e32 v249, 0xffff0000, v137
	v_pk_mul_f32 v[242:243], v[242:243], s[86:87] op_sel_hi:[1,0]
	v_pk_mul_f32 v[244:245], v[244:245], s[86:87] op_sel_hi:[1,0]
	v_pk_mul_f32 v[246:247], v[246:247], s[86:87] op_sel_hi:[1,0]
	v_pk_mul_f32 v[248:249], v[248:249], s[86:87] op_sel_hi:[1,0]
	v_exp_f32_e32 v242, v242
	v_exp_f32_e32 v243, v243
	v_exp_f32_e32 v244, v244
	v_exp_f32_e32 v245, v245
	v_exp_f32_e32 v246, v246
	v_exp_f32_e32 v247, v247
	v_exp_f32_e32 v248, v248
	v_exp_f32_e32 v249, v249
	v_pk_add_f32 v[242:243], v[242:243], 1.0 op_sel_hi:[1,0]
	v_pk_add_f32 v[244:245], v[244:245], 1.0 op_sel_hi:[1,0]
	v_pk_add_f32 v[246:247], v[246:247], 1.0 op_sel_hi:[1,0]
	v_pk_add_f32 v[248:249], v[248:249], 1.0 op_sel_hi:[1,0]
	v_pk_mul_f32 v[216:217], v[216:217], v[242:243]
	v_pk_mul_f32 v[218:219], v[218:219], v[244:245]
	v_pk_mul_f32 v[220:221], v[220:221], v[246:247]
	v_pk_mul_f32 v[222:223], v[222:223], v[248:249]
	v_pk_mul_f32 v[62:63], v[62:63], v[216:217]
	v_pk_mul_f32 v[64:65], v[64:65], v[218:219]
	v_pk_mul_f32 v[58:59], v[58:59], v[220:221]
	v_pk_mul_f32 v[60:61], v[60:61], v[222:223]
	v_lshlrev_b32_e32 v216, 16, v138
	v_and_b32_e32 v217, 0xffff0000, v138
	v_lshlrev_b32_e32 v218, 16, v139
	v_and_b32_e32 v219, 0xffff0000, v139
	v_lshlrev_b32_e32 v220, 16, v140
	v_and_b32_e32 v221, 0xffff0000, v140
	v_lshlrev_b32_e32 v222, 16, v141
	v_and_b32_e32 v223, 0xffff0000, v141
	v_pk_mul_f32 v[216:217], v[216:217], s[86:87] op_sel_hi:[1,0]
	v_pk_mul_f32 v[218:219], v[218:219], s[86:87] op_sel_hi:[1,0]
	v_pk_mul_f32 v[220:221], v[220:221], s[86:87] op_sel_hi:[1,0]
	v_pk_mul_f32 v[222:223], v[222:223], s[86:87] op_sel_hi:[1,0]
	v_exp_f32_e32 v216, v216
	v_exp_f32_e32 v217, v217
	v_exp_f32_e32 v218, v218
	v_exp_f32_e32 v219, v219
	v_exp_f32_e32 v220, v220
	v_exp_f32_e32 v221, v221
	v_exp_f32_e32 v222, v222
	v_exp_f32_e32 v223, v223
	v_pk_add_f32 v[216:217], v[216:217], 1.0 op_sel_hi:[1,0]
	v_pk_add_f32 v[218:219], v[218:219], 1.0 op_sel_hi:[1,0]
	v_pk_add_f32 v[220:221], v[220:221], 1.0 op_sel_hi:[1,0]
	v_pk_add_f32 v[222:223], v[222:223], 1.0 op_sel_hi:[1,0]
	v_rcp_f32_e32 v216, v216
	v_rcp_f32_e32 v217, v217
	v_rcp_f32_e32 v218, v218
	v_rcp_f32_e32 v219, v219
	v_rcp_f32_e32 v220, v220
	v_rcp_f32_e32 v221, v221
	v_rcp_f32_e32 v222, v222
	v_rcp_f32_e32 v223, v223
	v_lshlrev_b32_e32 v242, 16, v142
	v_and_b32_e32 v243, 0xffff0000, v142
	v_lshlrev_b32_e32 v244, 16, v143
	v_and_b32_e32 v245, 0xffff0000, v143
	v_lshlrev_b32_e32 v246, 16, v144
	v_and_b32_e32 v247, 0xffff0000, v144
	v_lshlrev_b32_e32 v248, 16, v145
	v_and_b32_e32 v249, 0xffff0000, v145
	v_pk_mul_f32 v[242:243], v[242:243], s[86:87] op_sel_hi:[1,0]
	v_pk_mul_f32 v[244:245], v[244:245], s[86:87] op_sel_hi:[1,0]
	v_pk_mul_f32 v[246:247], v[246:247], s[86:87] op_sel_hi:[1,0]
	v_pk_mul_f32 v[248:249], v[248:249], s[86:87] op_sel_hi:[1,0]
	v_exp_f32_e32 v242, v242
	v_exp_f32_e32 v243, v243
	v_exp_f32_e32 v244, v244
	v_exp_f32_e32 v245, v245
	v_exp_f32_e32 v246, v246
	v_exp_f32_e32 v247, v247
	v_exp_f32_e32 v248, v248
	v_exp_f32_e32 v249, v249
	v_pk_add_f32 v[242:243], v[242:243], 1.0 op_sel_hi:[1,0]
	v_pk_add_f32 v[244:245], v[244:245], 1.0 op_sel_hi:[1,0]
	v_pk_add_f32 v[246:247], v[246:247], 1.0 op_sel_hi:[1,0]
	v_pk_add_f32 v[248:249], v[248:249], 1.0 op_sel_hi:[1,0]
	v_pk_mul_f32 v[216:217], v[216:217], v[242:243]
	v_pk_mul_f32 v[218:219], v[218:219], v[244:245]
	v_pk_mul_f32 v[220:221], v[220:221], v[246:247]
	v_pk_mul_f32 v[222:223], v[222:223], v[248:249]
	v_pk_mul_f32 v[30:31], v[30:31], v[216:217]
	v_pk_mul_f32 v[32:33], v[32:33], v[218:219]
	v_pk_mul_f32 v[26:27], v[26:27], v[220:221]
	v_pk_mul_f32 v[28:29], v[28:29], v[222:223]
	s_waitcnt vmcnt(8)
	v_lshlrev_b32_e32 v216, 16, v146
	v_and_b32_e32 v217, 0xffff0000, v146
	v_lshlrev_b32_e32 v218, 16, v147
	v_and_b32_e32 v219, 0xffff0000, v147
	v_lshlrev_b32_e32 v220, 16, v148
	v_and_b32_e32 v221, 0xffff0000, v148
	v_lshlrev_b32_e32 v222, 16, v149
	v_and_b32_e32 v223, 0xffff0000, v149
	v_pk_mul_f32 v[216:217], v[216:217], s[86:87] op_sel_hi:[1,0]
	v_pk_mul_f32 v[218:219], v[218:219], s[86:87] op_sel_hi:[1,0]
	v_pk_mul_f32 v[220:221], v[220:221], s[86:87] op_sel_hi:[1,0]
	v_pk_mul_f32 v[222:223], v[222:223], s[86:87] op_sel_hi:[1,0]
	v_exp_f32_e32 v216, v216
	v_exp_f32_e32 v217, v217
	v_exp_f32_e32 v218, v218
	v_exp_f32_e32 v219, v219
	v_exp_f32_e32 v220, v220
	v_exp_f32_e32 v221, v221
	v_exp_f32_e32 v222, v222
	v_exp_f32_e32 v223, v223
	v_pk_add_f32 v[216:217], v[216:217], 1.0 op_sel_hi:[1,0]
	v_pk_add_f32 v[218:219], v[218:219], 1.0 op_sel_hi:[1,0]
	v_pk_add_f32 v[220:221], v[220:221], 1.0 op_sel_hi:[1,0]
	v_pk_add_f32 v[222:223], v[222:223], 1.0 op_sel_hi:[1,0]
	v_rcp_f32_e32 v216, v216
	v_rcp_f32_e32 v217, v217
	v_rcp_f32_e32 v218, v218
	v_rcp_f32_e32 v219, v219
	v_rcp_f32_e32 v220, v220
	v_rcp_f32_e32 v221, v221
	v_rcp_f32_e32 v222, v222
	v_rcp_f32_e32 v223, v223
	v_lshlrev_b32_e32 v242, 16, v150
	v_and_b32_e32 v243, 0xffff0000, v150
	v_lshlrev_b32_e32 v244, 16, v151
	v_and_b32_e32 v245, 0xffff0000, v151
	v_lshlrev_b32_e32 v246, 16, v152
	v_and_b32_e32 v247, 0xffff0000, v152
	v_lshlrev_b32_e32 v248, 16, v153
	v_and_b32_e32 v249, 0xffff0000, v153
	v_pk_mul_f32 v[242:243], v[242:243], s[86:87] op_sel_hi:[1,0]
	v_pk_mul_f32 v[244:245], v[244:245], s[86:87] op_sel_hi:[1,0]
	v_pk_mul_f32 v[246:247], v[246:247], s[86:87] op_sel_hi:[1,0]
	v_pk_mul_f32 v[248:249], v[248:249], s[86:87] op_sel_hi:[1,0]
	v_exp_f32_e32 v242, v242
	v_exp_f32_e32 v243, v243
	v_exp_f32_e32 v244, v244
	v_exp_f32_e32 v245, v245
	v_exp_f32_e32 v246, v246
	v_exp_f32_e32 v247, v247
	v_exp_f32_e32 v248, v248
	v_exp_f32_e32 v249, v249
	v_pk_add_f32 v[242:243], v[242:243], 1.0 op_sel_hi:[1,0]
	v_pk_add_f32 v[244:245], v[244:245], 1.0 op_sel_hi:[1,0]
	v_pk_add_f32 v[246:247], v[246:247], 1.0 op_sel_hi:[1,0]
	v_pk_add_f32 v[248:249], v[248:249], 1.0 op_sel_hi:[1,0]
	v_pk_mul_f32 v[216:217], v[216:217], v[242:243]
	v_pk_mul_f32 v[218:219], v[218:219], v[244:245]
	v_pk_mul_f32 v[220:221], v[220:221], v[246:247]
	v_pk_mul_f32 v[222:223], v[222:223], v[248:249]
	v_pk_mul_f32 v[54:55], v[54:55], v[216:217]
	v_pk_mul_f32 v[56:57], v[56:57], v[218:219]
	v_pk_mul_f32 v[50:51], v[50:51], v[220:221]
	v_pk_mul_f32 v[52:53], v[52:53], v[222:223]
	v_lshlrev_b32_e32 v216, 16, v154
	v_and_b32_e32 v217, 0xffff0000, v154
	v_lshlrev_b32_e32 v218, 16, v155
	v_and_b32_e32 v219, 0xffff0000, v155
	v_lshlrev_b32_e32 v220, 16, v156
	v_and_b32_e32 v221, 0xffff0000, v156
	v_lshlrev_b32_e32 v222, 16, v157
	v_and_b32_e32 v223, 0xffff0000, v157
	v_pk_mul_f32 v[216:217], v[216:217], s[86:87] op_sel_hi:[1,0]
	v_pk_mul_f32 v[218:219], v[218:219], s[86:87] op_sel_hi:[1,0]
	v_pk_mul_f32 v[220:221], v[220:221], s[86:87] op_sel_hi:[1,0]
	v_pk_mul_f32 v[222:223], v[222:223], s[86:87] op_sel_hi:[1,0]
	v_exp_f32_e32 v216, v216
	v_exp_f32_e32 v217, v217
	v_exp_f32_e32 v218, v218
	v_exp_f32_e32 v219, v219
	v_exp_f32_e32 v220, v220
	v_exp_f32_e32 v221, v221
	v_exp_f32_e32 v222, v222
	v_exp_f32_e32 v223, v223
	v_pk_add_f32 v[216:217], v[216:217], 1.0 op_sel_hi:[1,0]
	v_pk_add_f32 v[218:219], v[218:219], 1.0 op_sel_hi:[1,0]
	v_pk_add_f32 v[220:221], v[220:221], 1.0 op_sel_hi:[1,0]
	v_pk_add_f32 v[222:223], v[222:223], 1.0 op_sel_hi:[1,0]
	v_rcp_f32_e32 v216, v216
	v_rcp_f32_e32 v217, v217
	v_rcp_f32_e32 v218, v218
	v_rcp_f32_e32 v219, v219
	v_rcp_f32_e32 v220, v220
	v_rcp_f32_e32 v221, v221
	v_rcp_f32_e32 v222, v222
	v_rcp_f32_e32 v223, v223
	v_lshlrev_b32_e32 v242, 16, v158
	v_and_b32_e32 v243, 0xffff0000, v158
	v_lshlrev_b32_e32 v244, 16, v159
	v_and_b32_e32 v245, 0xffff0000, v159
	v_lshlrev_b32_e32 v246, 16, v160
	v_and_b32_e32 v247, 0xffff0000, v160
	v_lshlrev_b32_e32 v248, 16, v161
	v_and_b32_e32 v249, 0xffff0000, v161
	v_pk_mul_f32 v[242:243], v[242:243], s[86:87] op_sel_hi:[1,0]
	v_pk_mul_f32 v[244:245], v[244:245], s[86:87] op_sel_hi:[1,0]
	v_pk_mul_f32 v[246:247], v[246:247], s[86:87] op_sel_hi:[1,0]
	v_pk_mul_f32 v[248:249], v[248:249], s[86:87] op_sel_hi:[1,0]
	v_exp_f32_e32 v242, v242
	v_exp_f32_e32 v243, v243
	v_exp_f32_e32 v244, v244
	v_exp_f32_e32 v245, v245
	v_exp_f32_e32 v246, v246
	v_exp_f32_e32 v247, v247
	v_exp_f32_e32 v248, v248
	v_exp_f32_e32 v249, v249
	v_pk_add_f32 v[242:243], v[242:243], 1.0 op_sel_hi:[1,0]
	v_pk_add_f32 v[244:245], v[244:245], 1.0 op_sel_hi:[1,0]
	v_pk_add_f32 v[246:247], v[246:247], 1.0 op_sel_hi:[1,0]
	v_pk_add_f32 v[248:249], v[248:249], 1.0 op_sel_hi:[1,0]
	v_pk_mul_f32 v[216:217], v[216:217], v[242:243]
	v_pk_mul_f32 v[218:219], v[218:219], v[244:245]
	v_pk_mul_f32 v[220:221], v[220:221], v[246:247]
	v_pk_mul_f32 v[222:223], v[222:223], v[248:249]
	v_pk_mul_f32 v[22:23], v[22:23], v[216:217]
	v_pk_mul_f32 v[24:25], v[24:25], v[218:219]
	v_pk_mul_f32 v[18:19], v[18:19], v[220:221]
	v_pk_mul_f32 v[20:21], v[20:21], v[222:223]
	s_waitcnt vmcnt(4)
	v_lshlrev_b32_e32 v216, 16, v162
	v_and_b32_e32 v217, 0xffff0000, v162
	v_lshlrev_b32_e32 v218, 16, v163
	v_and_b32_e32 v219, 0xffff0000, v163
	v_lshlrev_b32_e32 v220, 16, v164
	v_and_b32_e32 v221, 0xffff0000, v164
	v_lshlrev_b32_e32 v222, 16, v165
	v_and_b32_e32 v223, 0xffff0000, v165
	v_pk_mul_f32 v[216:217], v[216:217], s[86:87] op_sel_hi:[1,0]
	v_pk_mul_f32 v[218:219], v[218:219], s[86:87] op_sel_hi:[1,0]
	v_pk_mul_f32 v[220:221], v[220:221], s[86:87] op_sel_hi:[1,0]
	v_pk_mul_f32 v[222:223], v[222:223], s[86:87] op_sel_hi:[1,0]
	v_exp_f32_e32 v216, v216
	v_exp_f32_e32 v217, v217
	v_exp_f32_e32 v218, v218
	v_exp_f32_e32 v219, v219
	v_exp_f32_e32 v220, v220
	v_exp_f32_e32 v221, v221
	v_exp_f32_e32 v222, v222
	v_exp_f32_e32 v223, v223
	v_pk_add_f32 v[216:217], v[216:217], 1.0 op_sel_hi:[1,0]
	v_pk_add_f32 v[218:219], v[218:219], 1.0 op_sel_hi:[1,0]
	v_pk_add_f32 v[220:221], v[220:221], 1.0 op_sel_hi:[1,0]
	v_pk_add_f32 v[222:223], v[222:223], 1.0 op_sel_hi:[1,0]
	v_rcp_f32_e32 v216, v216
	v_rcp_f32_e32 v217, v217
	v_rcp_f32_e32 v218, v218
	v_rcp_f32_e32 v219, v219
	v_rcp_f32_e32 v220, v220
	v_rcp_f32_e32 v221, v221
	v_rcp_f32_e32 v222, v222
	v_rcp_f32_e32 v223, v223
	v_lshlrev_b32_e32 v242, 16, v166
	v_and_b32_e32 v243, 0xffff0000, v166
	v_lshlrev_b32_e32 v244, 16, v167
	v_and_b32_e32 v245, 0xffff0000, v167
	v_lshlrev_b32_e32 v246, 16, v168
	v_and_b32_e32 v247, 0xffff0000, v168
	v_lshlrev_b32_e32 v248, 16, v169
	v_and_b32_e32 v249, 0xffff0000, v169
	v_pk_mul_f32 v[242:243], v[242:243], s[86:87] op_sel_hi:[1,0]
	v_pk_mul_f32 v[244:245], v[244:245], s[86:87] op_sel_hi:[1,0]
	v_pk_mul_f32 v[246:247], v[246:247], s[86:87] op_sel_hi:[1,0]
	v_pk_mul_f32 v[248:249], v[248:249], s[86:87] op_sel_hi:[1,0]
	v_exp_f32_e32 v242, v242
	v_exp_f32_e32 v243, v243
	v_exp_f32_e32 v244, v244
	v_exp_f32_e32 v245, v245
	v_exp_f32_e32 v246, v246
	v_exp_f32_e32 v247, v247
	v_exp_f32_e32 v248, v248
	v_exp_f32_e32 v249, v249
	v_pk_add_f32 v[242:243], v[242:243], 1.0 op_sel_hi:[1,0]
	v_pk_add_f32 v[244:245], v[244:245], 1.0 op_sel_hi:[1,0]
	v_pk_add_f32 v[246:247], v[246:247], 1.0 op_sel_hi:[1,0]
	v_pk_add_f32 v[248:249], v[248:249], 1.0 op_sel_hi:[1,0]
	v_pk_mul_f32 v[216:217], v[216:217], v[242:243]
	v_pk_mul_f32 v[218:219], v[218:219], v[244:245]
	v_pk_mul_f32 v[220:221], v[220:221], v[246:247]
	v_pk_mul_f32 v[222:223], v[222:223], v[248:249]
	v_pk_mul_f32 v[46:47], v[46:47], v[216:217]
	v_pk_mul_f32 v[48:49], v[48:49], v[218:219]
	v_pk_mul_f32 v[42:43], v[42:43], v[220:221]
	v_pk_mul_f32 v[44:45], v[44:45], v[222:223]
	v_lshlrev_b32_e32 v216, 16, v170
	v_and_b32_e32 v217, 0xffff0000, v170
	v_lshlrev_b32_e32 v218, 16, v171
	v_and_b32_e32 v219, 0xffff0000, v171
	v_lshlrev_b32_e32 v220, 16, v172
	v_and_b32_e32 v221, 0xffff0000, v172
	v_lshlrev_b32_e32 v222, 16, v173
	v_and_b32_e32 v223, 0xffff0000, v173
	v_pk_mul_f32 v[216:217], v[216:217], s[86:87] op_sel_hi:[1,0]
	v_pk_mul_f32 v[218:219], v[218:219], s[86:87] op_sel_hi:[1,0]
	v_pk_mul_f32 v[220:221], v[220:221], s[86:87] op_sel_hi:[1,0]
	v_pk_mul_f32 v[222:223], v[222:223], s[86:87] op_sel_hi:[1,0]
	v_exp_f32_e32 v216, v216
	v_exp_f32_e32 v217, v217
	v_exp_f32_e32 v218, v218
	v_exp_f32_e32 v219, v219
	v_exp_f32_e32 v220, v220
	v_exp_f32_e32 v221, v221
	v_exp_f32_e32 v222, v222
	v_exp_f32_e32 v223, v223
	v_pk_add_f32 v[216:217], v[216:217], 1.0 op_sel_hi:[1,0]
	v_pk_add_f32 v[218:219], v[218:219], 1.0 op_sel_hi:[1,0]
	v_pk_add_f32 v[220:221], v[220:221], 1.0 op_sel_hi:[1,0]
	v_pk_add_f32 v[222:223], v[222:223], 1.0 op_sel_hi:[1,0]
	v_rcp_f32_e32 v216, v216
	v_rcp_f32_e32 v217, v217
	v_rcp_f32_e32 v218, v218
	v_rcp_f32_e32 v219, v219
	v_rcp_f32_e32 v220, v220
	v_rcp_f32_e32 v221, v221
	v_rcp_f32_e32 v222, v222
	v_rcp_f32_e32 v223, v223
	v_lshlrev_b32_e32 v242, 16, v174
	v_and_b32_e32 v243, 0xffff0000, v174
	v_lshlrev_b32_e32 v244, 16, v175
	v_and_b32_e32 v245, 0xffff0000, v175
	v_lshlrev_b32_e32 v246, 16, v176
	v_and_b32_e32 v247, 0xffff0000, v176
	v_lshlrev_b32_e32 v248, 16, v177
	v_and_b32_e32 v249, 0xffff0000, v177
	v_pk_mul_f32 v[242:243], v[242:243], s[86:87] op_sel_hi:[1,0]
	v_pk_mul_f32 v[244:245], v[244:245], s[86:87] op_sel_hi:[1,0]
	v_pk_mul_f32 v[246:247], v[246:247], s[86:87] op_sel_hi:[1,0]
	v_pk_mul_f32 v[248:249], v[248:249], s[86:87] op_sel_hi:[1,0]
	v_exp_f32_e32 v242, v242
	v_exp_f32_e32 v243, v243
	v_exp_f32_e32 v244, v244
	v_exp_f32_e32 v245, v245
	v_exp_f32_e32 v246, v246
	v_exp_f32_e32 v247, v247
	v_exp_f32_e32 v248, v248
	v_exp_f32_e32 v249, v249
	v_pk_add_f32 v[242:243], v[242:243], 1.0 op_sel_hi:[1,0]
	v_pk_add_f32 v[244:245], v[244:245], 1.0 op_sel_hi:[1,0]
	v_pk_add_f32 v[246:247], v[246:247], 1.0 op_sel_hi:[1,0]
	v_pk_add_f32 v[248:249], v[248:249], 1.0 op_sel_hi:[1,0]
	v_pk_mul_f32 v[216:217], v[216:217], v[242:243]
	v_pk_mul_f32 v[218:219], v[218:219], v[244:245]
	v_pk_mul_f32 v[220:221], v[220:221], v[246:247]
	v_pk_mul_f32 v[222:223], v[222:223], v[248:249]
	v_pk_mul_f32 v[14:15], v[14:15], v[216:217]
	v_pk_mul_f32 v[16:17], v[16:17], v[218:219]
	v_pk_mul_f32 v[10:11], v[10:11], v[220:221]
	v_pk_mul_f32 v[12:13], v[12:13], v[222:223]
	s_waitcnt vmcnt(0)
	v_lshlrev_b32_e32 v216, 16, v178
	v_and_b32_e32 v217, 0xffff0000, v178
	v_lshlrev_b32_e32 v218, 16, v179
	v_and_b32_e32 v219, 0xffff0000, v179
	v_lshlrev_b32_e32 v220, 16, v180
	v_and_b32_e32 v221, 0xffff0000, v180
	v_lshlrev_b32_e32 v222, 16, v181
	v_and_b32_e32 v223, 0xffff0000, v181
	v_pk_mul_f32 v[216:217], v[216:217], s[86:87] op_sel_hi:[1,0]
	v_pk_mul_f32 v[218:219], v[218:219], s[86:87] op_sel_hi:[1,0]
	v_pk_mul_f32 v[220:221], v[220:221], s[86:87] op_sel_hi:[1,0]
	v_pk_mul_f32 v[222:223], v[222:223], s[86:87] op_sel_hi:[1,0]
	v_exp_f32_e32 v216, v216
	v_exp_f32_e32 v217, v217
	v_exp_f32_e32 v218, v218
	v_exp_f32_e32 v219, v219
	v_exp_f32_e32 v220, v220
	v_exp_f32_e32 v221, v221
	v_exp_f32_e32 v222, v222
	v_exp_f32_e32 v223, v223
	v_pk_add_f32 v[216:217], v[216:217], 1.0 op_sel_hi:[1,0]
	v_pk_add_f32 v[218:219], v[218:219], 1.0 op_sel_hi:[1,0]
	v_pk_add_f32 v[220:221], v[220:221], 1.0 op_sel_hi:[1,0]
	v_pk_add_f32 v[222:223], v[222:223], 1.0 op_sel_hi:[1,0]
	v_rcp_f32_e32 v216, v216
	v_rcp_f32_e32 v217, v217
	v_rcp_f32_e32 v218, v218
	v_rcp_f32_e32 v219, v219
	v_rcp_f32_e32 v220, v220
	v_rcp_f32_e32 v221, v221
	v_rcp_f32_e32 v222, v222
	v_rcp_f32_e32 v223, v223
	v_lshlrev_b32_e32 v242, 16, v182
	v_and_b32_e32 v243, 0xffff0000, v182
	v_lshlrev_b32_e32 v244, 16, v183
	v_and_b32_e32 v245, 0xffff0000, v183
	v_lshlrev_b32_e32 v246, 16, v184
	v_and_b32_e32 v247, 0xffff0000, v184
	v_lshlrev_b32_e32 v248, 16, v185
	v_and_b32_e32 v249, 0xffff0000, v185
	v_pk_mul_f32 v[242:243], v[242:243], s[86:87] op_sel_hi:[1,0]
	v_pk_mul_f32 v[244:245], v[244:245], s[86:87] op_sel_hi:[1,0]
	v_pk_mul_f32 v[246:247], v[246:247], s[86:87] op_sel_hi:[1,0]
	v_pk_mul_f32 v[248:249], v[248:249], s[86:87] op_sel_hi:[1,0]
	v_exp_f32_e32 v242, v242
	v_exp_f32_e32 v243, v243
	v_exp_f32_e32 v244, v244
	v_exp_f32_e32 v245, v245
	v_exp_f32_e32 v246, v246
	v_exp_f32_e32 v247, v247
	v_exp_f32_e32 v248, v248
	v_exp_f32_e32 v249, v249
	v_pk_add_f32 v[242:243], v[242:243], 1.0 op_sel_hi:[1,0]
	v_pk_add_f32 v[244:245], v[244:245], 1.0 op_sel_hi:[1,0]
	v_pk_add_f32 v[246:247], v[246:247], 1.0 op_sel_hi:[1,0]
	v_pk_add_f32 v[248:249], v[248:249], 1.0 op_sel_hi:[1,0]
	v_pk_mul_f32 v[216:217], v[216:217], v[242:243]
	v_pk_mul_f32 v[218:219], v[218:219], v[244:245]
	v_pk_mul_f32 v[220:221], v[220:221], v[246:247]
	v_pk_mul_f32 v[222:223], v[222:223], v[248:249]
	v_pk_mul_f32 v[38:39], v[38:39], v[216:217]
	v_pk_mul_f32 v[40:41], v[40:41], v[218:219]
	v_pk_mul_f32 v[34:35], v[34:35], v[220:221]
	v_pk_mul_f32 v[36:37], v[36:37], v[222:223]
	v_lshlrev_b32_e32 v216, 16, v186
	v_and_b32_e32 v217, 0xffff0000, v186
	v_lshlrev_b32_e32 v218, 16, v187
	v_and_b32_e32 v219, 0xffff0000, v187
	v_lshlrev_b32_e32 v220, 16, v188
	v_and_b32_e32 v221, 0xffff0000, v188
	v_lshlrev_b32_e32 v222, 16, v189
	v_and_b32_e32 v223, 0xffff0000, v189
	v_pk_mul_f32 v[216:217], v[216:217], s[86:87] op_sel_hi:[1,0]
	v_pk_mul_f32 v[218:219], v[218:219], s[86:87] op_sel_hi:[1,0]
	v_pk_mul_f32 v[220:221], v[220:221], s[86:87] op_sel_hi:[1,0]
	v_pk_mul_f32 v[222:223], v[222:223], s[86:87] op_sel_hi:[1,0]
	v_exp_f32_e32 v216, v216
	v_exp_f32_e32 v217, v217
	v_exp_f32_e32 v218, v218
	v_exp_f32_e32 v219, v219
	v_exp_f32_e32 v220, v220
	v_exp_f32_e32 v221, v221
	v_exp_f32_e32 v222, v222
	v_exp_f32_e32 v223, v223
	v_pk_add_f32 v[216:217], v[216:217], 1.0 op_sel_hi:[1,0]
	v_pk_add_f32 v[218:219], v[218:219], 1.0 op_sel_hi:[1,0]
	v_pk_add_f32 v[220:221], v[220:221], 1.0 op_sel_hi:[1,0]
	v_pk_add_f32 v[222:223], v[222:223], 1.0 op_sel_hi:[1,0]
	v_rcp_f32_e32 v216, v216
	v_rcp_f32_e32 v217, v217
	v_rcp_f32_e32 v218, v218
	v_rcp_f32_e32 v219, v219
	v_rcp_f32_e32 v220, v220
	v_rcp_f32_e32 v221, v221
	v_rcp_f32_e32 v222, v222
	v_rcp_f32_e32 v223, v223
	v_lshlrev_b32_e32 v242, 16, v190
	v_and_b32_e32 v243, 0xffff0000, v190
	v_lshlrev_b32_e32 v244, 16, v191
	v_and_b32_e32 v245, 0xffff0000, v191
	v_lshlrev_b32_e32 v246, 16, v192
	v_and_b32_e32 v247, 0xffff0000, v192
	v_lshlrev_b32_e32 v248, 16, v193
	v_and_b32_e32 v249, 0xffff0000, v193
	v_pk_mul_f32 v[242:243], v[242:243], s[86:87] op_sel_hi:[1,0]
	v_pk_mul_f32 v[244:245], v[244:245], s[86:87] op_sel_hi:[1,0]
	v_pk_mul_f32 v[246:247], v[246:247], s[86:87] op_sel_hi:[1,0]
	v_pk_mul_f32 v[248:249], v[248:249], s[86:87] op_sel_hi:[1,0]
	v_exp_f32_e32 v242, v242
	v_exp_f32_e32 v243, v243
	v_exp_f32_e32 v244, v244
	v_exp_f32_e32 v245, v245
	v_exp_f32_e32 v246, v246
	v_exp_f32_e32 v247, v247
	v_exp_f32_e32 v248, v248
	v_exp_f32_e32 v249, v249
	v_pk_add_f32 v[242:243], v[242:243], 1.0 op_sel_hi:[1,0]
	v_pk_add_f32 v[244:245], v[244:245], 1.0 op_sel_hi:[1,0]
	v_pk_add_f32 v[246:247], v[246:247], 1.0 op_sel_hi:[1,0]
	v_pk_add_f32 v[248:249], v[248:249], 1.0 op_sel_hi:[1,0]
	v_pk_mul_f32 v[216:217], v[216:217], v[242:243]
	v_pk_mul_f32 v[218:219], v[218:219], v[244:245]
	v_pk_mul_f32 v[220:221], v[220:221], v[246:247]
	v_pk_mul_f32 v[222:223], v[222:223], v[248:249]
	v_pk_mul_f32 v[6:7], v[6:7], v[216:217]
	v_pk_mul_f32 v[8:9], v[8:9], v[218:219]
	v_pk_mul_f32 v[2:3], v[2:3], v[220:221]
	v_pk_mul_f32 v[4:5], v[4:5], v[222:223]
	s_branch .Lem_done

.LBB0_504:
	v_add_u32_e32 v253, 0x10000, v163
	ds_read_b128 v[130:133], v253
	ds_read_b128 v[134:137], v253 offset:1024
	ds_read_b128 v[150:153], v253 offset:2048
	ds_read_b128 v[154:157], v253 offset:3072
	s_add_u32 s10, s52, 0xfff80080
	s_addc_u32 s11, s53, -1
	s_cmp_eq_u32 s29, 28
	s_cselect_b32 s11, s9, s11
	s_cselect_b32 s10, s8, s10
	s_cselect_b32 s55, s35, s7
	s_cselect_b32 s54, s34, s5
	s_add_i32 m0, s42, 0xc000
	ds_read_b128 v[158:161], v162
	ds_read_b128 v[166:169], v162 offset:1024
	ds_read_b128 v[170:173], v162 offset:2048
	ds_read_b128 v[174:177], v162 offset:3072
	ds_read_b128 v[178:181], v162 offset:4096
	ds_read_b128 v[182:185], v162 offset:5120
	ds_read_b128 v[186:189], v162 offset:6144
	ds_read_b128 v[190:193], v162 offset:7168
	global_load_lds_dwordx4 v146, s[52:53]
	s_add_i32 m0, s42, 0xe000
	s_nop 0
	global_load_lds_dwordx4 v148, s[52:53]
	s_waitcnt lgkmcnt(8)
	s_setprio 1
	s_barrier
	s_waitcnt lgkmcnt(0)
	v_mfma_f32_16x16x32_bf16 v[126:129], v[130:133], v[158:161], v[126:129]
	v_mfma_f32_16x16x32_bf16 v[122:125], v[150:153], v[158:161], v[122:125]
	v_mfma_f32_16x16x32_bf16 v[118:121], v[130:133], v[170:173], v[118:121]
	v_mfma_f32_16x16x32_bf16 v[114:117], v[150:153], v[170:173], v[114:117]
	v_mfma_f32_16x16x32_bf16 v[110:113], v[130:133], v[178:181], v[110:113]
	v_mfma_f32_16x16x32_bf16 v[106:109], v[150:153], v[178:181], v[106:109]
	v_mfma_f32_16x16x32_bf16 v[102:105], v[130:133], v[186:189], v[102:105]
	v_mfma_f32_16x16x32_bf16 v[98:101], v[150:153], v[186:189], v[98:101]
	v_mfma_f32_16x16x32_bf16 v[126:129], v[134:137], v[166:169], v[126:129]
	v_mfma_f32_16x16x32_bf16 v[122:125], v[154:157], v[166:169], v[122:125]
	v_mfma_f32_16x16x32_bf16 v[118:121], v[134:137], v[174:177], v[118:121]
	v_mfma_f32_16x16x32_bf16 v[114:117], v[154:157], v[174:177], v[114:117]
	v_mfma_f32_16x16x32_bf16 v[110:113], v[134:137], v[182:185], v[110:113]
	v_mfma_f32_16x16x32_bf16 v[106:109], v[154:157], v[182:185], v[106:109]
	v_mfma_f32_16x16x32_bf16 v[102:105], v[134:137], v[190:193], v[102:105]
	v_mfma_f32_16x16x32_bf16 v[98:101], v[154:157], v[190:193], v[98:101]
	s_barrier
	s_setprio 0
	s_mov_b32 m0, s41
	ds_read_b128 v[206:209], v253 offset:16384
	ds_read_b128 v[210:213], v253 offset:17408
	ds_read_b128 v[214:217], v253 offset:18432
	ds_read_b128 v[218:221], v253 offset:19456
	global_load_lds_dwordx4 v194, s[54:55]
	s_mov_b32 m0, s57
	s_nop 0
	global_load_lds_dwordx4 v138, s[54:55]
	s_setprio 1
	s_barrier
	s_waitcnt lgkmcnt(0)
	v_mfma_f32_16x16x32_bf16 v[62:65], v[206:209], v[158:161], v[62:65]
	v_mfma_f32_16x16x32_bf16 v[58:61], v[214:217], v[158:161], v[58:61]
	v_mfma_f32_16x16x32_bf16 v[54:57], v[206:209], v[170:173], v[54:57]
	v_mfma_f32_16x16x32_bf16 v[46:49], v[214:217], v[170:173], v[46:49]
	v_mfma_f32_16x16x32_bf16 v[50:53], v[206:209], v[178:181], v[50:53]
	v_mfma_f32_16x16x32_bf16 v[42:45], v[214:217], v[178:181], v[42:45]
	v_mfma_f32_16x16x32_bf16 v[38:41], v[206:209], v[186:189], v[38:41]
	v_mfma_f32_16x16x32_bf16 v[34:37], v[214:217], v[186:189], v[34:37]
	v_mfma_f32_16x16x32_bf16 v[62:65], v[210:213], v[166:169], v[62:65]
	v_mfma_f32_16x16x32_bf16 v[58:61], v[218:221], v[166:169], v[58:61]
	v_mfma_f32_16x16x32_bf16 v[54:57], v[210:213], v[174:177], v[54:57]
	v_mfma_f32_16x16x32_bf16 v[46:49], v[218:221], v[174:177], v[46:49]
	v_mfma_f32_16x16x32_bf16 v[50:53], v[210:213], v[182:185], v[50:53]
	v_mfma_f32_16x16x32_bf16 v[42:45], v[218:221], v[182:185], v[42:45]
	v_mfma_f32_16x16x32_bf16 v[38:41], v[210:213], v[190:193], v[38:41]
	s_mov_b32 m0, s42
	v_mfma_f32_16x16x32_bf16 v[34:37], v[218:221], v[190:193], v[34:37]
	s_barrier
	s_setprio 0
	ds_read_b128 v[158:161], v162 offset:16384
	ds_read_b128 v[166:169], v162 offset:17408
	ds_read_b128 v[170:173], v162 offset:18432
	ds_read_b128 v[174:177], v162 offset:19456
	ds_read_b128 v[178:181], v162 offset:20480
	ds_read_b128 v[182:185], v162 offset:21504
	ds_read_b128 v[186:189], v162 offset:22528
	ds_read_b128 v[190:193], v162 offset:23552
	global_load_lds_dwordx4 v142, s[10:11]
	s_mov_b32 m0, s58
	s_nop 0
	global_load_lds_dwordx4 v140, s[10:11]
	s_setprio 1
	s_barrier
	s_waitcnt lgkmcnt(0)
	v_mfma_f32_16x16x32_bf16 v[94:97], v[130:133], v[158:161], v[94:97]
	v_mfma_f32_16x16x32_bf16 v[90:93], v[150:153], v[158:161], v[90:93]
	v_mfma_f32_16x16x32_bf16 v[86:89], v[130:133], v[170:173], v[86:89]
	v_mfma_f32_16x16x32_bf16 v[82:85], v[150:153], v[170:173], v[82:85]
	v_mfma_f32_16x16x32_bf16 v[78:81], v[130:133], v[178:181], v[78:81]
	v_mfma_f32_16x16x32_bf16 v[74:77], v[150:153], v[178:181], v[74:77]
	v_mfma_f32_16x16x32_bf16 v[70:73], v[130:133], v[186:189], v[70:73]
	v_mfma_f32_16x16x32_bf16 v[66:69], v[150:153], v[186:189], v[66:69]
	v_mfma_f32_16x16x32_bf16 v[94:97], v[134:137], v[166:169], v[94:97]
	v_mfma_f32_16x16x32_bf16 v[90:93], v[154:157], v[166:169], v[90:93]
	v_mfma_f32_16x16x32_bf16 v[86:89], v[134:137], v[174:177], v[86:89]
	v_mfma_f32_16x16x32_bf16 v[82:85], v[154:157], v[174:177], v[82:85]
	v_mfma_f32_16x16x32_bf16 v[78:81], v[134:137], v[182:185], v[78:81]
	v_mfma_f32_16x16x32_bf16 v[74:77], v[154:157], v[182:185], v[74:77]
	v_mfma_f32_16x16x32_bf16 v[70:73], v[134:137], v[190:193], v[70:73]
	v_mfma_f32_16x16x32_bf16 v[66:69], v[154:157], v[190:193], v[66:69]
	s_barrier
	s_setprio 0
	s_add_u32 s86, s54, 0x80000
	s_addc_u32 s87, s55, 0
	s_mov_b32 m0, s59
	s_nop 0
	global_load_lds_dwordx4 v194, s[86:87]
	s_mov_b32 m0, s60
	s_nop 0
	global_load_lds_dwordx4 v138, s[86:87]
	s_waitcnt vmcnt(6)
	s_setprio 1
	s_barrier
	v_mfma_f32_16x16x32_bf16 v[30:33], v[206:209], v[158:161], v[30:33]
	v_mfma_f32_16x16x32_bf16 v[18:21], v[214:217], v[158:161], v[18:21]
	v_mfma_f32_16x16x32_bf16 v[26:29], v[206:209], v[170:173], v[26:29]
	v_mfma_f32_16x16x32_bf16 v[14:17], v[214:217], v[170:173], v[14:17]
	v_mfma_f32_16x16x32_bf16 v[22:25], v[206:209], v[178:181], v[22:25]
	v_mfma_f32_16x16x32_bf16 v[6:9], v[214:217], v[178:181], v[6:9]
	v_mfma_f32_16x16x32_bf16 v[10:13], v[206:209], v[186:189], v[10:13]
	v_mfma_f32_16x16x32_bf16 v[2:5], v[214:217], v[186:189], v[2:5]
	v_mfma_f32_16x16x32_bf16 v[30:33], v[210:213], v[166:169], v[30:33]
	v_mfma_f32_16x16x32_bf16 v[18:21], v[218:221], v[166:169], v[18:21]
	v_mfma_f32_16x16x32_bf16 v[26:29], v[210:213], v[174:177], v[26:29]
	v_mfma_f32_16x16x32_bf16 v[14:17], v[218:221], v[174:177], v[14:17]
	v_mfma_f32_16x16x32_bf16 v[22:25], v[210:213], v[182:185], v[22:25]
	v_mfma_f32_16x16x32_bf16 v[6:9], v[218:221], v[182:185], v[6:9]
	v_mfma_f32_16x16x32_bf16 v[10:13], v[210:213], v[190:193], v[10:13]
	v_mfma_f32_16x16x32_bf16 v[2:5], v[218:221], v[190:193], v[2:5]
	s_barrier
	s_setprio 0
	ds_read_b128 v[130:133], v253 offset:32768
	ds_read_b128 v[134:137], v253 offset:33792
	ds_read_b128 v[150:153], v253 offset:34816
	ds_read_b128 v[154:157], v253 offset:35840
	s_add_u32 s10, s10, 0x80000
	s_addc_u32 s11, s11, 0
	s_mov_b32 m0, s61
	ds_read_b128 v[158:161], v162 offset:32768
	ds_read_b128 v[166:169], v162 offset:33792
	ds_read_b128 v[170:173], v162 offset:34816
	ds_read_b128 v[174:177], v162 offset:35840
	ds_read_b128 v[178:181], v162 offset:36864
	ds_read_b128 v[182:185], v162 offset:37888
	ds_read_b128 v[186:189], v162 offset:38912
	ds_read_b128 v[190:193], v162 offset:39936
	global_load_lds_dwordx4 v142, s[10:11]
	s_mov_b32 m0, s62
	s_nop 0
	global_load_lds_dwordx4 v140, s[10:11]
	s_waitcnt lgkmcnt(8)
	s_setprio 1
	s_barrier
	s_waitcnt lgkmcnt(0)
	v_mfma_f32_16x16x32_bf16 v[126:129], v[130:133], v[158:161], v[126:129]
	v_mfma_f32_16x16x32_bf16 v[122:125], v[150:153], v[158:161], v[122:125]
	v_mfma_f32_16x16x32_bf16 v[118:121], v[130:133], v[170:173], v[118:121]
	v_mfma_f32_16x16x32_bf16 v[114:117], v[150:153], v[170:173], v[114:117]
	v_mfma_f32_16x16x32_bf16 v[110:113], v[130:133], v[178:181], v[110:113]
	v_mfma_f32_16x16x32_bf16 v[106:109], v[150:153], v[178:181], v[106:109]
	v_mfma_f32_16x16x32_bf16 v[102:105], v[130:133], v[186:189], v[102:105]
	v_mfma_f32_16x16x32_bf16 v[98:101], v[150:153], v[186:189], v[98:101]
	v_mfma_f32_16x16x32_bf16 v[126:129], v[134:137], v[166:169], v[126:129]
	v_mfma_f32_16x16x32_bf16 v[122:125], v[154:157], v[166:169], v[122:125]
	v_mfma_f32_16x16x32_bf16 v[118:121], v[134:137], v[174:177], v[118:121]
	v_mfma_f32_16x16x32_bf16 v[114:117], v[154:157], v[174:177], v[114:117]
	v_mfma_f32_16x16x32_bf16 v[110:113], v[134:137], v[182:185], v[110:113]
	v_mfma_f32_16x16x32_bf16 v[106:109], v[154:157], v[182:185], v[106:109]
	v_mfma_f32_16x16x32_bf16 v[102:105], v[134:137], v[190:193], v[102:105]
	v_mfma_f32_16x16x32_bf16 v[98:101], v[154:157], v[190:193], v[98:101]
	s_barrier
	s_setprio 0
	s_mov_b32 m0, s70
	ds_read_b128 v[206:209], v253 offset:49152
	ds_read_b128 v[210:213], v253 offset:50176
	ds_read_b128 v[214:217], v253 offset:51200
	ds_read_b128 v[218:221], v253 offset:52224
	s_add_u32 s98, s54, 0x80
	s_addc_u32 s99, s55, 0
	global_load_lds_dwordx4 v194, s[98:99]
	s_mov_b32 m0, s71
	s_nop 0
	global_load_lds_dwordx4 v138, s[98:99]
	s_setprio 1
	s_barrier
	s_waitcnt lgkmcnt(0)
	v_mfma_f32_16x16x32_bf16 v[62:65], v[206:209], v[158:161], v[62:65]
	v_mfma_f32_16x16x32_bf16 v[58:61], v[214:217], v[158:161], v[58:61]
	v_mfma_f32_16x16x32_bf16 v[54:57], v[206:209], v[170:173], v[54:57]
	v_mfma_f32_16x16x32_bf16 v[46:49], v[214:217], v[170:173], v[46:49]
	v_mfma_f32_16x16x32_bf16 v[50:53], v[206:209], v[178:181], v[50:53]
	v_mfma_f32_16x16x32_bf16 v[42:45], v[214:217], v[178:181], v[42:45]
	v_mfma_f32_16x16x32_bf16 v[38:41], v[206:209], v[186:189], v[38:41]
	v_mfma_f32_16x16x32_bf16 v[34:37], v[214:217], v[186:189], v[34:37]
	v_mfma_f32_16x16x32_bf16 v[62:65], v[210:213], v[166:169], v[62:65]
	v_mfma_f32_16x16x32_bf16 v[58:61], v[218:221], v[166:169], v[58:61]
	v_mfma_f32_16x16x32_bf16 v[54:57], v[210:213], v[174:177], v[54:57]
	v_mfma_f32_16x16x32_bf16 v[46:49], v[218:221], v[174:177], v[46:49]
	v_mfma_f32_16x16x32_bf16 v[50:53], v[210:213], v[182:185], v[50:53]
	v_mfma_f32_16x16x32_bf16 v[42:45], v[218:221], v[182:185], v[42:45]
	v_mfma_f32_16x16x32_bf16 v[38:41], v[210:213], v[190:193], v[38:41]
	s_mov_b32 m0, s78
	v_mfma_f32_16x16x32_bf16 v[34:37], v[218:221], v[190:193], v[34:37]
	s_barrier
	s_setprio 0
	ds_read_b128 v[158:161], v162 offset:49152
	ds_read_b128 v[166:169], v162 offset:50176
	ds_read_b128 v[170:173], v162 offset:51200
	ds_read_b128 v[174:177], v162 offset:52224
	ds_read_b128 v[178:181], v162 offset:53248
	ds_read_b128 v[182:185], v162 offset:54272
	ds_read_b128 v[186:189], v162 offset:55296
	ds_read_b128 v[190:193], v162 offset:56320
	s_add_u32 s100, s10, 0xfff80080
	s_addc_u32 s101, s11, -1
	global_load_lds_dwordx4 v142, s[100:101]
	s_mov_b32 m0, s79
	s_nop 0
	global_load_lds_dwordx4 v140, s[100:101]
	s_setprio 1
	s_barrier
	s_waitcnt lgkmcnt(0)
	v_mfma_f32_16x16x32_bf16 v[94:97], v[130:133], v[158:161], v[94:97]
	v_mfma_f32_16x16x32_bf16 v[90:93], v[150:153], v[158:161], v[90:93]
	v_mfma_f32_16x16x32_bf16 v[86:89], v[130:133], v[170:173], v[86:89]
	v_mfma_f32_16x16x32_bf16 v[82:85], v[150:153], v[170:173], v[82:85]
	v_mfma_f32_16x16x32_bf16 v[78:81], v[130:133], v[178:181], v[78:81]
	v_mfma_f32_16x16x32_bf16 v[74:77], v[150:153], v[178:181], v[74:77]
	v_mfma_f32_16x16x32_bf16 v[70:73], v[130:133], v[186:189], v[70:73]
	v_mfma_f32_16x16x32_bf16 v[66:69], v[150:153], v[186:189], v[66:69]
	v_mfma_f32_16x16x32_bf16 v[94:97], v[134:137], v[166:169], v[94:97]
	v_mfma_f32_16x16x32_bf16 v[90:93], v[154:157], v[166:169], v[90:93]
	v_mfma_f32_16x16x32_bf16 v[86:89], v[134:137], v[174:177], v[86:89]
	v_mfma_f32_16x16x32_bf16 v[82:85], v[154:157], v[174:177], v[82:85]
	v_mfma_f32_16x16x32_bf16 v[78:81], v[134:137], v[182:185], v[78:81]
	v_mfma_f32_16x16x32_bf16 v[74:77], v[154:157], v[182:185], v[74:77]
	v_mfma_f32_16x16x32_bf16 v[70:73], v[134:137], v[190:193], v[70:73]
	v_mfma_f32_16x16x32_bf16 v[66:69], v[154:157], v[190:193], v[66:69]
	s_barrier
	s_setprio 0
	s_add_u32 s10, s54, 0x80080
	s_addc_u32 s11, s55, 0
	s_mov_b32 m0, s80
	s_nop 0
	global_load_lds_dwordx4 v194, s[10:11]
	s_mov_b32 m0, s81
	s_nop 0
	global_load_lds_dwordx4 v138, s[10:11]
	s_waitcnt vmcnt(6)
	s_setprio 1
	s_barrier
	v_mfma_f32_16x16x32_bf16 v[30:33], v[206:209], v[158:161], v[30:33]
	v_mfma_f32_16x16x32_bf16 v[18:21], v[214:217], v[158:161], v[18:21]
	v_mfma_f32_16x16x32_bf16 v[26:29], v[206:209], v[170:173], v[26:29]
	v_mfma_f32_16x16x32_bf16 v[14:17], v[214:217], v[170:173], v[14:17]
	v_mfma_f32_16x16x32_bf16 v[22:25], v[206:209], v[178:181], v[22:25]
	v_mfma_f32_16x16x32_bf16 v[6:9], v[214:217], v[178:181], v[6:9]
	v_mfma_f32_16x16x32_bf16 v[10:13], v[206:209], v[186:189], v[10:13]
	v_mfma_f32_16x16x32_bf16 v[2:5], v[214:217], v[186:189], v[2:5]
	v_mfma_f32_16x16x32_bf16 v[30:33], v[210:213], v[166:169], v[30:33]
	v_mfma_f32_16x16x32_bf16 v[18:21], v[218:221], v[166:169], v[18:21]
	v_mfma_f32_16x16x32_bf16 v[26:29], v[210:213], v[174:177], v[26:29]
	v_mfma_f32_16x16x32_bf16 v[14:17], v[218:221], v[174:177], v[14:17]
	v_mfma_f32_16x16x32_bf16 v[22:25], v[210:213], v[182:185], v[22:25]
	v_mfma_f32_16x16x32_bf16 v[6:9], v[218:221], v[182:185], v[6:9]
	v_mfma_f32_16x16x32_bf16 v[10:13], v[210:213], v[190:193], v[10:13]
	v_mfma_f32_16x16x32_bf16 v[2:5], v[218:221], v[190:193], v[2:5]
	s_setprio 0
	s_add_i32 s29, s29, 2
	s_add_u32 s52, s52, 0x100
	s_addc_u32 s53, s53, 0
	s_add_u32 s5, s5, 0x100
	s_addc_u32 s7, s7, 0
	s_cmp_gt_u32 s29, 29
	s_barrier
	s_cbranch_scc0 .LBB0_504
	v_readlane_b32 s10, v250, 21
	s_cmp_gt_i32 s40, 63
	v_readlane_b32 s11, v250, 22
	s_mov_b64 s[20:21], s[48:49]
	s_cselect_b32 s11, s21, s11
	s_cselect_b32 s10, s20, s10
	v_readlane_b32 s20, v252, 0
	v_readlane_b32 s26, v252, 6
	v_readlane_b32 s27, v252, 7
	s_cselect_b32 s53, s3, s27
	s_cselect_b32 s52, s2, s26
	s_sub_i32 s5, s40, 64
	s_cmp_gt_i32 s40, 63
	s_cselect_b32 s54, s5, s40
	s_lshr_b32 s5, s40, 3
	s_cmp_gt_i32 s40, 63
	s_mulk_i32 s5, 0x1800
	v_lshl_or_b32 v130, s28, 8, v164
	s_cselect_b32 s28, 0xc000, s5
	s_ashr_i32 s29, s28, 31
	s_lshl_b64 s[28:29], s[28:29], 2
	s_add_u32 s28, s63, s28
	v_ashrrev_i32_e32 v131, 31, v130
	s_addc_u32 s29, s67, s29
	v_lshlrev_b64 v[130:131], 2, v[130:131]
	v_lshl_add_u64 v[132:133], s[28:29], 0, v[130:131]
	s_mov_b64 s[28:29], 0x6484000
	s_ashr_i32 s55, s54, 31
	v_lshl_add_u64 v[154:155], v[132:133], 0, s[28:29]
	s_lshl_b64 s[28:29], s[54:55], 19
	v_lshl_add_u64 v[134:135], s[28:29], 0, v[144:145]
	v_lshlrev_b64 v[134:135], 2, v[134:135]
	v_lshl_add_u64 v[136:137], s[10:11], 0, v[134:135]
	v_lshl_add_u64 v[134:135], s[52:53], 0, v[134:135]
	s_mov_b32 s5, 0x6484000
	v_lshl_add_u64 v[150:151], v[136:137], 0, v[130:131]
	v_lshl_add_u64 v[152:153], v[134:135], 0, v[130:131]
	v_add_co_u32_e32 v130, vcc, s5, v132
	s_mov_b64 s[10:11], 0x20000
	s_nop 0
	v_addc_co_u32_e32 v131, vcc, 0, v133, vcc
	v_add_co_u32_e32 v156, vcc, s13, v150
	global_load_dwordx4 v[134:137], v[130:131], off
	s_nop 0
	global_load_dwordx4 v[130:133], v[154:155], off offset:16
	global_load_dwordx4 v[166:169], v[150:151], off offset:16
	global_load_dwordx4 v[170:173], v[150:151], off
	v_lshl_add_u64 v[158:159], v[150:151], 0, s[10:11]
	v_addc_co_u32_e32 v157, vcc, 0, v151, vcc
	s_mov_b32 s5, 0x40000
	global_load_dwordx4 v[174:177], v[156:157], off
	global_load_dwordx4 v[178:181], v[158:159], off offset:16
	s_mov_b64 s[10:11], 0x40000
	v_add_co_u32_e32 v158, vcc, s5, v150
	v_lshl_add_u64 v[160:161], v[150:151], 0, s[10:11]
	s_nop 0
	v_addc_co_u32_e32 v159, vcc, 0, v151, vcc
	s_mov_b32 s7, 0x60000
	global_load_dwordx4 v[182:185], v[158:159], off
	global_load_dwordx4 v[186:189], v[160:161], off offset:16
	s_mov_b64 s[10:11], 0x60000
	v_add_co_u32_e32 v160, vcc, s7, v150
	v_lshl_add_u64 v[206:207], v[150:151], 0, s[10:11]
	s_nop 0
	v_addc_co_u32_e32 v161, vcc, 0, v151, vcc
	global_load_dwordx4 v[190:193], v[160:161], off
	s_nop 0
	global_load_dwordx4 v[206:209], v[206:207], off offset:16
	v_readlane_b32 s21, v252, 1
	v_readlane_b32 s22, v252, 2
	v_readlane_b32 s23, v252, 3
	v_readlane_b32 s24, v252, 4
	v_readlane_b32 s25, v252, 5
	s_waitcnt vmcnt(0)
	v_pk_fma_f32 v[124:125], v[124:125], v[132:133], v[168:169]
	v_pk_fma_f32 v[122:123], v[122:123], v[130:131], v[166:167]
	global_store_dwordx4 v[152:153], v[122:125], off offset:16
	v_pk_fma_f32 v[128:129], v[128:129], v[136:137], v[172:173]
	v_pk_fma_f32 v[126:127], v[126:127], v[134:135], v[170:171]
	v_pk_fma_f32 v[122:123], v[120:121], v[136:137], v[176:177]
	v_pk_fma_f32 v[120:121], v[118:119], v[134:135], v[174:175]
	v_add_co_u32_e32 v118, vcc, s13, v152
	v_pk_fma_f32 v[116:117], v[116:117], v[132:133], v[180:181]
	s_nop 0
	v_addc_co_u32_e32 v119, vcc, 0, v153, vcc
	v_pk_fma_f32 v[114:115], v[114:115], v[130:131], v[178:179]
	global_store_dwordx4 v[118:119], v[114:117], off offset:16
	v_pk_fma_f32 v[108:109], v[108:109], v[132:133], v[188:189]
	v_pk_fma_f32 v[106:107], v[106:107], v[130:131], v[186:187]
	v_pk_fma_f32 v[114:115], v[112:113], v[136:137], v[184:185]
	v_pk_fma_f32 v[112:113], v[110:111], v[134:135], v[182:183]
	v_add_co_u32_e32 v110, vcc, s5, v152
	global_store_dwordx4 v[152:153], v[126:129], off
	s_nop 0
	v_addc_co_u32_e32 v111, vcc, 0, v153, vcc
	global_store_dwordx4 v[110:111], v[106:109], off offset:16
	v_pk_fma_f32 v[100:101], v[100:101], v[132:133], v[208:209]
	v_pk_fma_f32 v[98:99], v[98:99], v[130:131], v[206:207]
	v_pk_fma_f32 v[106:107], v[104:105], v[136:137], v[192:193]
	v_pk_fma_f32 v[104:105], v[102:103], v[134:135], v[190:191]
	v_add_co_u32_e32 v102, vcc, s7, v152
	global_store_dwordx4 v[118:119], v[120:123], off
	s_nop 0
	v_addc_co_u32_e32 v103, vcc, 0, v153, vcc
	global_store_dwordx4 v[110:111], v[112:115], off
	global_store_dwordx4 v[102:103], v[104:107], off
	global_store_dwordx4 v[102:103], v[98:101], off offset:16
	s_mov_b32 s5, 0x100000
	s_mov_b64 s[10:11], 0x100000
	v_add_co_u32_e32 v98, vcc, s5, v150
	v_lshl_add_u64 v[100:101], v[150:151], 0, s[10:11]
	s_nop 0
	v_addc_co_u32_e32 v99, vcc, 0, v151, vcc
	global_load_dwordx4 v[112:115], v[98:99], off
	global_load_dwordx4 v[120:123], v[100:101], off offset:16
	s_mov_b64 s[10:11], 0x120000
	v_add_co_u32_e32 v100, vcc, s45, v150
	v_lshl_add_u64 v[104:105], v[150:151], 0, s[10:11]
	s_nop 0
	v_addc_co_u32_e32 v101, vcc, 0, v151, vcc
	s_mov_b64 s[10:11], 0x140000
	s_mov_b32 s7, 0x140000
	global_load_dwordx4 v[124:127], v[100:101], off
	global_load_dwordx4 v[166:169], v[104:105], off offset:16
	v_lshl_add_u64 v[106:107], v[150:151], 0, s[10:11]
	v_add_co_u32_e32 v104, vcc, s7, v150
	s_mov_b64 s[10:11], 0x160000
	s_nop 0
	v_addc_co_u32_e32 v105, vcc, 0, v151, vcc
	v_lshl_add_u64 v[108:109], v[150:151], 0, s[10:11]
	s_mov_b32 s10, 0x160000
	global_load_dwordx4 v[170:173], v[104:105], off
	global_load_dwordx4 v[174:177], v[106:107], off offset:16
	v_add_co_u32_e32 v106, vcc, s10, v150
	s_waitcnt vmcnt(0)
	v_pk_fma_f32 v[112:113], v[94:95], v[134:135], v[112:113]
	v_addc_co_u32_e32 v107, vcc, 0, v151, vcc
	global_load_dwordx4 v[178:181], v[106:107], off
	global_load_dwordx4 v[182:185], v[108:109], off offset:16
	v_add_co_u32_e32 v94, vcc, s5, v152
	v_pk_fma_f32 v[92:93], v[92:93], v[132:133], v[122:123]
	s_nop 0
	v_addc_co_u32_e32 v95, vcc, 0, v153, vcc
	v_pk_fma_f32 v[90:91], v[90:91], v[130:131], v[120:121]
	global_store_dwordx4 v[94:95], v[90:93], off offset:16
	v_pk_fma_f32 v[84:85], v[84:85], v[132:133], v[168:169]
	v_pk_fma_f32 v[82:83], v[82:83], v[130:131], v[166:167]
	v_pk_fma_f32 v[90:91], v[88:89], v[136:137], v[126:127]
	v_pk_fma_f32 v[88:89], v[86:87], v[134:135], v[124:125]
	v_add_co_u32_e32 v86, vcc, s45, v152
	v_pk_fma_f32 v[114:115], v[96:97], v[136:137], v[114:115]
	s_nop 0
	v_addc_co_u32_e32 v87, vcc, 0, v153, vcc
	global_store_dwordx4 v[86:87], v[82:85], off offset:16
	v_pk_fma_f32 v[76:77], v[76:77], v[132:133], v[176:177]
	v_pk_fma_f32 v[74:75], v[74:75], v[130:131], v[174:175]
	v_pk_fma_f32 v[82:83], v[80:81], v[136:137], v[172:173]
	v_pk_fma_f32 v[80:81], v[78:79], v[134:135], v[170:171]
	v_add_co_u32_e32 v78, vcc, s7, v152
	global_store_dwordx4 v[94:95], v[112:115], off
	s_nop 0
	v_addc_co_u32_e32 v79, vcc, 0, v153, vcc
	global_store_dwordx4 v[78:79], v[74:77], off offset:16
	global_store_dwordx4 v[86:87], v[88:91], off
	global_store_dwordx4 v[78:79], v[80:83], off
	v_add_co_u32_e32 v74, vcc, s10, v152
	s_waitcnt vmcnt(0)
	v_pk_fma_f32 v[72:73], v[72:73], v[136:137], v[180:181]
	v_pk_fma_f32 v[70:71], v[70:71], v[134:135], v[178:179]
	v_addc_co_u32_e32 v75, vcc, 0, v153, vcc
	v_pk_fma_f32 v[68:69], v[68:69], v[132:133], v[184:185]
	v_pk_fma_f32 v[66:67], v[66:67], v[130:131], v[182:183]
	global_store_dwordx4 v[74:75], v[70:73], off
	global_store_dwordx4 v[74:75], v[66:69], off offset:16
	s_mov_b64 s[10:11], 0x20200
	v_lshl_add_u64 v[76:77], v[150:151], 0, s[10:11]
	s_mov_b64 s[10:11], 0x40200
	global_load_dwordx4 v[80:83], v[150:151], off offset:512
	global_load_dwordx4 v[70:73], v[154:155], off offset:512
	global_load_dwordx4 v[66:69], v[154:155], off offset:528
	global_load_dwordx4 v[88:91], v[150:151], off offset:528
	global_load_dwordx4 v[112:115], v[156:157], off offset:512
	global_load_dwordx4 v[120:123], v[158:159], off offset:512
	global_load_dwordx4 v[124:127], v[76:77], off offset:16
	v_lshl_add_u64 v[76:77], v[150:151], 0, s[10:11]
	s_mov_b64 s[10:11], 0x60200
	global_load_dwordx4 v[128:131], v[76:77], off offset:16
	global_load_dwordx4 v[132:135], v[160:161], off offset:512
	v_lshl_add_u64 v[76:77], v[150:151], 0, s[10:11]
	global_load_dwordx4 v[154:157], v[76:77], off offset:16
	s_waitcnt vmcnt(0)
	v_pk_fma_f32 v[64:65], v[64:65], v[72:73], v[82:83]
	v_pk_fma_f32 v[62:63], v[62:63], v[70:71], v[80:81]
	v_pk_fma_f32 v[60:61], v[60:61], v[68:69], v[90:91]
	v_pk_fma_f32 v[58:59], v[58:59], v[66:67], v[88:89]
	v_pk_fma_f32 v[52:53], v[52:53], v[72:73], v[122:123]
	v_pk_fma_f32 v[50:51], v[50:51], v[70:71], v[120:121]
	v_pk_fma_f32 v[48:49], v[48:49], v[68:69], v[126:127]
	v_pk_fma_f32 v[46:47], v[46:47], v[66:67], v[124:125]
	v_pk_fma_f32 v[56:57], v[56:57], v[72:73], v[114:115]
	v_pk_fma_f32 v[54:55], v[54:55], v[70:71], v[112:113]
	global_store_dwordx4 v[152:153], v[62:65], off offset:512
	global_store_dwordx4 v[152:153], v[58:61], off offset:528
	global_store_dwordx4 v[118:119], v[54:57], off offset:512
	global_store_dwordx4 v[110:111], v[50:53], off offset:512
	v_pk_fma_f32 v[44:45], v[44:45], v[68:69], v[130:131]
	v_pk_fma_f32 v[42:43], v[42:43], v[66:67], v[128:129]
	v_pk_fma_f32 v[40:41], v[40:41], v[72:73], v[134:135]
	v_pk_fma_f32 v[38:39], v[38:39], v[70:71], v[132:133]
	v_pk_fma_f32 v[36:37], v[36:37], v[68:69], v[156:157]
	v_pk_fma_f32 v[34:35], v[34:35], v[66:67], v[154:155]
	global_store_dwordx4 v[118:119], v[46:49], off offset:528
	global_store_dwordx4 v[110:111], v[42:45], off offset:528
	global_store_dwordx4 v[102:103], v[38:41], off offset:512
	global_store_dwordx4 v[102:103], v[34:37], off offset:528
	s_mov_b64 s[10:11], 0x100200
	v_lshl_add_u64 v[50:51], v[150:151], 0, s[10:11]
	s_mov_b64 s[10:11], 0x120200
	v_lshl_add_u64 v[54:55], v[150:151], 0, s[10:11]
	s_mov_b64 s[10:11], 0x140200
	v_lshl_add_u64 v[58:59], v[150:151], 0, s[10:11]
	s_mov_b64 s[10:11], 0x160200
	global_load_dwordx4 v[34:37], v[98:99], off offset:512
	global_load_dwordx4 v[38:41], v[100:101], off offset:512
	global_load_dwordx4 v[42:45], v[104:105], off offset:512
	global_load_dwordx4 v[46:49], v[106:107], off offset:512
	v_lshl_add_u64 v[62:63], v[150:151], 0, s[10:11]
	global_load_dwordx4 v[50:53], v[50:51], off offset:16
	s_waitcnt vmcnt(0)
	v_pk_fma_f32 v[32:33], v[32:33], v[72:73], v[36:37]
	global_load_dwordx4 v[54:57], v[54:55], off offset:16
	v_pk_fma_f32 v[30:31], v[30:31], v[70:71], v[34:35]
	global_load_dwordx4 v[58:61], v[58:59], off offset:16
	v_pk_fma_f32 v[28:29], v[28:29], v[72:73], v[40:41]
	global_load_dwordx4 v[62:65], v[62:63], off offset:16
	v_pk_fma_f32 v[26:27], v[26:27], v[70:71], v[38:39]
	v_pk_fma_f32 v[24:25], v[24:25], v[72:73], v[44:45]
	v_pk_fma_f32 v[22:23], v[22:23], v[70:71], v[42:43]
	v_pk_fma_f32 v[12:13], v[12:13], v[72:73], v[48:49]
	v_pk_fma_f32 v[10:11], v[10:11], v[70:71], v[46:47]
	v_pk_fma_f32 v[20:21], v[20:21], v[68:69], v[52:53]
	v_pk_fma_f32 v[18:19], v[18:19], v[66:67], v[50:51]
	global_store_dwordx4 v[94:95], v[30:33], off offset:512
	global_store_dwordx4 v[86:87], v[26:29], off offset:512
	global_store_dwordx4 v[78:79], v[22:25], off offset:512
	global_store_dwordx4 v[74:75], v[10:13], off offset:512
	s_waitcnt vmcnt(0)
	v_pk_fma_f32 v[16:17], v[16:17], v[68:69], v[56:57]
	v_pk_fma_f32 v[14:15], v[14:15], v[66:67], v[54:55]
	v_pk_fma_f32 v[8:9], v[8:9], v[68:69], v[60:61]
	v_pk_fma_f32 v[6:7], v[6:7], v[66:67], v[58:59]
	v_pk_fma_f32 v[4:5], v[4:5], v[68:69], v[64:65]
	v_pk_fma_f32 v[2:3], v[2:3], v[66:67], v[62:63]
	global_store_dwordx4 v[94:95], v[18:21], off offset:528
	global_store_dwordx4 v[86:87], v[14:17], off offset:528
	global_store_dwordx4 v[78:79], v[6:9], off offset:528
	global_store_dwordx4 v[74:75], v[2:5], off offset:528
	s_and_b64 vcc, exec, s[0:1]
	s_mov_b32 s40, s6
	s_mov_b32 s28, s4
	s_mov_b64 s[54:55], s[34:35]
	s_mov_b64 s[52:53], s[8:9]
	s_cbranch_vccz .LBB0_501
	s_waitcnt vmcnt(0)
	v_readlane_b32 s28, v250, 12
	v_readlane_b32 s26, v250, 15
	s_cmpk_gt_u32 s12, 0xff
	v_readlane_b32 s29, v250, 13
	v_readlane_b32 s27, v250, 16
	s_mov_b32 s70, 0x800000
	v_readlane_b32 s79, v250, 18
	s_cbranch_scc1 .LBB0_508
	s_barrier
